# EpiRes epilogues: residual-source loads of adjacent 16-column fragments paired into one 16-byte load, un-swapped to fragment lanes with v_permlane16_swap + v_permlane32_swap
# speedup vs baseline: 1.0156x; 1.0049x over previous
; __device__ __forceinline__ u32x2 pk4(f32x4 v) { u32x2 r; r.x = pk2(v.x, v.y); r.y = pk2(v.z, v.w); return r; }
; __device__ __forceinline__ void stats_main(const float* stm, int row, int fq, float& mu, float& rs) {
;     const f32x4* p = (const f32x4*)(stm + (size_t)row * 32 + fq * 8);
;     const f32x4 a = p[0], b = p[1];
;     __device__ __forceinline__ void operator()(const f32x4 (&acc)[2][2][4][2], const pg8::Unit& u, int wr, int wc, int fr, int fq) const {
;     ...
;                 const int row = u.pm * 256 + ai * 128 + wr * 64 + m * 16 + fr;
;                 float mu = 0.f, rs = 1.f; if (ln) stats_main(stm_p, row, fq, mu, rs);
;                 float s1 = 0.f, s2 = 0.f;
; #pragma unroll
;                 for (int bj = 0; bj < 2; ++bj)
; #pragma unroll
;                     for (int n = 0; n < 2; ++n) {
;                         const int col = u.pn * 256 + bj * 128 + wc * 32 + n * 16 + fq * 4;
;                         const u32x2 raw = *(const u32x2*)(src + (size_t)row * DM + col);
;                         f32x4 x = (f32x4){bflo(raw.x), bfhi(raw.x), bflo(raw.y), bfhi(raw.y)};
;                         if (ln) x = (x - mu) * rs * *(const f32x4*)(g + col) + *(const f32x4*)(b + col);
;                         const u32x2 pz = pk4(x * ALPHA + acc[ai][bj][m][n]);
;                         *(u32x2*)(dst + (size_t)row * DM + col) = pz;
.LBB0_1836:
	v_readlane_b32 s80, v251, 34
	v_readlane_b32 s81, v251, 35
	v_readlane_b32 s98, v251, 36
	v_readlane_b32 s99, v251, 37
	v_and_b32_e32 v244, 0xfffffff0, v162
	v_lshl_add_u32 v244, s23, 8, v244
	v_and_b32_e32 v245, 31, v219
	v_add_u32_e32 v244, v244, v245
	v_lshrrev_b32_e32 v245, 5, v219
	v_lshl_add_u32 v244, v245, 7, v244
	v_lshlrev_b32_e32 v244, 2, v244
	global_load_dword v214, v244, s[80:81]
	global_load_dword v215, v244, s[98:99]
	v_lshl_add_u32 v245, s29, 8, v160
	v_lshl_add_u32 v244, s23, 8, v162
	v_lshlrev_b32_e32 v242, 11, v245
	v_lshl_add_u32 v242, v244, 1, v242
	v_lshlrev_b32_e32 v246, 7, v245
	v_mov_b32_e32 v247, 0
	v_lshlrev_b32_e32 v248, 7, v245
	v_mov_b32_e32 v249, 0
	v_add_u32_e32 v246, 0x1000, v246
	v_add_u32_e32 v248, 0x5000, v248
	v_lshl_add_u64 v[246:247], v[246:247], 0, v[134:135]
	v_lshl_add_u64 v[248:249], v[248:249], 0, v[134:135]
	global_load_dwordx4 v[190:193], v[246:247], off offset:-4080
	global_load_dwordx4 v[194:197], v[246:247], off offset:-4096
	v_lshrrev_b32_e32 v245, 4, v219
	v_lshl_add_u32 v245, v245, 3, v242
	global_load_dwordx4 v[198:201], v245, s[46:47]
	v_lshrrev_b32_e32 v245, 4, v219
	v_lshl_add_u32 v245, v245, 3, v242
	global_load_dwordx4 v[202:205], v245, s[46:47] offset:256
	v_lshrrev_b32_e32 v245, 6, v160
	v_lshrrev_b32_e32 v244, 5, v162
	v_lshl_add_u32 v245, v245, 2, v244
	v_lshlrev_b32_e32 v245, 9, v245
	v_and_b32_e32 v244, 12, v162
	v_lshl_add_u32 v244, v244, 2, v245
	v_add_u32_e32 v244, 0x20000, v244
	v_lshl_add_u32 v245, v219, 2, v245
	v_add_u32_e32 v245, 0x20000, v245
	s_waitcnt vmcnt(5)
	ds_write_b32 v245, v214
	s_waitcnt vmcnt(4)
	ds_write_b32 v245, v215 offset:256
	v_add_u32_e32 v243, 0x8000, v242
	global_load_dwordx4 v[206:209], v[246:247], off offset:-2032
	global_load_dwordx4 v[214:217], v[246:247], off offset:-2048
	v_lshrrev_b32_e32 v245, 4, v219
	v_lshl_add_u32 v245, v245, 3, v243
	global_load_dwordx4 v[234:237], v245, s[46:47]
	v_lshrrev_b32_e32 v245, 4, v219
	v_lshl_add_u32 v245, v245, 3, v243
	global_load_dwordx4 v[238:241], v245, s[46:47] offset:256
	s_waitcnt lgkmcnt(0)
	v_and_b32_e32 v140, 64, v219
	v_xor_b32_e32 v3, 16, v219
	v_add_u32_e32 v140, 64, v140
	v_cmp_lt_i32_e32 vcc, v3, v140
	v_lshl_add_u32 v146, s29, 8, v160
	v_ashrrev_i32_e32 v147, 31, v146
	v_cndmask_b32_e32 v3, v219, v3, vcc
	v_lshlrev_b32_e32 v165, 2, v3
	v_xor_b32_e32 v3, 32, v219
	v_cmp_lt_i32_e32 vcc, v3, v140
	v_lshlrev_b64 v[148:149], 7, v[146:147]
	s_nop 0
	v_cndmask_b32_e32 v3, v219, v3, vcc
	v_lshlrev_b32_e32 v164, 2, v3
	v_cndmask_b32_e64 v3, 0, 1, s[96:97]
	v_cmp_ne_u32_e64 s[44:45], 1, v3
	s_andn2_b64 vcc, exec, s[96:97]
	s_cbranch_vccnz .LBB0_1838
	v_lshl_add_u64 v[144:145], v[134:135], 0, v[148:149]
	s_waitcnt vmcnt(6)
	v_mov_b64_e32 v[140:141], v[194:195]
	v_mov_b64_e32 v[142:143], v[196:197]
	s_waitcnt vmcnt(7)
	v_mov_b64_e32 v[150:151], v[190:191]
	v_mov_b64_e32 v[152:153], v[192:193]
	s_waitcnt lgkmcnt(0)
	v_mov_b32_e32 v144, v140
	v_mov_b32_e32 v145, v150
	v_mov_b32_e32 v154, v142
	v_mov_b32_e32 v155, v152
	v_pk_add_f32 v[144:145], v[144:145], v[154:155]
	v_add_f32_e32 v140, v141, v143
	v_add_f32_e32 v142, v151, v153
	v_mov_b32_e32 v141, v144
	v_mov_b32_e32 v143, v145
	v_pk_add_f32 v[140:141], v[140:141], v[142:143]
	ds_bpermute_b32 v143, v165, v141
	ds_bpermute_b32 v142, v165, v140
	s_waitcnt lgkmcnt(0)
	v_pk_add_f32 v[140:141], v[140:141], v[142:143]
	ds_bpermute_b32 v143, v164, v141
	ds_bpermute_b32 v142, v164, v140
	s_waitcnt lgkmcnt(0)
	v_pk_add_f32 v[140:141], v[140:141], v[142:143]
	s_nop 0
	v_pk_mul_f32 v[150:151], v[140:141], s[82:83] op_sel_hi:[1,0]
	s_nop 0
	v_fma_f32 v3, -v151, v151, v150
	v_max_f32_e32 v3, 0, v3
	v_add_f32_e32 v3, 0x3727c5ac, v3
	v_rsq_f32_e32 v152, v3
	s_branch .LBB0_1839

; __device__ __forceinline__ u32x2 pk4(f32x4 v) { u32x2 r; r.x = pk2(v.x, v.y); r.y = pk2(v.z, v.w); return r; }
;     __device__ __forceinline__ void operator()(const f32x4 (&acc)[2][2][4][2], const pg8::Unit& u, int wr, int wc, int fr, int fq) const {
;     ...
;                 for (int bj = 0; bj < 2; ++bj)
; #pragma unroll
;                     for (int n = 0; n < 2; ++n) {
;                         const int col = u.pn * 256 + bj * 128 + wc * 32 + n * 16 + fq * 4;
;                         const u32x2 raw = *(const u32x2*)(src + (size_t)row * DM + col);
;                         f32x4 x = (f32x4){bflo(raw.x), bfhi(raw.x), bflo(raw.y), bfhi(raw.y)};
;                         if (ln) x = (x - mu) * rs * *(const f32x4*)(g + col) + *(const f32x4*)(b + col);
;                         const u32x2 pz = pk4(x * ALPHA + acc[ai][bj][m][n]);
;                         *(u32x2*)(dst + (size_t)row * DM + col) = pz;
.LBB0_1839:
	v_lshl_add_u32 v144, s23, 8, v162
	v_lshlrev_b64 v[140:141], 11, v[146:147]
	v_lshl_add_u64 v[140:141], s[46:47], 0, v[140:141]
	v_ashrrev_i32_e32 v145, 31, v144
	v_lshl_add_u64 v[154:155], v[144:145], 1, v[140:141]
	v_add_u32_e32 v243, 0x10000, v242
	s_waitcnt vmcnt(5)
	v_permlane16_swap_b32_e32 v198, v200
	v_permlane16_swap_b32_e32 v199, v201
	s_nop 0
	v_permlane32_swap_b32_e32 v198, v200
	v_permlane32_swap_b32_e32 v199, v201
	v_mov_b64_e32 v[142:143], v[198:199]
	global_load_dwordx4 v[190:193], v[246:247], off offset:16
	global_load_dwordx4 v[194:197], v[246:247], off
	v_readlane_b32 s56, v251, 22
	v_lshlrev_b64 v[166:167], 2, v[144:145]
	v_readlane_b32 s68, v251, 34
	v_readlane_b32 s69, v251, 35
	v_readlane_b32 s70, v251, 36
	v_readlane_b32 s71, v251, 37
	v_readlane_b32 s24, v251, 0
	v_mov_b32_e32 v153, v152
	s_and_b64 vcc, exec, s[44:45]
	v_lshl_add_u64 v[140:141], s[70:71], 0, v[166:167]
	v_readlane_b32 s25, v251, 1
	v_readlane_b32 s26, v251, 2
	v_readlane_b32 s27, v251, 3
	v_readlane_b32 s57, v251, 23
	v_readlane_b32 s58, v251, 24
	v_readlane_b32 s59, v251, 25
	v_readlane_b32 s60, v251, 26
	v_readlane_b32 s61, v251, 27
	v_readlane_b32 s62, v251, 28
	v_readlane_b32 s63, v251, 29
	v_readlane_b32 s64, v251, 30
	v_readlane_b32 s65, v251, 31
	v_readlane_b32 s66, v251, 32
	v_readlane_b32 s67, v251, 33
	s_waitcnt lgkmcnt(0)
	v_lshlrev_b32_e32 v156, 16, v142
	v_and_b32_e32 v157, 0xffff0000, v142
	v_lshlrev_b32_e32 v158, 16, v143
	v_and_b32_e32 v159, 0xffff0000, v143
	v_lshl_add_u64 v[142:143], s[68:69], 0, v[166:167]
	s_cbranch_vccnz .LBB0_1841
	v_sub_f32_e32 v157, v157, v151
	v_sub_f32_e32 v156, v156, v151
	v_sub_f32_e32 v159, v159, v151
	v_sub_f32_e32 v158, v158, v151
	v_pk_mul_f32 v[166:167], v[152:153], v[156:157]
	v_mov_b32_e32 v156, v152
	v_mov_b32_e32 v157, v152
	v_pk_mul_f32 v[168:169], v[156:157], v[158:159]
	ds_read_b128 v[156:159], v244
	ds_read_b128 v[180:183], v244 offset:256
	s_waitcnt lgkmcnt(0)
	v_pk_fma_f32 v[158:159], v[168:169], v[158:159], v[182:183]
	v_pk_fma_f32 v[156:157], v[166:167], v[156:157], v[180:181]
.LBB0_1841:
	v_readlane_b32 s70, v250, 30
	v_lshlrev_b64 v[166:167], 10, v[146:147]
	v_pk_fma_f32 v[128:129], v[156:157], s[72:73], v[128:129] op_sel_hi:[1,0,1]
	v_readlane_b32 s71, v250, 31
	v_pk_fma_f32 v[158:159], v[158:159], s[72:73], v[130:131] op_sel_hi:[1,0,1]
	v_cvt_pk_bf16_f32 v130, v128, v129
	v_lshl_add_u64 v[128:129], v[166:167], 1, s[70:71]
	v_cvt_pk_bf16_f32 v131, v158, v159
	v_lshl_add_u64 v[128:129], v[144:145], 1, v[128:129]
	global_store_dwordx2 v[128:129], v[130:131], off
	v_mov_b64_e32 v[158:159], v[200:201]
	v_lshrrev_b32_e32 v245, 4, v219
	v_lshl_add_u32 v245, v245, 3, v243
	global_load_dwordx4 v[198:201], v245, s[46:47]
	s_and_b64 vcc, exec, s[44:45]
	s_waitcnt lgkmcnt(0)
	v_lshlrev_b32_e32 v156, 16, v158
	v_and_b32_e32 v157, 0xffff0000, v158
	v_lshlrev_b32_e32 v158, 16, v159
	v_and_b32_e32 v159, 0xffff0000, v159
	s_cbranch_vccnz .LBB0_1843
	v_sub_f32_e32 v157, v157, v151
	v_sub_f32_e32 v156, v156, v151
	v_sub_f32_e32 v159, v159, v151
	v_sub_f32_e32 v158, v158, v151
	v_pk_mul_f32 v[166:167], v[152:153], v[156:157]
	v_mov_b32_e32 v156, v152
	v_mov_b32_e32 v157, v152
	v_pk_mul_f32 v[168:169], v[156:157], v[158:159]
	ds_read_b128 v[156:159], v244 offset:64
	ds_read_b128 v[180:183], v244 offset:320
	s_waitcnt lgkmcnt(0)
	v_pk_fma_f32 v[158:159], v[168:169], v[158:159], v[182:183]
	v_pk_fma_f32 v[156:157], v[166:167], v[156:157], v[180:181]
.LBB0_1843:
	v_pk_fma_f32 v[126:127], v[158:159], s[72:73], v[126:127] op_sel_hi:[1,0,1]
	v_pk_fma_f32 v[124:125], v[156:157], s[72:73], v[124:125] op_sel_hi:[1,0,1]
	s_and_b64 vcc, exec, s[44:45]
	v_cvt_pk_bf16_f32 v124, v124, v125
	v_cvt_pk_bf16_f32 v125, v126, v127
	global_store_dwordx2 v[128:129], v[124:125], off offset:32
	s_waitcnt vmcnt(7)
	v_permlane16_swap_b32_e32 v202, v204
	v_permlane16_swap_b32_e32 v203, v205
	s_nop 0
	v_permlane32_swap_b32_e32 v202, v204
	v_permlane32_swap_b32_e32 v203, v205
	v_mov_b64_e32 v[156:157], v[202:203]
	s_waitcnt lgkmcnt(0)
	v_lshlrev_b32_e32 v126, 16, v156
	v_and_b32_e32 v127, 0xffff0000, v156
	v_lshlrev_b32_e32 v156, 16, v157
	v_and_b32_e32 v157, 0xffff0000, v157
	s_cbranch_vccnz .LBB0_1845
	ds_read_b128 v[180:183], v244 offset:128
	ds_read_b128 v[184:187], v244 offset:384
	v_sub_f32_e32 v157, v157, v151
	v_sub_f32_e32 v156, v156, v151
	v_sub_f32_e32 v127, v127, v151
	v_sub_f32_e32 v126, v126, v151
	v_mov_b32_e32 v158, v152
	v_mov_b32_e32 v159, v152
	v_pk_mul_f32 v[126:127], v[152:153], v[126:127]
	v_pk_mul_f32 v[156:157], v[158:159], v[156:157]
	s_waitcnt lgkmcnt(0)
	v_pk_fma_f32 v[126:127], v[126:127], v[180:181], v[184:185]
	v_pk_fma_f32 v[156:157], v[156:157], v[182:183], v[186:187]
.LBB0_1845:
	s_nop 0
	v_pk_fma_f32 v[122:123], v[156:157], s[72:73], v[122:123] op_sel_hi:[1,0,1]
	v_pk_fma_f32 v[120:121], v[126:127], s[72:73], v[120:121] op_sel_hi:[1,0,1]
	s_and_b64 vcc, exec, s[44:45]
	v_cvt_pk_bf16_f32 v120, v120, v121
	v_cvt_pk_bf16_f32 v121, v122, v123
	global_store_dwordx2 v[128:129], v[120:121], off offset:256
	v_mov_b64_e32 v[126:127], v[204:205]
	v_lshrrev_b32_e32 v245, 4, v219
	v_lshl_add_u32 v245, v245, 3, v243
	global_load_dwordx4 v[202:205], v245, s[46:47] offset:256
	s_waitcnt lgkmcnt(0)
	v_lshlrev_b32_e32 v122, 16, v126
	v_and_b32_e32 v123, 0xffff0000, v126
	v_lshlrev_b32_e32 v126, 16, v127
	v_and_b32_e32 v127, 0xffff0000, v127
	s_cbranch_vccnz .LBB0_1847
	v_sub_f32_e32 v123, v123, v151
	v_sub_f32_e32 v122, v122, v151
	v_sub_f32_e32 v127, v127, v151
	v_sub_f32_e32 v126, v126, v151
	v_pk_mul_f32 v[122:123], v[152:153], v[122:123]
	v_mov_b32_e32 v153, v152
	v_pk_mul_f32 v[126:127], v[152:153], v[126:127]
	ds_read_b128 v[150:153], v244 offset:192
	ds_read_b128 v[154:157], v244 offset:448
	s_waitcnt lgkmcnt(0)
	v_pk_fma_f32 v[126:127], v[126:127], v[152:153], v[156:157]
	v_pk_fma_f32 v[122:123], v[122:123], v[150:151], v[154:155]

; __device__ __forceinline__ void stats_main(const float* stm, int row, int fq, float& mu, float& rs) {
;     const f32x4* p = (const f32x4*)(stm + (size_t)row * 32 + fq * 8);
;     const f32x4 a = p[0], b = p[1];
;     float s1 = (a.x + a.z) + (b.x + b.z), s2 = (a.y + a.w) + (b.y + b.w);
;     s1 += __shfl_xor(s1, 16); s2 += __shfl_xor(s2, 16); s1 += __shfl_xor(s1, 32); s2 += __shfl_xor(s2, 32);
;     mu = s1 * (1.f / DM); rs = __builtin_amdgcn_rsqf(fmaxf(s2 * (1.f / DM) - mu * mu, 0.f) + LN_EPS);
;     __device__ __forceinline__ void operator()(const f32x4 (&acc)[2][2][4][2], const pg8::Unit& u, int wr, int wc, int fr, int fq) const {
;     ...
;                 const int row = u.pm * 256 + ai * 128 + wr * 64 + m * 16 + fr;
;                 float mu = 0.f, rs = 1.f; if (ln) stats_main(stm_p, row, fq, mu, rs);
.LBB0_1849:
	s_or_b64 exec, exec, s[0:1]
	v_or_b32_e32 v124, 16, v146
	v_ashrrev_i32_e32 v125, 31, v124
	s_and_b64 vcc, exec, s[44:45]
	v_lshlrev_b64 v[116:117], 7, v[124:125]
	s_cbranch_vccnz .LBB0_1851
	v_lshl_add_u64 v[122:123], v[134:135], 0, v[116:117]
	s_waitcnt lgkmcnt(0)
	s_waitcnt vmcnt(6)
	v_mov_b64_e32 v[118:119], v[214:215]
	v_mov_b64_e32 v[120:121], v[216:217]
	s_waitcnt vmcnt(7)
	v_mov_b64_e32 v[126:127], v[206:207]
	v_mov_b64_e32 v[128:129], v[208:209]
	s_waitcnt lgkmcnt(0)
	v_mov_b32_e32 v122, v118
	s_waitcnt lgkmcnt(0)
	v_mov_b32_e32 v123, v126
	v_mov_b32_e32 v130, v120
	v_mov_b32_e32 v131, v128
	v_pk_add_f32 v[122:123], v[122:123], v[130:131]
	v_add_f32_e32 v118, v119, v121
	v_add_f32_e32 v120, v127, v129
	v_mov_b32_e32 v119, v122
	v_mov_b32_e32 v121, v123
	v_pk_add_f32 v[118:119], v[118:119], v[120:121]
	ds_bpermute_b32 v121, v165, v119
	ds_bpermute_b32 v120, v165, v118
	s_waitcnt lgkmcnt(0)
	v_pk_add_f32 v[118:119], v[118:119], v[120:121]
	ds_bpermute_b32 v121, v164, v119
	ds_bpermute_b32 v120, v164, v118
	s_waitcnt lgkmcnt(0)
	v_pk_add_f32 v[118:119], v[118:119], v[120:121]
	s_nop 0
	v_pk_mul_f32 v[118:119], v[118:119], s[82:83] op_sel_hi:[1,0]
	s_nop 0
	v_fma_f32 v3, -v119, v119, v118
	v_max_f32_e32 v3, 0, v3
	v_add_f32_e32 v3, 0x3727c5ac, v3
	v_rsq_f32_e32 v120, v3
	s_branch .LBB0_1852

; __device__ __forceinline__ u32x2 pk4(f32x4 v) { u32x2 r; r.x = pk2(v.x, v.y); r.y = pk2(v.z, v.w); return r; }
;     __device__ __forceinline__ void operator()(const f32x4 (&acc)[2][2][4][2], const pg8::Unit& u, int wr, int wc, int fr, int fq) const {
;     ...
;                 for (int bj = 0; bj < 2; ++bj)
; #pragma unroll
;                     for (int n = 0; n < 2; ++n) {
;                         const int col = u.pn * 256 + bj * 128 + wc * 32 + n * 16 + fq * 4;
;                         const u32x2 raw = *(const u32x2*)(src + (size_t)row * DM + col);
;                         f32x4 x = (f32x4){bflo(raw.x), bfhi(raw.x), bflo(raw.y), bfhi(raw.y)};
;                         if (ln) x = (x - mu) * rs * *(const f32x4*)(g + col) + *(const f32x4*)(b + col);
;                         const u32x2 pz = pk4(x * ALPHA + acc[ai][bj][m][n]);
;                         *(u32x2*)(dst + (size_t)row * DM + col) = pz;
.LBB0_1852:
	v_lshlrev_b64 v[122:123], 11, v[124:125]
	v_lshl_add_u64 v[122:123], s[46:47], 0, v[122:123]
	v_lshl_add_u64 v[122:123], v[144:145], 1, v[122:123]
	v_add_u32_e32 v243, 0x18000, v242
	s_waitcnt vmcnt(5)
	v_permlane16_swap_b32_e32 v234, v236
	v_permlane16_swap_b32_e32 v235, v237
	s_nop 0
	v_permlane32_swap_b32_e32 v234, v236
	v_permlane32_swap_b32_e32 v235, v237
	v_mov_b64_e32 v[128:129], v[234:235]
	global_load_dwordx4 v[206:209], v[246:247], off offset:2064
	global_load_dwordx4 v[214:217], v[246:247], off offset:2048
	v_mov_b32_e32 v121, v120
	s_and_b64 vcc, exec, s[44:45]
	s_waitcnt lgkmcnt(0)
	v_lshlrev_b32_e32 v126, 16, v128
	v_and_b32_e32 v127, 0xffff0000, v128
	v_lshlrev_b32_e32 v128, 16, v129
	v_and_b32_e32 v129, 0xffff0000, v129
	s_cbranch_vccnz .LBB0_1854
	v_sub_f32_e32 v127, v127, v119
	v_sub_f32_e32 v126, v126, v119
	v_sub_f32_e32 v129, v129, v119
	v_sub_f32_e32 v128, v128, v119
	v_pk_mul_f32 v[130:131], v[120:121], v[126:127]
	v_mov_b32_e32 v126, v120
	v_mov_b32_e32 v127, v120
	v_pk_mul_f32 v[152:153], v[126:127], v[128:129]
	ds_read_b128 v[126:129], v244
	ds_read_b128 v[148:151], v244 offset:256
	s_waitcnt lgkmcnt(0)
	v_pk_fma_f32 v[128:129], v[152:153], v[128:129], v[150:151]
	v_pk_fma_f32 v[126:127], v[130:131], v[126:127], v[148:149]
.LBB0_1854:
	v_lshlrev_b64 v[124:125], 10, v[124:125]
	v_pk_fma_f32 v[112:113], v[126:127], s[72:73], v[112:113] op_sel_hi:[1,0,1]
	v_pk_fma_f32 v[128:129], v[128:129], s[72:73], v[114:115] op_sel_hi:[1,0,1]
	v_cvt_pk_bf16_f32 v114, v112, v113
	v_lshl_add_u64 v[112:113], v[124:125], 1, s[70:71]
	v_cvt_pk_bf16_f32 v115, v128, v129
	v_lshl_add_u64 v[112:113], v[144:145], 1, v[112:113]
	global_store_dwordx2 v[112:113], v[114:115], off
	v_mov_b64_e32 v[126:127], v[236:237]
	v_lshrrev_b32_e32 v245, 4, v219
	v_lshl_add_u32 v245, v245, 3, v243
	global_load_dwordx4 v[234:237], v245, s[46:47]
	s_and_b64 vcc, exec, s[44:45]
	s_waitcnt lgkmcnt(0)
	v_lshlrev_b32_e32 v124, 16, v126
	v_and_b32_e32 v125, 0xffff0000, v126
	v_lshlrev_b32_e32 v126, 16, v127
	v_and_b32_e32 v127, 0xffff0000, v127
	s_cbranch_vccnz .LBB0_1856
	v_sub_f32_e32 v125, v125, v119
	v_sub_f32_e32 v124, v124, v119
	v_sub_f32_e32 v127, v127, v119
	v_sub_f32_e32 v126, v126, v119
	v_pk_mul_f32 v[148:149], v[120:121], v[124:125]
	v_mov_b32_e32 v124, v120
	v_mov_b32_e32 v125, v120
	v_pk_mul_f32 v[150:151], v[124:125], v[126:127]
	ds_read_b128 v[124:127], v244 offset:64
	ds_read_b128 v[128:131], v244 offset:320
	s_waitcnt lgkmcnt(0)
	v_pk_fma_f32 v[126:127], v[150:151], v[126:127], v[130:131]
	v_pk_fma_f32 v[124:125], v[148:149], v[124:125], v[128:129]
.LBB0_1856:
	v_pk_fma_f32 v[110:111], v[126:127], s[72:73], v[110:111] op_sel_hi:[1,0,1]
	v_pk_fma_f32 v[108:109], v[124:125], s[72:73], v[108:109] op_sel_hi:[1,0,1]
	s_and_b64 vcc, exec, s[44:45]
	v_cvt_pk_bf16_f32 v108, v108, v109
	v_cvt_pk_bf16_f32 v109, v110, v111
	global_store_dwordx2 v[112:113], v[108:109], off offset:32
	s_waitcnt vmcnt(7)
	v_permlane16_swap_b32_e32 v238, v240
	v_permlane16_swap_b32_e32 v239, v241
	s_nop 0
	v_permlane32_swap_b32_e32 v238, v240
	v_permlane32_swap_b32_e32 v239, v241
	v_mov_b64_e32 v[124:125], v[238:239]
	s_waitcnt lgkmcnt(0)
	v_lshlrev_b32_e32 v110, 16, v124
	v_and_b32_e32 v111, 0xffff0000, v124
	v_lshlrev_b32_e32 v124, 16, v125
	v_and_b32_e32 v125, 0xffff0000, v125
	s_cbranch_vccnz .LBB0_1858
	v_sub_f32_e32 v125, v125, v119
	v_sub_f32_e32 v124, v124, v119
	v_mov_b32_e32 v126, v120
	v_mov_b32_e32 v127, v120
	v_pk_mul_f32 v[124:125], v[126:127], v[124:125]
	ds_read_b128 v[126:129], v244 offset:128
	ds_read_b128 v[148:151], v244 offset:384
	v_sub_f32_e32 v111, v111, v119
	v_sub_f32_e32 v110, v110, v119
	v_pk_mul_f32 v[110:111], v[120:121], v[110:111]
	s_waitcnt lgkmcnt(0)
	v_pk_fma_f32 v[124:125], v[124:125], v[128:129], v[150:151]
	v_pk_fma_f32 v[110:111], v[110:111], v[126:127], v[148:149]
.LBB0_1858:
	v_pk_fma_f32 v[106:107], v[124:125], s[72:73], v[106:107] op_sel_hi:[1,0,1]
	v_pk_fma_f32 v[104:105], v[110:111], s[72:73], v[104:105] op_sel_hi:[1,0,1]
	s_and_b64 vcc, exec, s[44:45]
	v_cvt_pk_bf16_f32 v104, v104, v105
	v_cvt_pk_bf16_f32 v105, v106, v107
	v_mov_b64_e32 v[148:149], v[104:105]
	v_mov_b64_e32 v[110:111], v[240:241]
	v_lshrrev_b32_e32 v245, 4, v219
	v_lshl_add_u32 v245, v245, 3, v243
	global_load_dwordx4 v[238:241], v245, s[46:47] offset:256
	s_waitcnt lgkmcnt(0)
	v_lshlrev_b32_e32 v106, 16, v110
	v_and_b32_e32 v107, 0xffff0000, v110
	v_lshlrev_b32_e32 v110, 16, v111
	v_and_b32_e32 v111, 0xffff0000, v111
	s_cbranch_vccnz .LBB0_1860
	v_sub_f32_e32 v107, v107, v119
	v_sub_f32_e32 v106, v106, v119
	v_sub_f32_e32 v111, v111, v119
	v_sub_f32_e32 v110, v110, v119
	v_pk_mul_f32 v[106:107], v[120:121], v[106:107]
	v_mov_b32_e32 v121, v120
	v_pk_mul_f32 v[110:111], v[120:121], v[110:111]
	ds_read_b128 v[118:121], v244 offset:192
	ds_read_b128 v[122:125], v244 offset:448
	s_waitcnt lgkmcnt(0)
	v_pk_fma_f32 v[110:111], v[110:111], v[120:121], v[124:125]
	v_pk_fma_f32 v[106:107], v[106:107], v[118:119], v[122:123]

; __device__ __forceinline__ void stats_main(const float* stm, int row, int fq, float& mu, float& rs) {
;     const f32x4* p = (const f32x4*)(stm + (size_t)row * 32 + fq * 8);
;     const f32x4 a = p[0], b = p[1];
;     float s1 = (a.x + a.z) + (b.x + b.z), s2 = (a.y + a.w) + (b.y + b.w);
;     s1 += __shfl_xor(s1, 16); s2 += __shfl_xor(s2, 16); s1 += __shfl_xor(s1, 32); s2 += __shfl_xor(s2, 32);
;     mu = s1 * (1.f / DM); rs = __builtin_amdgcn_rsqf(fmaxf(s2 * (1.f / DM) - mu * mu, 0.f) + LN_EPS);
;     __device__ __forceinline__ void operator()(const f32x4 (&acc)[2][2][4][2], const pg8::Unit& u, int wr, int wc, int fr, int fq) const {
;     ...
;                 const int row = u.pm * 256 + ai * 128 + wr * 64 + m * 16 + fr;
;                 float mu = 0.f, rs = 1.f; if (ln) stats_main(stm_p, row, fq, mu, rs);
.LBB0_1862:
	s_or_b64 exec, exec, s[0:1]
	v_or_b32_e32 v108, 32, v146
	v_ashrrev_i32_e32 v109, 31, v108
	s_and_b64 vcc, exec, s[44:45]
	v_lshlrev_b64 v[100:101], 7, v[108:109]
	s_cbranch_vccnz .LBB0_1864
	v_lshl_add_u64 v[106:107], v[134:135], 0, v[100:101]
	s_waitcnt lgkmcnt(0)
	s_waitcnt vmcnt(6)
	v_mov_b64_e32 v[102:103], v[194:195]
	v_mov_b64_e32 v[104:105], v[196:197]
	s_waitcnt vmcnt(7)
	v_mov_b64_e32 v[110:111], v[190:191]
	v_mov_b64_e32 v[112:113], v[192:193]
	s_waitcnt lgkmcnt(0)
	v_mov_b32_e32 v106, v102
	s_waitcnt lgkmcnt(0)
	v_mov_b32_e32 v107, v110
	v_mov_b32_e32 v114, v104
	v_mov_b32_e32 v115, v112
	v_pk_add_f32 v[106:107], v[106:107], v[114:115]
	v_add_f32_e32 v102, v103, v105
	v_add_f32_e32 v104, v111, v113
	v_mov_b32_e32 v103, v106
	v_mov_b32_e32 v105, v107
	v_pk_add_f32 v[102:103], v[102:103], v[104:105]
	ds_bpermute_b32 v105, v165, v103
	ds_bpermute_b32 v104, v165, v102
	s_waitcnt lgkmcnt(0)
	v_pk_add_f32 v[102:103], v[102:103], v[104:105]
	ds_bpermute_b32 v105, v164, v103
	ds_bpermute_b32 v104, v164, v102
	s_waitcnt lgkmcnt(0)
	v_pk_add_f32 v[102:103], v[102:103], v[104:105]
	s_nop 0
	v_pk_mul_f32 v[102:103], v[102:103], s[82:83] op_sel_hi:[1,0]
	s_nop 0
	v_fma_f32 v3, -v103, v103, v102
	v_max_f32_e32 v3, 0, v3
	v_add_f32_e32 v3, 0x3727c5ac, v3
	v_rsq_f32_e32 v104, v3
	s_branch .LBB0_1865

; __device__ __forceinline__ u32x2 pk4(f32x4 v) { u32x2 r; r.x = pk2(v.x, v.y); r.y = pk2(v.z, v.w); return r; }
;     __device__ __forceinline__ void operator()(const f32x4 (&acc)[2][2][4][2], const pg8::Unit& u, int wr, int wc, int fr, int fq) const {
;     ...
;                 for (int bj = 0; bj < 2; ++bj)
; #pragma unroll
;                     for (int n = 0; n < 2; ++n) {
;                         const int col = u.pn * 256 + bj * 128 + wc * 32 + n * 16 + fq * 4;
;                         const u32x2 raw = *(const u32x2*)(src + (size_t)row * DM + col);
;                         f32x4 x = (f32x4){bflo(raw.x), bfhi(raw.x), bflo(raw.y), bfhi(raw.y)};
;                         if (ln) x = (x - mu) * rs * *(const f32x4*)(g + col) + *(const f32x4*)(b + col);
;                         const u32x2 pz = pk4(x * ALPHA + acc[ai][bj][m][n]);
;                         *(u32x2*)(dst + (size_t)row * DM + col) = pz;
.LBB0_1865:
	v_lshlrev_b64 v[106:107], 11, v[108:109]
	v_lshl_add_u64 v[106:107], s[46:47], 0, v[106:107]
	v_lshl_add_u64 v[106:107], v[144:145], 1, v[106:107]
	v_add_u32_e32 v243, 0x40000, v242
	s_waitcnt vmcnt(5)
	v_permlane16_swap_b32_e32 v198, v200
	v_permlane16_swap_b32_e32 v199, v201
	s_nop 0
	v_permlane32_swap_b32_e32 v198, v200
	v_permlane32_swap_b32_e32 v199, v201
	v_mov_b64_e32 v[112:113], v[198:199]
	global_load_dwordx4 v[190:193], v[248:249], off offset:-4080
	global_load_dwordx4 v[194:197], v[248:249], off offset:-4096
	v_mov_b32_e32 v105, v104
	s_and_b64 vcc, exec, s[44:45]
	s_waitcnt lgkmcnt(0)
	v_lshlrev_b32_e32 v110, 16, v112
	v_and_b32_e32 v111, 0xffff0000, v112
	v_lshlrev_b32_e32 v112, 16, v113
	v_and_b32_e32 v113, 0xffff0000, v113
	s_cbranch_vccnz .LBB0_1867
	v_sub_f32_e32 v111, v111, v103
	v_sub_f32_e32 v110, v110, v103
	v_sub_f32_e32 v113, v113, v103
	v_sub_f32_e32 v112, v112, v103
	v_pk_mul_f32 v[118:119], v[104:105], v[110:111]
	v_mov_b32_e32 v110, v104
	v_mov_b32_e32 v111, v104
	v_pk_mul_f32 v[120:121], v[110:111], v[112:113]
	ds_read_b128 v[110:113], v244
	ds_read_b128 v[114:117], v244 offset:256
	s_waitcnt lgkmcnt(0)
	v_pk_fma_f32 v[112:113], v[120:121], v[112:113], v[116:117]
	v_pk_fma_f32 v[110:111], v[118:119], v[110:111], v[114:115]
.LBB0_1867:
	v_lshlrev_b64 v[108:109], 10, v[108:109]
	v_pk_fma_f32 v[96:97], v[110:111], s[72:73], v[96:97] op_sel_hi:[1,0,1]
	v_pk_fma_f32 v[112:113], v[112:113], s[72:73], v[98:99] op_sel_hi:[1,0,1]
	v_cvt_pk_bf16_f32 v98, v96, v97
	v_lshl_add_u64 v[96:97], v[108:109], 1, s[70:71]
	v_cvt_pk_bf16_f32 v99, v112, v113
	v_lshl_add_u64 v[96:97], v[144:145], 1, v[96:97]
	v_mov_b64_e32 v[148:149], v[98:99]
	v_mov_b64_e32 v[110:111], v[200:201]
	v_lshrrev_b32_e32 v245, 4, v219
	v_lshl_add_u32 v245, v245, 3, v243
	global_load_dwordx4 v[198:201], v245, s[46:47]
	s_and_b64 vcc, exec, s[44:45]
	s_waitcnt lgkmcnt(0)
	v_lshlrev_b32_e32 v108, 16, v110
	v_and_b32_e32 v109, 0xffff0000, v110
	v_lshlrev_b32_e32 v110, 16, v111
	v_and_b32_e32 v111, 0xffff0000, v111
	s_cbranch_vccnz .LBB0_1869
	v_sub_f32_e32 v109, v109, v103
	v_sub_f32_e32 v108, v108, v103
	v_sub_f32_e32 v111, v111, v103
	v_sub_f32_e32 v110, v110, v103
	v_pk_mul_f32 v[116:117], v[104:105], v[108:109]
	v_mov_b32_e32 v108, v104
	v_mov_b32_e32 v109, v104
	v_pk_mul_f32 v[118:119], v[108:109], v[110:111]
	ds_read_b128 v[108:111], v244 offset:64
	ds_read_b128 v[112:115], v244 offset:320
	s_waitcnt lgkmcnt(0)
	v_pk_fma_f32 v[110:111], v[118:119], v[110:111], v[114:115]
	v_pk_fma_f32 v[108:109], v[116:117], v[108:109], v[112:113]
.LBB0_1869:
	v_pk_fma_f32 v[94:95], v[110:111], s[72:73], v[94:95] op_sel_hi:[1,0,1]
	v_pk_fma_f32 v[92:93], v[108:109], s[72:73], v[92:93] op_sel_hi:[1,0,1]
	s_and_b64 vcc, exec, s[44:45]
	v_cvt_pk_bf16_f32 v92, v92, v93
	v_cvt_pk_bf16_f32 v93, v94, v95
	v_mov_b64_e32 v[150:151], v[92:93]
	v_lshrrev_b32_e32 v152, 4, v219
	v_lshlrev_b32_e32 v152, 3, v152
	v_mov_b32_e32 v153, v2
	v_permlane32_swap_b32_e32 v148, v150
	v_permlane32_swap_b32_e32 v149, v151
	v_lshl_add_u64 v[152:153], v[152:153], 0, v[96:97]
	s_nop 0
	v_permlane16_swap_b32_e32 v148, v150
	v_permlane16_swap_b32_e32 v149, v151
	global_store_dwordx4 v[152:153], v[148:151], off sc0
	s_waitcnt vmcnt(7)
	v_permlane16_swap_b32_e32 v202, v204
	v_permlane16_swap_b32_e32 v203, v205
	s_nop 0
	v_permlane32_swap_b32_e32 v202, v204
	v_permlane32_swap_b32_e32 v203, v205
	v_mov_b64_e32 v[108:109], v[202:203]
	s_waitcnt lgkmcnt(0)
	v_lshlrev_b32_e32 v94, 16, v108
	v_and_b32_e32 v95, 0xffff0000, v108
	v_lshlrev_b32_e32 v108, 16, v109
	v_and_b32_e32 v109, 0xffff0000, v109
	s_cbranch_vccnz .LBB0_1871
	v_sub_f32_e32 v109, v109, v103
	v_sub_f32_e32 v108, v108, v103
	v_mov_b32_e32 v110, v104
	v_mov_b32_e32 v111, v104
	v_pk_mul_f32 v[108:109], v[110:111], v[108:109]
	ds_read_b128 v[110:113], v244 offset:128
	ds_read_b128 v[114:117], v244 offset:384
	v_sub_f32_e32 v95, v95, v103
	v_sub_f32_e32 v94, v94, v103
	v_pk_mul_f32 v[94:95], v[104:105], v[94:95]
	s_waitcnt lgkmcnt(0)
	v_pk_fma_f32 v[108:109], v[108:109], v[112:113], v[116:117]
	v_pk_fma_f32 v[94:95], v[94:95], v[110:111], v[114:115]
.LBB0_1871:
	v_pk_fma_f32 v[90:91], v[108:109], s[72:73], v[90:91] op_sel_hi:[1,0,1]
	v_pk_fma_f32 v[88:89], v[94:95], s[72:73], v[88:89] op_sel_hi:[1,0,1]
	s_and_b64 vcc, exec, s[44:45]
	v_cvt_pk_bf16_f32 v88, v88, v89
	v_cvt_pk_bf16_f32 v89, v90, v91
	v_mov_b64_e32 v[148:149], v[88:89]
	v_mov_b64_e32 v[94:95], v[204:205]
	v_lshrrev_b32_e32 v245, 4, v219
	v_lshl_add_u32 v245, v245, 3, v243
	global_load_dwordx4 v[202:205], v245, s[46:47] offset:256
	s_waitcnt lgkmcnt(0)
	v_lshlrev_b32_e32 v90, 16, v94
	v_and_b32_e32 v91, 0xffff0000, v94
	v_lshlrev_b32_e32 v94, 16, v95
	v_and_b32_e32 v95, 0xffff0000, v95
	s_cbranch_vccnz .LBB0_1873
	v_sub_f32_e32 v91, v91, v103
	v_sub_f32_e32 v90, v90, v103
	v_sub_f32_e32 v95, v95, v103
	v_sub_f32_e32 v94, v94, v103
	v_pk_mul_f32 v[90:91], v[104:105], v[90:91]
	v_mov_b32_e32 v105, v104
	v_pk_mul_f32 v[94:95], v[104:105], v[94:95]
	ds_read_b128 v[102:105], v244 offset:192
	ds_read_b128 v[106:109], v244 offset:448
	s_waitcnt lgkmcnt(0)
	v_pk_fma_f32 v[94:95], v[94:95], v[104:105], v[108:109]
	v_pk_fma_f32 v[90:91], v[90:91], v[102:103], v[106:107]

; __device__ __forceinline__ void stats_main(const float* stm, int row, int fq, float& mu, float& rs) {
;     const f32x4* p = (const f32x4*)(stm + (size_t)row * 32 + fq * 8);
;     const f32x4 a = p[0], b = p[1];
;     float s1 = (a.x + a.z) + (b.x + b.z), s2 = (a.y + a.w) + (b.y + b.w);
;     s1 += __shfl_xor(s1, 16); s2 += __shfl_xor(s2, 16); s1 += __shfl_xor(s1, 32); s2 += __shfl_xor(s2, 32);
;     mu = s1 * (1.f / DM); rs = __builtin_amdgcn_rsqf(fmaxf(s2 * (1.f / DM) - mu * mu, 0.f) + LN_EPS);
;     __device__ __forceinline__ void operator()(const f32x4 (&acc)[2][2][4][2], const pg8::Unit& u, int wr, int wc, int fr, int fq) const {
;     ...
;                 const int row = u.pm * 256 + ai * 128 + wr * 64 + m * 16 + fr;
;                 float mu = 0.f, rs = 1.f; if (ln) stats_main(stm_p, row, fq, mu, rs);
.LBB0_1875:
	s_or_b64 exec, exec, s[0:1]
	v_or_b32_e32 v92, 48, v146
	v_ashrrev_i32_e32 v93, 31, v92
	s_and_b64 vcc, exec, s[44:45]
	v_lshlrev_b64 v[84:85], 7, v[92:93]
	s_cbranch_vccnz .LBB0_1877
	v_lshl_add_u64 v[90:91], v[134:135], 0, v[84:85]
	s_waitcnt lgkmcnt(0)
	s_waitcnt vmcnt(6)
	v_mov_b64_e32 v[86:87], v[214:215]
	v_mov_b64_e32 v[88:89], v[216:217]
	s_waitcnt vmcnt(7)
	v_mov_b64_e32 v[94:95], v[206:207]
	v_mov_b64_e32 v[96:97], v[208:209]
	s_waitcnt lgkmcnt(0)
	v_mov_b32_e32 v90, v86
	s_waitcnt lgkmcnt(0)
	v_mov_b32_e32 v91, v94
	v_mov_b32_e32 v98, v88
	v_mov_b32_e32 v99, v96
	v_pk_add_f32 v[90:91], v[90:91], v[98:99]
	v_add_f32_e32 v86, v87, v89
	v_add_f32_e32 v88, v95, v97
	v_mov_b32_e32 v87, v90
	v_mov_b32_e32 v89, v91
	v_pk_add_f32 v[86:87], v[86:87], v[88:89]
	ds_bpermute_b32 v89, v165, v87
	ds_bpermute_b32 v88, v165, v86
	s_waitcnt lgkmcnt(0)
	v_pk_add_f32 v[86:87], v[86:87], v[88:89]
	ds_bpermute_b32 v89, v164, v87
	ds_bpermute_b32 v88, v164, v86
	s_waitcnt lgkmcnt(0)
	v_pk_add_f32 v[86:87], v[86:87], v[88:89]
	s_nop 0
	v_pk_mul_f32 v[86:87], v[86:87], s[82:83] op_sel_hi:[1,0]
	s_nop 0
	v_fma_f32 v3, -v87, v87, v86
	v_max_f32_e32 v3, 0, v3
	v_add_f32_e32 v3, 0x3727c5ac, v3
	v_rsq_f32_e32 v88, v3
	s_branch .LBB0_1878

; __device__ __forceinline__ u32x2 pk4(f32x4 v) { u32x2 r; r.x = pk2(v.x, v.y); r.y = pk2(v.z, v.w); return r; }
;     __device__ __forceinline__ void operator()(const f32x4 (&acc)[2][2][4][2], const pg8::Unit& u, int wr, int wc, int fr, int fq) const {
;     ...
;                 for (int bj = 0; bj < 2; ++bj)
; #pragma unroll
;                     for (int n = 0; n < 2; ++n) {
;                         const int col = u.pn * 256 + bj * 128 + wc * 32 + n * 16 + fq * 4;
;                         const u32x2 raw = *(const u32x2*)(src + (size_t)row * DM + col);
;                         f32x4 x = (f32x4){bflo(raw.x), bfhi(raw.x), bflo(raw.y), bfhi(raw.y)};
;                         if (ln) x = (x - mu) * rs * *(const f32x4*)(g + col) + *(const f32x4*)(b + col);
;                         const u32x2 pz = pk4(x * ALPHA + acc[ai][bj][m][n]);
;                         *(u32x2*)(dst + (size_t)row * DM + col) = pz;
.LBB0_1878:
	v_lshlrev_b64 v[90:91], 11, v[92:93]
	v_lshl_add_u64 v[90:91], s[46:47], 0, v[90:91]
	v_lshl_add_u64 v[90:91], v[144:145], 1, v[90:91]
	v_add_u32_e32 v243, 0x48000, v242
	s_waitcnt vmcnt(5)
	v_permlane16_swap_b32_e32 v234, v236
	v_permlane16_swap_b32_e32 v235, v237
	s_nop 0
	v_permlane32_swap_b32_e32 v234, v236
	v_permlane32_swap_b32_e32 v235, v237
	v_mov_b64_e32 v[96:97], v[234:235]
	global_load_dwordx4 v[206:209], v[248:249], off offset:-2032
	global_load_dwordx4 v[214:217], v[248:249], off offset:-2048
	v_mov_b32_e32 v89, v88
	s_and_b64 vcc, exec, s[44:45]
	s_waitcnt lgkmcnt(0)
	v_lshlrev_b32_e32 v94, 16, v96
	v_and_b32_e32 v95, 0xffff0000, v96
	v_lshlrev_b32_e32 v96, 16, v97
	v_and_b32_e32 v97, 0xffff0000, v97
	s_cbranch_vccnz .LBB0_1880
	v_sub_f32_e32 v95, v95, v87
	v_sub_f32_e32 v94, v94, v87
	v_sub_f32_e32 v97, v97, v87
	v_sub_f32_e32 v96, v96, v87
	v_pk_mul_f32 v[102:103], v[88:89], v[94:95]
	v_mov_b32_e32 v94, v88
	v_mov_b32_e32 v95, v88
	v_pk_mul_f32 v[104:105], v[94:95], v[96:97]
	ds_read_b128 v[94:97], v244
	ds_read_b128 v[98:101], v244 offset:256
	s_waitcnt lgkmcnt(0)
	v_pk_fma_f32 v[96:97], v[104:105], v[96:97], v[100:101]
	v_pk_fma_f32 v[94:95], v[102:103], v[94:95], v[98:99]
.LBB0_1880:
	v_lshlrev_b64 v[92:93], 10, v[92:93]
	v_pk_fma_f32 v[80:81], v[94:95], s[72:73], v[80:81] op_sel_hi:[1,0,1]
	v_pk_fma_f32 v[96:97], v[96:97], s[72:73], v[82:83] op_sel_hi:[1,0,1]
	v_cvt_pk_bf16_f32 v82, v80, v81
	v_lshl_add_u64 v[80:81], v[92:93], 1, s[70:71]
	v_cvt_pk_bf16_f32 v83, v96, v97
	v_lshl_add_u64 v[80:81], v[144:145], 1, v[80:81]
	v_mov_b64_e32 v[148:149], v[82:83]
	v_mov_b64_e32 v[94:95], v[236:237]
	v_lshrrev_b32_e32 v245, 4, v219
	v_lshl_add_u32 v245, v245, 3, v243
	global_load_dwordx4 v[234:237], v245, s[46:47]
	s_and_b64 vcc, exec, s[44:45]
	s_waitcnt lgkmcnt(0)
	v_lshlrev_b32_e32 v92, 16, v94
	v_and_b32_e32 v93, 0xffff0000, v94
	v_lshlrev_b32_e32 v94, 16, v95
	v_and_b32_e32 v95, 0xffff0000, v95
	s_cbranch_vccnz .LBB0_1882
	v_sub_f32_e32 v93, v93, v87
	v_sub_f32_e32 v92, v92, v87
	v_sub_f32_e32 v95, v95, v87
	v_sub_f32_e32 v94, v94, v87
	v_pk_mul_f32 v[100:101], v[88:89], v[92:93]
	v_mov_b32_e32 v92, v88
	v_mov_b32_e32 v93, v88
	v_pk_mul_f32 v[102:103], v[92:93], v[94:95]
	ds_read_b128 v[92:95], v244 offset:64
	ds_read_b128 v[96:99], v244 offset:320
	s_waitcnt lgkmcnt(0)
	v_pk_fma_f32 v[94:95], v[102:103], v[94:95], v[98:99]
	v_pk_fma_f32 v[92:93], v[100:101], v[92:93], v[96:97]
.LBB0_1882:
	v_pk_fma_f32 v[78:79], v[94:95], s[72:73], v[78:79] op_sel_hi:[1,0,1]
	v_pk_fma_f32 v[76:77], v[92:93], s[72:73], v[76:77] op_sel_hi:[1,0,1]
	s_and_b64 vcc, exec, s[44:45]
	v_cvt_pk_bf16_f32 v76, v76, v77
	v_cvt_pk_bf16_f32 v77, v78, v79
	v_mov_b64_e32 v[150:151], v[76:77]
	v_lshrrev_b32_e32 v152, 4, v219
	v_lshlrev_b32_e32 v152, 3, v152
	v_mov_b32_e32 v153, v2
	v_permlane32_swap_b32_e32 v148, v150
	v_permlane32_swap_b32_e32 v149, v151
	v_lshl_add_u64 v[152:153], v[152:153], 0, v[80:81]
	s_nop 0
	v_permlane16_swap_b32_e32 v148, v150
	v_permlane16_swap_b32_e32 v149, v151
	global_store_dwordx4 v[152:153], v[148:151], off sc0
	s_waitcnt vmcnt(7)
	v_permlane16_swap_b32_e32 v238, v240
	v_permlane16_swap_b32_e32 v239, v241
	s_nop 0
	v_permlane32_swap_b32_e32 v238, v240
	v_permlane32_swap_b32_e32 v239, v241
	v_mov_b64_e32 v[92:93], v[238:239]
	s_waitcnt lgkmcnt(0)
	v_lshlrev_b32_e32 v78, 16, v92
	v_and_b32_e32 v79, 0xffff0000, v92
	v_lshlrev_b32_e32 v92, 16, v93
	v_and_b32_e32 v93, 0xffff0000, v93
	s_cbranch_vccnz .LBB0_1884
	v_sub_f32_e32 v93, v93, v87
	v_sub_f32_e32 v92, v92, v87
	v_mov_b32_e32 v94, v88
	v_mov_b32_e32 v95, v88
	v_pk_mul_f32 v[92:93], v[94:95], v[92:93]
	ds_read_b128 v[94:97], v244 offset:128
	ds_read_b128 v[98:101], v244 offset:384
	v_sub_f32_e32 v79, v79, v87
	v_sub_f32_e32 v78, v78, v87
	v_pk_mul_f32 v[78:79], v[88:89], v[78:79]
	s_waitcnt lgkmcnt(0)
	v_pk_fma_f32 v[92:93], v[92:93], v[96:97], v[100:101]
	v_pk_fma_f32 v[78:79], v[78:79], v[94:95], v[98:99]
.LBB0_1884:
	v_pk_fma_f32 v[74:75], v[92:93], s[72:73], v[74:75] op_sel_hi:[1,0,1]
	v_pk_fma_f32 v[72:73], v[78:79], s[72:73], v[72:73] op_sel_hi:[1,0,1]
	s_and_b64 vcc, exec, s[44:45]
	v_cvt_pk_bf16_f32 v72, v72, v73
	v_cvt_pk_bf16_f32 v73, v74, v75
	v_mov_b64_e32 v[148:149], v[72:73]
	v_mov_b64_e32 v[78:79], v[240:241]
	v_lshrrev_b32_e32 v245, 4, v219
	v_lshl_add_u32 v245, v245, 3, v243
	global_load_dwordx4 v[238:241], v245, s[46:47] offset:256
	s_waitcnt lgkmcnt(0)
	v_lshlrev_b32_e32 v74, 16, v78
	v_and_b32_e32 v75, 0xffff0000, v78
	v_lshlrev_b32_e32 v78, 16, v79
	v_and_b32_e32 v79, 0xffff0000, v79
	s_cbranch_vccnz .LBB0_1886
	v_sub_f32_e32 v75, v75, v87
	v_sub_f32_e32 v74, v74, v87
	v_sub_f32_e32 v79, v79, v87
	v_sub_f32_e32 v78, v78, v87
	v_pk_mul_f32 v[74:75], v[88:89], v[74:75]
	v_mov_b32_e32 v89, v88
	v_pk_mul_f32 v[78:79], v[88:89], v[78:79]
	ds_read_b128 v[86:89], v244 offset:192
	ds_read_b128 v[90:93], v244 offset:448
	s_waitcnt lgkmcnt(0)
	v_pk_fma_f32 v[78:79], v[78:79], v[88:89], v[92:93]
	v_pk_fma_f32 v[74:75], v[74:75], v[86:87], v[90:91]

; __device__ __forceinline__ void stats_main(const float* stm, int row, int fq, float& mu, float& rs) {
;     const f32x4* p = (const f32x4*)(stm + (size_t)row * 32 + fq * 8);
;     const f32x4 a = p[0], b = p[1];
;     float s1 = (a.x + a.z) + (b.x + b.z), s2 = (a.y + a.w) + (b.y + b.w);
;     s1 += __shfl_xor(s1, 16); s2 += __shfl_xor(s2, 16); s1 += __shfl_xor(s1, 32); s2 += __shfl_xor(s2, 32);
;     mu = s1 * (1.f / DM); rs = __builtin_amdgcn_rsqf(fmaxf(s2 * (1.f / DM) - mu * mu, 0.f) + LN_EPS);
;     __device__ __forceinline__ void operator()(const f32x4 (&acc)[2][2][4][2], const pg8::Unit& u, int wr, int wc, int fr, int fq) const {
;     ...
;                 const int row = u.pm * 256 + ai * 128 + wr * 64 + m * 16 + fr;
;                 float mu = 0.f, rs = 1.f; if (ln) stats_main(stm_p, row, fq, mu, rs);
.LBB0_1888:
	s_or_b64 exec, exec, s[0:1]
	v_add_u32_e32 v76, 0x80, v146
	v_ashrrev_i32_e32 v77, 31, v76
	s_and_b64 vcc, exec, s[44:45]
	v_lshlrev_b64 v[68:69], 7, v[76:77]
	s_cbranch_vccnz .LBB0_1890
	v_lshl_add_u64 v[74:75], v[134:135], 0, v[68:69]
	s_waitcnt lgkmcnt(0)
	s_waitcnt vmcnt(6)
	v_mov_b64_e32 v[70:71], v[194:195]
	v_mov_b64_e32 v[72:73], v[196:197]
	s_waitcnt vmcnt(7)
	v_mov_b64_e32 v[78:79], v[190:191]
	v_mov_b64_e32 v[80:81], v[192:193]
	s_waitcnt lgkmcnt(0)
	v_mov_b32_e32 v74, v70
	s_waitcnt lgkmcnt(0)
	v_mov_b32_e32 v75, v78
	v_mov_b32_e32 v82, v72
	v_mov_b32_e32 v83, v80
	v_pk_add_f32 v[74:75], v[74:75], v[82:83]
	v_add_f32_e32 v70, v71, v73
	v_add_f32_e32 v72, v79, v81
	v_mov_b32_e32 v71, v74
	v_mov_b32_e32 v73, v75
	v_pk_add_f32 v[70:71], v[70:71], v[72:73]
	ds_bpermute_b32 v73, v165, v71
	ds_bpermute_b32 v72, v165, v70
	s_waitcnt lgkmcnt(0)
	v_pk_add_f32 v[70:71], v[70:71], v[72:73]
	ds_bpermute_b32 v73, v164, v71
	ds_bpermute_b32 v72, v164, v70
	s_waitcnt lgkmcnt(0)
	v_pk_add_f32 v[70:71], v[70:71], v[72:73]
	s_nop 0
	v_pk_mul_f32 v[70:71], v[70:71], s[82:83] op_sel_hi:[1,0]
	s_nop 0
	v_fma_f32 v3, -v71, v71, v70
	v_max_f32_e32 v3, 0, v3
	v_add_f32_e32 v3, 0x3727c5ac, v3
	v_rsq_f32_e32 v72, v3
	s_branch .LBB0_1891

; __device__ __forceinline__ u32x2 pk4(f32x4 v) { u32x2 r; r.x = pk2(v.x, v.y); r.y = pk2(v.z, v.w); return r; }
;     __device__ __forceinline__ void operator()(const f32x4 (&acc)[2][2][4][2], const pg8::Unit& u, int wr, int wc, int fr, int fq) const {
;     ...
;                 for (int bj = 0; bj < 2; ++bj)
; #pragma unroll
;                     for (int n = 0; n < 2; ++n) {
;                         const int col = u.pn * 256 + bj * 128 + wc * 32 + n * 16 + fq * 4;
;                         const u32x2 raw = *(const u32x2*)(src + (size_t)row * DM + col);
;                         f32x4 x = (f32x4){bflo(raw.x), bfhi(raw.x), bflo(raw.y), bfhi(raw.y)};
;                         if (ln) x = (x - mu) * rs * *(const f32x4*)(g + col) + *(const f32x4*)(b + col);
;                         const u32x2 pz = pk4(x * ALPHA + acc[ai][bj][m][n]);
;                         *(u32x2*)(dst + (size_t)row * DM + col) = pz;
.LBB0_1891:
	v_lshlrev_b64 v[74:75], 11, v[76:77]
	v_lshl_add_u64 v[74:75], s[46:47], 0, v[74:75]
	v_lshl_add_u64 v[74:75], v[144:145], 1, v[74:75]
	v_add_u32_e32 v243, 0x50000, v242
	s_waitcnt vmcnt(5)
	v_permlane16_swap_b32_e32 v198, v200
	v_permlane16_swap_b32_e32 v199, v201
	s_nop 0
	v_permlane32_swap_b32_e32 v198, v200
	v_permlane32_swap_b32_e32 v199, v201
	v_mov_b64_e32 v[80:81], v[198:199]
	global_load_dwordx4 v[190:193], v[248:249], off offset:16
	global_load_dwordx4 v[194:197], v[248:249], off
	v_mov_b32_e32 v73, v72
	s_and_b64 vcc, exec, s[44:45]
	s_waitcnt lgkmcnt(0)
	v_lshlrev_b32_e32 v78, 16, v80
	v_and_b32_e32 v79, 0xffff0000, v80
	v_lshlrev_b32_e32 v80, 16, v81
	v_and_b32_e32 v81, 0xffff0000, v81
	s_cbranch_vccnz .LBB0_1893
	v_sub_f32_e32 v79, v79, v71
	v_sub_f32_e32 v78, v78, v71
	v_sub_f32_e32 v81, v81, v71
	v_sub_f32_e32 v80, v80, v71
	v_pk_mul_f32 v[86:87], v[72:73], v[78:79]
	v_mov_b32_e32 v78, v72
	v_mov_b32_e32 v79, v72
	v_pk_mul_f32 v[88:89], v[78:79], v[80:81]
	ds_read_b128 v[78:81], v244
	ds_read_b128 v[82:85], v244 offset:256
	s_waitcnt lgkmcnt(0)
	v_pk_fma_f32 v[80:81], v[88:89], v[80:81], v[84:85]
	v_pk_fma_f32 v[78:79], v[86:87], v[78:79], v[82:83]
.LBB0_1893:
	v_lshlrev_b64 v[76:77], 10, v[76:77]
	v_pk_fma_f32 v[64:65], v[78:79], s[72:73], v[64:65] op_sel_hi:[1,0,1]
	v_pk_fma_f32 v[80:81], v[80:81], s[72:73], v[66:67] op_sel_hi:[1,0,1]
	v_cvt_pk_bf16_f32 v66, v64, v65
	v_lshl_add_u64 v[64:65], v[76:77], 1, s[70:71]
	v_cvt_pk_bf16_f32 v67, v80, v81
	v_lshl_add_u64 v[64:65], v[144:145], 1, v[64:65]
	v_mov_b64_e32 v[148:149], v[66:67]
	v_mov_b64_e32 v[78:79], v[200:201]
	v_lshrrev_b32_e32 v245, 4, v219
	v_lshl_add_u32 v245, v245, 3, v243
	global_load_dwordx4 v[198:201], v245, s[46:47]
	s_and_b64 vcc, exec, s[44:45]
	s_waitcnt lgkmcnt(0)
	v_lshlrev_b32_e32 v76, 16, v78
	v_and_b32_e32 v77, 0xffff0000, v78
	v_lshlrev_b32_e32 v78, 16, v79
	v_and_b32_e32 v79, 0xffff0000, v79
	s_cbranch_vccnz .LBB0_1895
	v_sub_f32_e32 v77, v77, v71
	v_sub_f32_e32 v76, v76, v71
	v_sub_f32_e32 v79, v79, v71
	v_sub_f32_e32 v78, v78, v71
	v_pk_mul_f32 v[84:85], v[72:73], v[76:77]
	v_mov_b32_e32 v76, v72
	v_mov_b32_e32 v77, v72
	v_pk_mul_f32 v[86:87], v[76:77], v[78:79]
	ds_read_b128 v[76:79], v244 offset:64
	ds_read_b128 v[80:83], v244 offset:320
	s_waitcnt lgkmcnt(0)
	v_pk_fma_f32 v[78:79], v[86:87], v[78:79], v[82:83]
	v_pk_fma_f32 v[76:77], v[84:85], v[76:77], v[80:81]
.LBB0_1895:
	v_pk_fma_f32 v[62:63], v[78:79], s[72:73], v[62:63] op_sel_hi:[1,0,1]
	v_pk_fma_f32 v[60:61], v[76:77], s[72:73], v[60:61] op_sel_hi:[1,0,1]
	s_and_b64 vcc, exec, s[44:45]
	v_cvt_pk_bf16_f32 v60, v60, v61
	v_cvt_pk_bf16_f32 v61, v62, v63
	v_mov_b64_e32 v[150:151], v[60:61]
	v_lshrrev_b32_e32 v152, 4, v219
	v_lshlrev_b32_e32 v152, 3, v152
	v_mov_b32_e32 v153, v2
	v_permlane32_swap_b32_e32 v148, v150
	v_permlane32_swap_b32_e32 v149, v151
	v_lshl_add_u64 v[152:153], v[152:153], 0, v[64:65]
	s_nop 0
	v_permlane16_swap_b32_e32 v148, v150
	v_permlane16_swap_b32_e32 v149, v151
	global_store_dwordx4 v[152:153], v[148:151], off sc0
	s_waitcnt vmcnt(7)
	v_permlane16_swap_b32_e32 v202, v204
	v_permlane16_swap_b32_e32 v203, v205
	s_nop 0
	v_permlane32_swap_b32_e32 v202, v204
	v_permlane32_swap_b32_e32 v203, v205
	v_mov_b64_e32 v[76:77], v[202:203]
	s_waitcnt lgkmcnt(0)
	v_lshlrev_b32_e32 v62, 16, v76
	v_and_b32_e32 v63, 0xffff0000, v76
	v_lshlrev_b32_e32 v76, 16, v77
	v_and_b32_e32 v77, 0xffff0000, v77
	s_cbranch_vccnz .LBB0_1897
	v_sub_f32_e32 v77, v77, v71
	v_sub_f32_e32 v76, v76, v71
	v_mov_b32_e32 v78, v72
	v_mov_b32_e32 v79, v72
	v_pk_mul_f32 v[76:77], v[78:79], v[76:77]
	ds_read_b128 v[78:81], v244 offset:128
	ds_read_b128 v[82:85], v244 offset:384
	v_sub_f32_e32 v63, v63, v71
	v_sub_f32_e32 v62, v62, v71
	v_pk_mul_f32 v[62:63], v[72:73], v[62:63]
	s_waitcnt lgkmcnt(0)
	v_pk_fma_f32 v[76:77], v[76:77], v[80:81], v[84:85]
	v_pk_fma_f32 v[62:63], v[62:63], v[78:79], v[82:83]
.LBB0_1897:
	v_pk_fma_f32 v[58:59], v[76:77], s[72:73], v[58:59] op_sel_hi:[1,0,1]
	v_pk_fma_f32 v[56:57], v[62:63], s[72:73], v[56:57] op_sel_hi:[1,0,1]
	s_and_b64 vcc, exec, s[44:45]
	v_cvt_pk_bf16_f32 v56, v56, v57
	v_cvt_pk_bf16_f32 v57, v58, v59
	v_mov_b64_e32 v[148:149], v[56:57]
	v_mov_b64_e32 v[62:63], v[204:205]
	v_lshrrev_b32_e32 v245, 4, v219
	v_lshl_add_u32 v245, v245, 3, v243
	global_load_dwordx4 v[202:205], v245, s[46:47] offset:256
	s_waitcnt lgkmcnt(0)
	v_lshlrev_b32_e32 v58, 16, v62
	v_and_b32_e32 v59, 0xffff0000, v62
	v_lshlrev_b32_e32 v62, 16, v63
	v_and_b32_e32 v63, 0xffff0000, v63
	s_cbranch_vccnz .LBB0_1899
	v_sub_f32_e32 v59, v59, v71
	v_sub_f32_e32 v58, v58, v71
	v_sub_f32_e32 v63, v63, v71
	v_sub_f32_e32 v62, v62, v71
	v_pk_mul_f32 v[58:59], v[72:73], v[58:59]
	v_mov_b32_e32 v73, v72
	v_pk_mul_f32 v[62:63], v[72:73], v[62:63]
	ds_read_b128 v[70:73], v244 offset:192
	ds_read_b128 v[74:77], v244 offset:448
	s_waitcnt lgkmcnt(0)
	v_pk_fma_f32 v[62:63], v[62:63], v[72:73], v[76:77]
	v_pk_fma_f32 v[58:59], v[58:59], v[70:71], v[74:75]

; __device__ __forceinline__ void stats_main(const float* stm, int row, int fq, float& mu, float& rs) {
;     const f32x4* p = (const f32x4*)(stm + (size_t)row * 32 + fq * 8);
;     const f32x4 a = p[0], b = p[1];
;     float s1 = (a.x + a.z) + (b.x + b.z), s2 = (a.y + a.w) + (b.y + b.w);
;     s1 += __shfl_xor(s1, 16); s2 += __shfl_xor(s2, 16); s1 += __shfl_xor(s1, 32); s2 += __shfl_xor(s2, 32);
;     mu = s1 * (1.f / DM); rs = __builtin_amdgcn_rsqf(fmaxf(s2 * (1.f / DM) - mu * mu, 0.f) + LN_EPS);
;     __device__ __forceinline__ void operator()(const f32x4 (&acc)[2][2][4][2], const pg8::Unit& u, int wr, int wc, int fr, int fq) const {
;     ...
;                 const int row = u.pm * 256 + ai * 128 + wr * 64 + m * 16 + fr;
;                 float mu = 0.f, rs = 1.f; if (ln) stats_main(stm_p, row, fq, mu, rs);
.LBB0_1901:
	s_or_b64 exec, exec, s[0:1]
	v_add_u32_e32 v60, 0x90, v146
	v_ashrrev_i32_e32 v61, 31, v60
	s_and_b64 vcc, exec, s[44:45]
	v_lshlrev_b64 v[52:53], 7, v[60:61]
	s_cbranch_vccnz .LBB0_1903
	v_lshl_add_u64 v[58:59], v[134:135], 0, v[52:53]
	s_waitcnt lgkmcnt(0)
	s_waitcnt vmcnt(6)
	v_mov_b64_e32 v[54:55], v[214:215]
	v_mov_b64_e32 v[56:57], v[216:217]
	s_waitcnt vmcnt(7)
	v_mov_b64_e32 v[62:63], v[206:207]
	v_mov_b64_e32 v[64:65], v[208:209]
	s_waitcnt lgkmcnt(0)
	v_mov_b32_e32 v58, v54
	s_waitcnt lgkmcnt(0)
	v_mov_b32_e32 v59, v62
	v_mov_b32_e32 v66, v56
	v_mov_b32_e32 v67, v64
	v_pk_add_f32 v[58:59], v[58:59], v[66:67]
	v_add_f32_e32 v54, v55, v57
	v_add_f32_e32 v56, v63, v65
	v_mov_b32_e32 v55, v58
	v_mov_b32_e32 v57, v59
	v_pk_add_f32 v[54:55], v[54:55], v[56:57]
	ds_bpermute_b32 v57, v165, v55
	ds_bpermute_b32 v56, v165, v54
	s_waitcnt lgkmcnt(0)
	v_pk_add_f32 v[54:55], v[54:55], v[56:57]
	ds_bpermute_b32 v57, v164, v55
	ds_bpermute_b32 v56, v164, v54
	s_waitcnt lgkmcnt(0)
	v_pk_add_f32 v[54:55], v[54:55], v[56:57]
	s_nop 0
	v_pk_mul_f32 v[54:55], v[54:55], s[82:83] op_sel_hi:[1,0]
	s_nop 0
	v_fma_f32 v3, -v55, v55, v54
	v_max_f32_e32 v3, 0, v3
	v_add_f32_e32 v3, 0x3727c5ac, v3
	v_rsq_f32_e32 v56, v3
	s_branch .LBB0_1904

; __device__ __forceinline__ u32x2 pk4(f32x4 v) { u32x2 r; r.x = pk2(v.x, v.y); r.y = pk2(v.z, v.w); return r; }
;     __device__ __forceinline__ void operator()(const f32x4 (&acc)[2][2][4][2], const pg8::Unit& u, int wr, int wc, int fr, int fq) const {
;     ...
;                 for (int bj = 0; bj < 2; ++bj)
; #pragma unroll
;                     for (int n = 0; n < 2; ++n) {
;                         const int col = u.pn * 256 + bj * 128 + wc * 32 + n * 16 + fq * 4;
;                         const u32x2 raw = *(const u32x2*)(src + (size_t)row * DM + col);
;                         f32x4 x = (f32x4){bflo(raw.x), bfhi(raw.x), bflo(raw.y), bfhi(raw.y)};
;                         if (ln) x = (x - mu) * rs * *(const f32x4*)(g + col) + *(const f32x4*)(b + col);
;                         const u32x2 pz = pk4(x * ALPHA + acc[ai][bj][m][n]);
;                         *(u32x2*)(dst + (size_t)row * DM + col) = pz;
;                         const float z0 = bflo(pz.x), z1 = bfhi(pz.x), z2 = bflo(pz.y), z3 = bfhi(pz.y);
;                         s1 += (z0 + z1) + (z2 + z3); s2 += (z0 * z0 + z1 * z1) + (z2 * z2 + z3 * z3);
.LBB0_1904:
	v_lshlrev_b64 v[58:59], 11, v[60:61]
	v_lshl_add_u64 v[58:59], s[46:47], 0, v[58:59]
	v_lshl_add_u64 v[58:59], v[144:145], 1, v[58:59]
	v_add_u32_e32 v243, 0x58000, v242
	s_waitcnt vmcnt(5)
	v_permlane16_swap_b32_e32 v234, v236
	v_permlane16_swap_b32_e32 v235, v237
	s_nop 0
	v_permlane32_swap_b32_e32 v234, v236
	v_permlane32_swap_b32_e32 v235, v237
	v_mov_b64_e32 v[64:65], v[234:235]
	global_load_dwordx4 v[206:209], v[248:249], off offset:2064
	global_load_dwordx4 v[214:217], v[248:249], off offset:2048
	v_mov_b32_e32 v57, v56
	s_and_b64 vcc, exec, s[44:45]
	s_waitcnt lgkmcnt(0)
	v_lshlrev_b32_e32 v62, 16, v64
	v_and_b32_e32 v63, 0xffff0000, v64
	v_lshlrev_b32_e32 v64, 16, v65
	v_and_b32_e32 v65, 0xffff0000, v65
	s_cbranch_vccnz .LBB0_1906
	v_sub_f32_e32 v63, v63, v55
	v_sub_f32_e32 v62, v62, v55
	v_sub_f32_e32 v65, v65, v55
	v_sub_f32_e32 v64, v64, v55
	v_pk_mul_f32 v[70:71], v[56:57], v[62:63]
	v_mov_b32_e32 v62, v56
	v_mov_b32_e32 v63, v56
	v_pk_mul_f32 v[72:73], v[62:63], v[64:65]
	ds_read_b128 v[62:65], v244
	ds_read_b128 v[66:69], v244 offset:256
	s_waitcnt lgkmcnt(0)
	v_pk_fma_f32 v[64:65], v[72:73], v[64:65], v[68:69]
	v_pk_fma_f32 v[62:63], v[70:71], v[62:63], v[66:67]
.LBB0_1906:
	v_lshlrev_b64 v[60:61], 10, v[60:61]
	v_pk_fma_f32 v[48:49], v[62:63], s[72:73], v[48:49] op_sel_hi:[1,0,1]
	v_pk_fma_f32 v[64:65], v[64:65], s[72:73], v[50:51] op_sel_hi:[1,0,1]
	v_cvt_pk_bf16_f32 v50, v48, v49
	v_lshl_add_u64 v[48:49], v[60:61], 1, s[70:71]
	v_cvt_pk_bf16_f32 v51, v64, v65
	v_lshl_add_u64 v[48:49], v[144:145], 1, v[48:49]
	v_mov_b64_e32 v[148:149], v[50:51]
	v_mov_b64_e32 v[62:63], v[236:237]
	v_lshrrev_b32_e32 v245, 4, v219
	v_lshl_add_u32 v245, v245, 3, v243
	global_load_dwordx4 v[234:237], v245, s[46:47]
	s_and_b64 vcc, exec, s[44:45]
	s_waitcnt lgkmcnt(0)
	v_lshlrev_b32_e32 v60, 16, v62
	v_and_b32_e32 v61, 0xffff0000, v62
	v_lshlrev_b32_e32 v62, 16, v63
	v_and_b32_e32 v63, 0xffff0000, v63
	s_cbranch_vccnz .LBB0_1908
	v_sub_f32_e32 v61, v61, v55
	v_sub_f32_e32 v60, v60, v55
	v_sub_f32_e32 v63, v63, v55
	v_sub_f32_e32 v62, v62, v55
	v_pk_mul_f32 v[68:69], v[56:57], v[60:61]
	v_mov_b32_e32 v60, v56
	v_mov_b32_e32 v61, v56
	v_pk_mul_f32 v[70:71], v[60:61], v[62:63]
	ds_read_b128 v[60:63], v244 offset:64
	ds_read_b128 v[64:67], v244 offset:320
	s_waitcnt lgkmcnt(0)
	v_pk_fma_f32 v[62:63], v[70:71], v[62:63], v[66:67]
	v_pk_fma_f32 v[60:61], v[68:69], v[60:61], v[64:65]
.LBB0_1908:
	v_pk_fma_f32 v[46:47], v[62:63], s[72:73], v[46:47] op_sel_hi:[1,0,1]
	v_pk_fma_f32 v[44:45], v[60:61], s[72:73], v[44:45] op_sel_hi:[1,0,1]
	s_and_b64 vcc, exec, s[44:45]
	v_cvt_pk_bf16_f32 v44, v44, v45
	v_cvt_pk_bf16_f32 v45, v46, v47
	v_mov_b64_e32 v[150:151], v[44:45]
	v_lshrrev_b32_e32 v152, 4, v219
	v_lshlrev_b32_e32 v152, 3, v152
	v_mov_b32_e32 v153, v2
	v_permlane32_swap_b32_e32 v148, v150
	v_permlane32_swap_b32_e32 v149, v151
	v_lshl_add_u64 v[152:153], v[152:153], 0, v[48:49]
	s_nop 0
	v_permlane16_swap_b32_e32 v148, v150
	v_permlane16_swap_b32_e32 v149, v151
	global_store_dwordx4 v[152:153], v[148:151], off sc0
	s_waitcnt vmcnt(7)
	v_permlane16_swap_b32_e32 v238, v240
	v_permlane16_swap_b32_e32 v239, v241
	s_nop 0
	v_permlane32_swap_b32_e32 v238, v240
	v_permlane32_swap_b32_e32 v239, v241
	v_mov_b64_e32 v[60:61], v[238:239]
	s_waitcnt lgkmcnt(0)
	v_lshlrev_b32_e32 v46, 16, v60
	v_and_b32_e32 v47, 0xffff0000, v60
	v_lshlrev_b32_e32 v60, 16, v61
	v_and_b32_e32 v61, 0xffff0000, v61
	s_cbranch_vccnz .LBB0_1910
	v_sub_f32_e32 v61, v61, v55
	v_sub_f32_e32 v60, v60, v55
	v_mov_b32_e32 v62, v56
	v_mov_b32_e32 v63, v56
	v_pk_mul_f32 v[60:61], v[62:63], v[60:61]
	ds_read_b128 v[62:65], v244 offset:128
	ds_read_b128 v[66:69], v244 offset:384
	v_sub_f32_e32 v47, v47, v55
	v_sub_f32_e32 v46, v46, v55
	v_pk_mul_f32 v[46:47], v[56:57], v[46:47]
	s_waitcnt lgkmcnt(0)
	v_pk_fma_f32 v[60:61], v[60:61], v[64:65], v[68:69]
	v_pk_fma_f32 v[46:47], v[46:47], v[62:63], v[66:67]
.LBB0_1910:
	v_pk_fma_f32 v[42:43], v[60:61], s[72:73], v[42:43] op_sel_hi:[1,0,1]
	v_pk_fma_f32 v[40:41], v[46:47], s[72:73], v[40:41] op_sel_hi:[1,0,1]
	s_and_b64 vcc, exec, s[44:45]
	v_cvt_pk_bf16_f32 v40, v40, v41
	v_cvt_pk_bf16_f32 v41, v42, v43
	v_mov_b64_e32 v[148:149], v[40:41]
	v_mov_b64_e32 v[46:47], v[240:241]
	v_lshrrev_b32_e32 v245, 4, v219
	v_lshl_add_u32 v245, v245, 3, v243
	global_load_dwordx4 v[238:241], v245, s[46:47] offset:256
	s_waitcnt lgkmcnt(0)
	v_lshlrev_b32_e32 v42, 16, v46
	v_and_b32_e32 v43, 0xffff0000, v46
	v_lshlrev_b32_e32 v46, 16, v47
	v_and_b32_e32 v47, 0xffff0000, v47
	s_cbranch_vccnz .LBB0_1912
	v_sub_f32_e32 v43, v43, v55
	v_sub_f32_e32 v42, v42, v55
	v_sub_f32_e32 v47, v47, v55
	v_sub_f32_e32 v46, v46, v55
	v_pk_mul_f32 v[42:43], v[56:57], v[42:43]
	v_mov_b32_e32 v57, v56
	v_pk_mul_f32 v[46:47], v[56:57], v[46:47]
	ds_read_b128 v[54:57], v244 offset:192
	ds_read_b128 v[58:61], v244 offset:448
	s_waitcnt lgkmcnt(0)
	v_pk_fma_f32 v[46:47], v[46:47], v[56:57], v[60:61]
	v_pk_fma_f32 v[42:43], v[42:43], v[54:55], v[58:59]

; __device__ __forceinline__ void stats_main(const float* stm, int row, int fq, float& mu, float& rs) {
;     const f32x4* p = (const f32x4*)(stm + (size_t)row * 32 + fq * 8);
;     const f32x4 a = p[0], b = p[1];
;     float s1 = (a.x + a.z) + (b.x + b.z), s2 = (a.y + a.w) + (b.y + b.w);
;     s1 += __shfl_xor(s1, 16); s2 += __shfl_xor(s2, 16); s1 += __shfl_xor(s1, 32); s2 += __shfl_xor(s2, 32);
;     mu = s1 * (1.f / DM); rs = __builtin_amdgcn_rsqf(fmaxf(s2 * (1.f / DM) - mu * mu, 0.f) + LN_EPS);
; }
.LBB0_1914:
	s_or_b64 exec, exec, s[0:1]
	v_add_u32_e32 v44, 0xa0, v146
	v_ashrrev_i32_e32 v45, 31, v44
	s_and_b64 vcc, exec, s[44:45]
	v_lshlrev_b64 v[36:37], 7, v[44:45]
	s_cbranch_vccnz .LBB0_1916
	v_lshl_add_u64 v[42:43], v[134:135], 0, v[36:37]
	s_waitcnt lgkmcnt(0)
	s_waitcnt vmcnt(6)
	v_mov_b64_e32 v[38:39], v[194:195]
	v_mov_b64_e32 v[40:41], v[196:197]
	s_waitcnt vmcnt(7)
	v_mov_b64_e32 v[46:47], v[190:191]
	v_mov_b64_e32 v[48:49], v[192:193]
	s_waitcnt lgkmcnt(0)
	v_mov_b32_e32 v42, v38
	s_waitcnt lgkmcnt(0)
	v_mov_b32_e32 v43, v46
	v_mov_b32_e32 v50, v40
	v_mov_b32_e32 v51, v48
	v_pk_add_f32 v[42:43], v[42:43], v[50:51]
	v_add_f32_e32 v38, v39, v41
	v_add_f32_e32 v40, v47, v49
	v_mov_b32_e32 v39, v42
	v_mov_b32_e32 v41, v43
	v_pk_add_f32 v[38:39], v[38:39], v[40:41]
	ds_bpermute_b32 v41, v165, v39
	ds_bpermute_b32 v40, v165, v38
	s_waitcnt lgkmcnt(0)
	v_pk_add_f32 v[38:39], v[38:39], v[40:41]
	ds_bpermute_b32 v41, v164, v39
	ds_bpermute_b32 v40, v164, v38
	s_waitcnt lgkmcnt(0)
	v_pk_add_f32 v[38:39], v[38:39], v[40:41]
	s_nop 0
	v_pk_mul_f32 v[38:39], v[38:39], s[82:83] op_sel_hi:[1,0]
	s_nop 0
	v_fma_f32 v3, -v39, v39, v38
	v_max_f32_e32 v3, 0, v3
	v_add_f32_e32 v3, 0x3727c5ac, v3
	v_rsq_f32_e32 v40, v3
	s_branch .LBB0_1917

; __device__ __forceinline__ u32x2 pk4(f32x4 v) { u32x2 r; r.x = pk2(v.x, v.y); r.y = pk2(v.z, v.w); return r; }
;     __device__ __forceinline__ void operator()(const f32x4 (&acc)[2][2][4][2], const pg8::Unit& u, int wr, int wc, int fr, int fq) const {
;     ...
;                 for (int bj = 0; bj < 2; ++bj)
; #pragma unroll
;                     for (int n = 0; n < 2; ++n) {
;                         const int col = u.pn * 256 + bj * 128 + wc * 32 + n * 16 + fq * 4;
;                         const u32x2 raw = *(const u32x2*)(src + (size_t)row * DM + col);
;                         f32x4 x = (f32x4){bflo(raw.x), bfhi(raw.x), bflo(raw.y), bfhi(raw.y)};
;                         if (ln) x = (x - mu) * rs * *(const f32x4*)(g + col) + *(const f32x4*)(b + col);
;                         const u32x2 pz = pk4(x * ALPHA + acc[ai][bj][m][n]);
;                         *(u32x2*)(dst + (size_t)row * DM + col) = pz;
;                         const float z0 = bflo(pz.x), z1 = bfhi(pz.x), z2 = bflo(pz.y), z3 = bfhi(pz.y);
;                         s1 += (z0 + z1) + (z2 + z3); s2 += (z0 * z0 + z1 * z1) + (z2 * z2 + z3 * z3);
.LBB0_1917:
	v_lshlrev_b64 v[42:43], 11, v[44:45]
	v_lshl_add_u64 v[42:43], s[46:47], 0, v[42:43]
	v_lshl_add_u64 v[42:43], v[144:145], 1, v[42:43]
	s_waitcnt vmcnt(5)
	v_permlane16_swap_b32_e32 v198, v200
	v_permlane16_swap_b32_e32 v199, v201
	s_nop 0
	v_permlane32_swap_b32_e32 v198, v200
	v_permlane32_swap_b32_e32 v199, v201
	v_mov_b64_e32 v[48:49], v[198:199]
	v_mov_b32_e32 v41, v40
	s_and_b64 vcc, exec, s[44:45]
	s_waitcnt lgkmcnt(0)
	v_lshlrev_b32_e32 v46, 16, v48
	v_and_b32_e32 v47, 0xffff0000, v48
	v_lshlrev_b32_e32 v48, 16, v49
	v_and_b32_e32 v49, 0xffff0000, v49
	s_cbranch_vccnz .LBB0_1919
	v_sub_f32_e32 v47, v47, v39
	v_sub_f32_e32 v46, v46, v39
	v_sub_f32_e32 v49, v49, v39
	v_sub_f32_e32 v48, v48, v39
	v_pk_mul_f32 v[54:55], v[40:41], v[46:47]
	v_mov_b32_e32 v46, v40
	v_mov_b32_e32 v47, v40
	v_pk_mul_f32 v[56:57], v[46:47], v[48:49]
	ds_read_b128 v[46:49], v244
	ds_read_b128 v[50:53], v244 offset:256
	s_waitcnt lgkmcnt(0)
	v_pk_fma_f32 v[48:49], v[56:57], v[48:49], v[52:53]
	v_pk_fma_f32 v[46:47], v[54:55], v[46:47], v[50:51]
.LBB0_1919:
	v_lshlrev_b64 v[44:45], 10, v[44:45]
	v_pk_fma_f32 v[32:33], v[46:47], s[72:73], v[32:33] op_sel_hi:[1,0,1]
	v_pk_fma_f32 v[48:49], v[48:49], s[72:73], v[34:35] op_sel_hi:[1,0,1]
	v_cvt_pk_bf16_f32 v34, v32, v33
	v_lshl_add_u64 v[32:33], v[44:45], 1, s[70:71]
	v_cvt_pk_bf16_f32 v35, v48, v49
	v_lshl_add_u64 v[32:33], v[144:145], 1, v[32:33]
	v_mov_b64_e32 v[148:149], v[34:35]
	v_mov_b64_e32 v[46:47], v[200:201]
	s_and_b64 vcc, exec, s[44:45]
	s_waitcnt lgkmcnt(0)
	v_lshlrev_b32_e32 v44, 16, v46
	v_and_b32_e32 v45, 0xffff0000, v46
	v_lshlrev_b32_e32 v46, 16, v47
	v_and_b32_e32 v47, 0xffff0000, v47
	s_cbranch_vccnz .LBB0_1921
	v_sub_f32_e32 v45, v45, v39
	v_sub_f32_e32 v44, v44, v39
	v_sub_f32_e32 v47, v47, v39
	v_sub_f32_e32 v46, v46, v39
	v_pk_mul_f32 v[52:53], v[40:41], v[44:45]
	v_mov_b32_e32 v44, v40
	v_mov_b32_e32 v45, v40
	v_pk_mul_f32 v[54:55], v[44:45], v[46:47]
	ds_read_b128 v[44:47], v244 offset:64
	ds_read_b128 v[48:51], v244 offset:320
	s_waitcnt lgkmcnt(0)
	v_pk_fma_f32 v[46:47], v[54:55], v[46:47], v[50:51]
	v_pk_fma_f32 v[44:45], v[52:53], v[44:45], v[48:49]
.LBB0_1921:
	v_pk_fma_f32 v[30:31], v[46:47], s[72:73], v[30:31] op_sel_hi:[1,0,1]
	v_pk_fma_f32 v[28:29], v[44:45], s[72:73], v[28:29] op_sel_hi:[1,0,1]
	s_and_b64 vcc, exec, s[44:45]
	v_cvt_pk_bf16_f32 v28, v28, v29
	v_cvt_pk_bf16_f32 v29, v30, v31
	v_mov_b64_e32 v[150:151], v[28:29]
	v_lshrrev_b32_e32 v152, 4, v219
	v_lshlrev_b32_e32 v152, 3, v152
	v_mov_b32_e32 v153, v2
	v_permlane32_swap_b32_e32 v148, v150
	v_permlane32_swap_b32_e32 v149, v151
	v_lshl_add_u64 v[152:153], v[152:153], 0, v[32:33]
	s_nop 0
	v_permlane16_swap_b32_e32 v148, v150
	v_permlane16_swap_b32_e32 v149, v151
	global_store_dwordx4 v[152:153], v[148:151], off sc0
	s_waitcnt vmcnt(4)
	v_permlane16_swap_b32_e32 v202, v204
	v_permlane16_swap_b32_e32 v203, v205
	s_nop 0
	v_permlane32_swap_b32_e32 v202, v204
	v_permlane32_swap_b32_e32 v203, v205
	v_mov_b64_e32 v[44:45], v[202:203]
	s_waitcnt lgkmcnt(0)
	v_lshlrev_b32_e32 v30, 16, v44
	v_and_b32_e32 v31, 0xffff0000, v44
	v_lshlrev_b32_e32 v44, 16, v45
	v_and_b32_e32 v45, 0xffff0000, v45
	s_cbranch_vccnz .LBB0_1923
	v_sub_f32_e32 v45, v45, v39
	v_sub_f32_e32 v44, v44, v39
	v_mov_b32_e32 v46, v40
	v_mov_b32_e32 v47, v40
	v_pk_mul_f32 v[44:45], v[46:47], v[44:45]
	ds_read_b128 v[46:49], v244 offset:128
	ds_read_b128 v[50:53], v244 offset:384
	v_sub_f32_e32 v31, v31, v39
	v_sub_f32_e32 v30, v30, v39
	v_pk_mul_f32 v[30:31], v[40:41], v[30:31]
	s_waitcnt lgkmcnt(0)
	v_pk_fma_f32 v[44:45], v[44:45], v[48:49], v[52:53]
	v_pk_fma_f32 v[30:31], v[30:31], v[46:47], v[50:51]
.LBB0_1923:
	v_pk_fma_f32 v[26:27], v[44:45], s[72:73], v[26:27] op_sel_hi:[1,0,1]
	v_pk_fma_f32 v[24:25], v[30:31], s[72:73], v[24:25] op_sel_hi:[1,0,1]
	s_and_b64 vcc, exec, s[44:45]
	v_cvt_pk_bf16_f32 v24, v24, v25
	v_cvt_pk_bf16_f32 v25, v26, v27
	v_mov_b64_e32 v[148:149], v[24:25]
	v_mov_b64_e32 v[30:31], v[204:205]
	s_waitcnt lgkmcnt(0)
	v_lshlrev_b32_e32 v26, 16, v30
	v_and_b32_e32 v27, 0xffff0000, v30
	v_lshlrev_b32_e32 v30, 16, v31
	v_and_b32_e32 v31, 0xffff0000, v31
	s_cbranch_vccnz .LBB0_1925
	v_sub_f32_e32 v27, v27, v39
	v_sub_f32_e32 v26, v26, v39
	v_sub_f32_e32 v31, v31, v39
	v_sub_f32_e32 v30, v30, v39
	v_pk_mul_f32 v[26:27], v[40:41], v[26:27]
	v_mov_b32_e32 v41, v40
	v_pk_mul_f32 v[30:31], v[40:41], v[30:31]
	ds_read_b128 v[38:41], v244 offset:192
	ds_read_b128 v[42:45], v244 offset:448
	s_waitcnt lgkmcnt(0)
	v_pk_fma_f32 v[30:31], v[30:31], v[40:41], v[44:45]
	v_pk_fma_f32 v[26:27], v[26:27], v[38:39], v[42:43]

; __device__ __forceinline__ void stats_main(const float* stm, int row, int fq, float& mu, float& rs) {
;     const f32x4* p = (const f32x4*)(stm + (size_t)row * 32 + fq * 8);
;     const f32x4 a = p[0], b = p[1];
;     float s1 = (a.x + a.z) + (b.x + b.z), s2 = (a.y + a.w) + (b.y + b.w);
;     s1 += __shfl_xor(s1, 16); s2 += __shfl_xor(s2, 16); s1 += __shfl_xor(s1, 32); s2 += __shfl_xor(s2, 32);
;     mu = s1 * (1.f / DM); rs = __builtin_amdgcn_rsqf(fmaxf(s2 * (1.f / DM) - mu * mu, 0.f) + LN_EPS);
; }
.LBB0_1927:
	s_or_b64 exec, exec, s[0:1]
	v_add_u32_e32 v28, 0xb0, v146
	v_ashrrev_i32_e32 v29, 31, v28
	s_and_b64 vcc, exec, s[44:45]
	v_lshlrev_b64 v[20:21], 7, v[28:29]
	s_cbranch_vccnz .LBB0_1929
	v_lshl_add_u64 v[26:27], v[134:135], 0, v[20:21]
	s_waitcnt lgkmcnt(0)
	s_waitcnt vmcnt(2)
	v_mov_b64_e32 v[22:23], v[214:215]
	v_mov_b64_e32 v[24:25], v[216:217]
	s_waitcnt vmcnt(3)
	v_mov_b64_e32 v[30:31], v[206:207]
	v_mov_b64_e32 v[32:33], v[208:209]
	s_waitcnt lgkmcnt(0)
	v_mov_b32_e32 v26, v22
	s_waitcnt lgkmcnt(0)
	v_mov_b32_e32 v27, v30
	v_mov_b32_e32 v34, v24
	v_mov_b32_e32 v35, v32
	v_pk_add_f32 v[26:27], v[26:27], v[34:35]
	v_add_f32_e32 v22, v23, v25
	v_add_f32_e32 v24, v31, v33
	v_mov_b32_e32 v23, v26
	v_mov_b32_e32 v25, v27
	v_pk_add_f32 v[22:23], v[22:23], v[24:25]
	ds_bpermute_b32 v25, v165, v23
	ds_bpermute_b32 v24, v165, v22
	s_waitcnt lgkmcnt(0)
	v_pk_add_f32 v[22:23], v[22:23], v[24:25]
	ds_bpermute_b32 v25, v164, v23
	ds_bpermute_b32 v24, v164, v22
	s_waitcnt lgkmcnt(0)
	v_pk_add_f32 v[22:23], v[22:23], v[24:25]
	s_nop 0
	v_pk_mul_f32 v[22:23], v[22:23], s[82:83] op_sel_hi:[1,0]
	s_nop 0
	v_fma_f32 v3, -v23, v23, v22
	v_max_f32_e32 v3, 0, v3
	v_add_f32_e32 v3, 0x3727c5ac, v3
	v_rsq_f32_e32 v24, v3
	s_branch .LBB0_1930

; __device__ __forceinline__ u32x2 pk4(f32x4 v) { u32x2 r; r.x = pk2(v.x, v.y); r.y = pk2(v.z, v.w); return r; }
;     __device__ __forceinline__ void operator()(const f32x4 (&acc)[2][2][4][2], const pg8::Unit& u, int wr, int wc, int fr, int fq) const {
;     ...
;                 for (int bj = 0; bj < 2; ++bj)
; #pragma unroll
;                     for (int n = 0; n < 2; ++n) {
;                         const int col = u.pn * 256 + bj * 128 + wc * 32 + n * 16 + fq * 4;
;                         const u32x2 raw = *(const u32x2*)(src + (size_t)row * DM + col);
;                         f32x4 x = (f32x4){bflo(raw.x), bfhi(raw.x), bflo(raw.y), bfhi(raw.y)};
;                         if (ln) x = (x - mu) * rs * *(const f32x4*)(g + col) + *(const f32x4*)(b + col);
;                         const u32x2 pz = pk4(x * ALPHA + acc[ai][bj][m][n]);
;                         *(u32x2*)(dst + (size_t)row * DM + col) = pz;
;                         const float z0 = bflo(pz.x), z1 = bfhi(pz.x), z2 = bflo(pz.y), z3 = bfhi(pz.y);
;                         s1 += (z0 + z1) + (z2 + z3); s2 += (z0 * z0 + z1 * z1) + (z2 * z2 + z3 * z3);
.LBB0_1930:
	v_lshlrev_b64 v[26:27], 11, v[28:29]
	v_lshl_add_u64 v[26:27], s[46:47], 0, v[26:27]
	v_lshl_add_u64 v[26:27], v[144:145], 1, v[26:27]
	s_waitcnt vmcnt(1)
	v_permlane16_swap_b32_e32 v234, v236
	v_permlane16_swap_b32_e32 v235, v237
	s_nop 0
	v_permlane32_swap_b32_e32 v234, v236
	v_permlane32_swap_b32_e32 v235, v237
	v_mov_b64_e32 v[32:33], v[234:235]
	v_mov_b32_e32 v25, v24
	s_and_b64 vcc, exec, s[44:45]
	s_waitcnt lgkmcnt(0)
	v_lshlrev_b32_e32 v30, 16, v32
	v_and_b32_e32 v31, 0xffff0000, v32
	v_lshlrev_b32_e32 v32, 16, v33
	v_and_b32_e32 v33, 0xffff0000, v33
	s_cbranch_vccnz .LBB0_1932
	v_sub_f32_e32 v31, v31, v23
	v_sub_f32_e32 v30, v30, v23
	v_sub_f32_e32 v33, v33, v23
	v_sub_f32_e32 v32, v32, v23
	v_pk_mul_f32 v[38:39], v[24:25], v[30:31]
	v_mov_b32_e32 v30, v24
	v_mov_b32_e32 v31, v24
	v_pk_mul_f32 v[40:41], v[30:31], v[32:33]
	ds_read_b128 v[30:33], v244
	ds_read_b128 v[34:37], v244 offset:256
	s_waitcnt lgkmcnt(0)
	v_pk_fma_f32 v[32:33], v[40:41], v[32:33], v[36:37]
	v_pk_fma_f32 v[30:31], v[38:39], v[30:31], v[34:35]
.LBB0_1932:
	v_lshlrev_b64 v[28:29], 10, v[28:29]
	v_pk_fma_f32 v[16:17], v[30:31], s[72:73], v[16:17] op_sel_hi:[1,0,1]
	v_pk_fma_f32 v[32:33], v[32:33], s[72:73], v[18:19] op_sel_hi:[1,0,1]
	v_cvt_pk_bf16_f32 v18, v16, v17
	v_lshl_add_u64 v[16:17], v[28:29], 1, s[70:71]
	v_cvt_pk_bf16_f32 v19, v32, v33
	v_lshl_add_u64 v[16:17], v[144:145], 1, v[16:17]
	v_mov_b64_e32 v[148:149], v[18:19]
	v_mov_b64_e32 v[30:31], v[236:237]
	s_and_b64 vcc, exec, s[44:45]
	s_waitcnt lgkmcnt(0)
	v_lshlrev_b32_e32 v28, 16, v30
	v_and_b32_e32 v29, 0xffff0000, v30
	v_lshlrev_b32_e32 v30, 16, v31
	v_and_b32_e32 v31, 0xffff0000, v31
	s_cbranch_vccnz .LBB0_1934
	v_sub_f32_e32 v29, v29, v23
	v_sub_f32_e32 v28, v28, v23
	v_sub_f32_e32 v31, v31, v23
	v_sub_f32_e32 v30, v30, v23
	v_pk_mul_f32 v[36:37], v[24:25], v[28:29]
	v_mov_b32_e32 v28, v24
	v_mov_b32_e32 v29, v24
	v_pk_mul_f32 v[38:39], v[28:29], v[30:31]
	ds_read_b128 v[28:31], v244 offset:64
	ds_read_b128 v[32:35], v244 offset:320
	s_waitcnt lgkmcnt(0)
	v_pk_fma_f32 v[30:31], v[38:39], v[30:31], v[34:35]
	v_pk_fma_f32 v[28:29], v[36:37], v[28:29], v[32:33]
.LBB0_1934:
	v_pk_fma_f32 v[14:15], v[30:31], s[72:73], v[14:15] op_sel_hi:[1,0,1]
	v_pk_fma_f32 v[12:13], v[28:29], s[72:73], v[12:13] op_sel_hi:[1,0,1]
	s_and_b64 vcc, exec, s[44:45]
	v_cvt_pk_bf16_f32 v12, v12, v13
	v_cvt_pk_bf16_f32 v13, v14, v15
	v_mov_b64_e32 v[150:151], v[12:13]
	v_lshrrev_b32_e32 v146, 4, v219
	v_lshlrev_b32_e32 v146, 3, v146
	v_mov_b32_e32 v147, v2
	v_permlane32_swap_b32_e32 v148, v150
	v_permlane32_swap_b32_e32 v149, v151
	v_lshl_add_u64 v[146:147], v[146:147], 0, v[16:17]
	s_nop 0
	v_permlane16_swap_b32_e32 v148, v150
	v_permlane16_swap_b32_e32 v149, v151
	global_store_dwordx4 v[146:147], v[148:151], off sc0
	s_waitcnt vmcnt(0)
	v_permlane16_swap_b32_e32 v238, v240
	v_permlane16_swap_b32_e32 v239, v241
	s_nop 0
	v_permlane32_swap_b32_e32 v238, v240
	v_permlane32_swap_b32_e32 v239, v241
	v_mov_b64_e32 v[28:29], v[238:239]
	s_waitcnt lgkmcnt(0)
	v_lshlrev_b32_e32 v14, 16, v28
	v_and_b32_e32 v15, 0xffff0000, v28
	v_lshlrev_b32_e32 v28, 16, v29
	v_and_b32_e32 v29, 0xffff0000, v29
	s_cbranch_vccnz .LBB0_1936
	v_sub_f32_e32 v29, v29, v23
	v_sub_f32_e32 v28, v28, v23
	v_mov_b32_e32 v30, v24
	v_mov_b32_e32 v31, v24
	v_pk_mul_f32 v[28:29], v[30:31], v[28:29]
	ds_read_b128 v[30:33], v244 offset:128
	ds_read_b128 v[34:37], v244 offset:384
	v_sub_f32_e32 v15, v15, v23
	v_sub_f32_e32 v14, v14, v23
	v_pk_mul_f32 v[14:15], v[24:25], v[14:15]
	s_waitcnt lgkmcnt(0)
	v_pk_fma_f32 v[28:29], v[28:29], v[32:33], v[36:37]
	v_pk_fma_f32 v[14:15], v[14:15], v[30:31], v[34:35]
.LBB0_1936:
	v_pk_fma_f32 v[10:11], v[28:29], s[72:73], v[10:11] op_sel_hi:[1,0,1]
	v_pk_fma_f32 v[8:9], v[14:15], s[72:73], v[8:9] op_sel_hi:[1,0,1]
	s_and_b64 vcc, exec, s[44:45]
	v_cvt_pk_bf16_f32 v8, v8, v9
	v_cvt_pk_bf16_f32 v9, v10, v11
	v_mov_b64_e32 v[148:149], v[8:9]
	v_mov_b64_e32 v[14:15], v[240:241]
	s_waitcnt lgkmcnt(0)
	v_lshlrev_b32_e32 v10, 16, v14
	v_and_b32_e32 v11, 0xffff0000, v14
	v_lshlrev_b32_e32 v14, 16, v15
	v_and_b32_e32 v15, 0xffff0000, v15
	s_cbranch_vccnz .LBB0_1938
	v_sub_f32_e32 v11, v11, v23
	v_sub_f32_e32 v10, v10, v23
	v_sub_f32_e32 v15, v15, v23
	v_sub_f32_e32 v14, v14, v23
	v_pk_mul_f32 v[10:11], v[24:25], v[10:11]
	v_mov_b32_e32 v25, v24
	v_pk_mul_f32 v[14:15], v[24:25], v[14:15]
	ds_read_b128 v[22:25], v244 offset:192
	ds_read_b128 v[26:29], v244 offset:448
	s_waitcnt lgkmcnt(0)
	v_pk_fma_f32 v[14:15], v[14:15], v[24:25], v[28:29]
	v_pk_fma_f32 v[10:11], v[10:11], v[22:23], v[26:27]

; __device__ __forceinline__ u32x2 pk4(f32x4 v) { u32x2 r; r.x = pk2(v.x, v.y); r.y = pk2(v.z, v.w); return r; }
;     __device__ __forceinline__ void operator()(int row, int col, f32x4 v, int, float&, float&) const { *(u32x2*)(O + (size_t)row * ldc + col) = pk4(v * s); }
; __device__ __forceinline__ void stats_main(const float* stm, int row, int fq, float& mu, float& rs) {
;     const f32x4* p = (const f32x4*)(stm + (size_t)row * 32 + fq * 8);
;     const f32x4 a = p[0], b = p[1];
;     float s1 = (a.x + a.z) + (b.x + b.z), s2 = (a.y + a.w) + (b.y + b.w);
;     s1 += __shfl_xor(s1, 16); s2 += __shfl_xor(s2, 16); s1 += __shfl_xor(s1, 32); s2 += __shfl_xor(s2, 32);
;     mu = s1 * (1.f / DM); rs = __builtin_amdgcn_rsqf(fmaxf(s2 * (1.f / DM) - mu * mu, 0.f) + LN_EPS);
; }
;     __device__ __forceinline__ void operator()(const f32x4 (&acc)[2][2][4][2], const pg8::Unit& u, int wr, int wc, int fr, int fq) const {
; #pragma unroll
;         for (int ai = 0; ai < 2; ++ai)
; #pragma unroll
;             for (int m = 0; m < 4; ++m) {
;                 const int row = u.pm * 256 + ai * 128 + wr * 64 + m * 16 + fr;
;                 float mu = 0.f, rs = 1.f; if (ln) stats_main(stm_p, row, fq, mu, rs);
;                 float s1 = 0.f, s2 = 0.f;
; #pragma unroll
;                 for (int bj = 0; bj < 2; ++bj)
; #pragma unroll
;                     for (int n = 0; n < 2; ++n) {
;                         const int col = u.pn * 256 + bj * 128 + wc * 32 + n * 16 + fq * 4;
;                         const u32x2 raw = *(const u32x2*)(src + (size_t)row * DM + col);
;                         f32x4 x = (f32x4){bflo(raw.x), bfhi(raw.x), bflo(raw.y), bfhi(raw.y)};
;                         if (ln) x = (x - mu) * rs * *(const f32x4*)(g + col) + *(const f32x4*)(b + col);
;                         const u32x2 pz = pk4(x * ALPHA + acc[ai][bj][m][n]);
;                         *(u32x2*)(dst + (size_t)row * DM + col) = pz;
;                         const float z0 = bflo(pz.x), z1 = bfhi(pz.x), z2 = bflo(pz.y), z3 = bfhi(pz.y);
;                         s1 += (z0 + z1) + (z2 + z3); s2 += (z0 * z0 + z1 * z1) + (z2 * z2 + z3 * z3);
.LBB0_2203:
	v_readlane_b32 s70, v250, 30
	v_readlane_b32 s71, v250, 31
	v_and_b32_e32 v244, 0xfffffff0, v166
	v_lshl_add_u32 v244, s22, 8, v244
	v_and_b32_e32 v245, 31, v219
	v_add_u32_e32 v244, v244, v245
	v_lshrrev_b32_e32 v245, 5, v219
	v_lshl_add_u32 v244, v245, 7, v244
	v_lshlrev_b32_e32 v244, 2, v244
	global_load_dword v214, v244, s[46:47]
	global_load_dword v215, v244, s[48:49]
	v_lshl_add_u32 v245, s23, 8, v164
	v_lshl_add_u32 v244, s22, 8, v166
	v_lshlrev_b32_e32 v242, 11, v245
	v_lshl_add_u32 v242, v244, 1, v242
	v_lshlrev_b32_e32 v246, 7, v245
	v_mov_b32_e32 v247, 0
	v_lshlrev_b32_e32 v248, 7, v245
	v_mov_b32_e32 v249, 0
	v_add_u32_e32 v246, 0x1000, v246
	v_add_u32_e32 v248, 0x5000, v248
	v_lshl_add_u64 v[246:247], v[246:247], 0, v[134:135]
	v_lshl_add_u64 v[248:249], v[248:249], 0, v[134:135]
	global_load_dwordx4 v[190:193], v[246:247], off offset:-4080
	global_load_dwordx4 v[194:197], v[246:247], off offset:-4096
	v_lshrrev_b32_e32 v245, 4, v219
	v_lshl_add_u32 v245, v245, 3, v242
	global_load_dwordx4 v[198:201], v245, s[70:71]
	v_lshrrev_b32_e32 v245, 4, v219
	v_lshl_add_u32 v245, v245, 3, v242
	global_load_dwordx4 v[202:205], v245, s[70:71] offset:256
	v_lshrrev_b32_e32 v245, 6, v164
	v_lshrrev_b32_e32 v244, 5, v166
	v_lshl_add_u32 v245, v245, 2, v244
	v_lshlrev_b32_e32 v245, 9, v245
	v_and_b32_e32 v244, 12, v166
	v_lshl_add_u32 v244, v244, 2, v245
	v_add_u32_e32 v244, 0x20000, v244
	v_lshl_add_u32 v245, v219, 2, v245
	v_add_u32_e32 v245, 0x20000, v245
	s_waitcnt vmcnt(5)
	ds_write_b32 v245, v214
	s_waitcnt vmcnt(4)
	ds_write_b32 v245, v215 offset:256
	v_add_u32_e32 v243, 0x8000, v242
	global_load_dwordx4 v[206:209], v[246:247], off offset:-2032
	global_load_dwordx4 v[214:217], v[246:247], off offset:-2048
	v_lshrrev_b32_e32 v245, 4, v219
	v_lshl_add_u32 v245, v245, 3, v243
	global_load_dwordx4 v[234:237], v245, s[70:71]
	v_lshrrev_b32_e32 v245, 4, v219
	v_lshl_add_u32 v245, v245, 3, v243
	global_load_dwordx4 v[238:241], v245, s[70:71] offset:256
	s_waitcnt lgkmcnt(0)
	v_and_b32_e32 v140, 64, v219
	v_lshl_add_u32 v146, s23, 8, v164
	v_xor_b32_e32 v3, 16, v219
	v_add_u32_e32 v140, 64, v140
	v_cmp_lt_i32_e32 vcc, v3, v140
	v_ashrrev_i32_e32 v147, 31, v146
	v_lshlrev_b64 v[148:149], 7, v[146:147]
	v_cndmask_b32_e32 v3, v219, v3, vcc
	v_lshlrev_b32_e32 v181, 2, v3
	v_xor_b32_e32 v3, 32, v219
	v_lshl_add_u64 v[150:151], v[134:135], 0, v[148:149]
	v_cmp_lt_i32_e32 vcc, v3, v140
	s_waitcnt vmcnt(7)
	v_mov_b64_e32 v[140:141], v[190:191]
	v_mov_b64_e32 v[142:143], v[192:193]
	global_load_dwordx4 v[190:193], v[246:247], off offset:16
	s_nop 0
	s_waitcnt vmcnt(7)
	v_mov_b64_e32 v[150:151], v[194:195]
	v_mov_b64_e32 v[152:153], v[196:197]
	global_load_dwordx4 v[194:197], v[246:247], off
	v_cndmask_b32_e32 v3, v219, v3, vcc
	v_lshlrev_b32_e32 v180, 2, v3
	v_readlane_b32 s70, v250, 30
	v_lshl_add_u32 v144, s22, 8, v166
	v_readlane_b32 s71, v250, 31
	v_ashrrev_i32_e32 v145, 31, v144
	s_lshl_b32 s0, s22, 3
	v_readlane_b32 s1, v252, 30
	s_or_b32 s60, s0, s1
	s_ashr_i32 s61, s60, 31
	s_waitcnt lgkmcnt(0)
	v_pk_add_f32 v[140:141], v[140:141], v[142:143]
	v_pk_add_f32 v[150:151], v[150:151], v[152:153]
	s_nop 0
	v_pk_add_f32 v[140:141], v[150:151], v[140:141]
	ds_bpermute_b32 v142, v181, v140
	ds_bpermute_b32 v143, v181, v141
	s_waitcnt lgkmcnt(0)
	v_pk_add_f32 v[140:141], v[140:141], v[142:143]
	ds_bpermute_b32 v142, v180, v140
	ds_bpermute_b32 v143, v180, v141
	s_waitcnt lgkmcnt(0)
	v_pk_add_f32 v[140:141], v[140:141], v[142:143]
	s_nop 0
	v_pk_mul_f32 v[160:161], v[140:141], s[82:83] op_sel_hi:[1,0]
	v_lshlrev_b64 v[140:141], 11, v[146:147]
	v_lshl_add_u64 v[140:141], s[70:71], 0, v[140:141]
	v_lshl_add_u64 v[152:153], v[144:145], 1, v[140:141]
	v_add_u32_e32 v243, 0x10000, v242
	s_waitcnt vmcnt(7)
	v_permlane16_swap_b32_e32 v198, v200
	v_permlane16_swap_b32_e32 v199, v201
	s_nop 0
	v_permlane32_swap_b32_e32 v198, v200
	v_permlane32_swap_b32_e32 v199, v201
	v_mov_b64_e32 v[140:141], v[198:199]
	v_fma_f32 v3, -v160, v160, v161
	v_max_f32_e32 v3, 0, v3
	v_add_f32_e32 v3, 0x3727c5ac, v3
	v_rsq_f32_e32 v162, v3
	s_waitcnt lgkmcnt(0)
	v_lshlrev_b32_e32 v142, 16, v141
	v_and_b32_e32 v143, 0xffff0000, v141
	v_lshlrev_b32_e32 v3, 16, v140
	v_and_b32_e32 v140, 0xffff0000, v140
	v_sub_f32_e32 v143, v143, v160
	v_sub_f32_e32 v142, v142, v160
	v_sub_f32_e32 v141, v140, v160
	v_sub_f32_e32 v140, v3, v160
	v_pk_mul_f32 v[150:151], v[142:143], v[162:163] op_sel_hi:[1,0]
	v_lshlrev_b64 v[142:143], 2, v[144:145]
	v_pk_mul_f32 v[158:159], v[140:141], v[162:163] op_sel_hi:[1,0]
	v_lshl_add_u64 v[140:141], s[46:47], 0, v[142:143]
	v_lshl_add_u64 v[142:143], s[48:49], 0, v[142:143]
	ds_read_b128 v[154:157], v244
	ds_read_b128 v[182:185], v244 offset:256
	s_waitcnt lgkmcnt(0)
	v_pk_fma_f32 v[154:155], v[154:155], v[158:159], v[182:183]
	s_nop 0
	v_pk_fma_f32 v[128:129], v[154:155], s[72:73], v[128:129] op_sel_hi:[1,0,1]
	v_mov_b64_e32 v[154:155], v[200:201]
	v_lshrrev_b32_e32 v245, 4, v219
	v_lshl_add_u32 v245, v245, 3, v243
	global_load_dwordx4 v[198:201], v245, s[70:71]
	v_pk_fma_f32 v[150:151], v[156:157], v[150:151], v[184:185]
	s_waitcnt lgkmcnt(0)
	v_lshlrev_b32_e32 v3, 16, v154
	v_pk_fma_f32 v[130:131], v[150:151], s[72:73], v[130:131] op_sel_hi:[1,0,1]
	v_cvt_pk_bf16_f32 v150, v128, v129
	v_cvt_pk_bf16_f32 v151, v130, v131
	v_and_b32_e32 v129, 0xffff0000, v154
	v_lshlrev_b32_e32 v131, 16, v155
	v_and_b32_e32 v147, 0xffff0000, v155
	global_store_dwordx2 v[152:153], v[150:151], off
	v_sub_f32_e32 v155, v129, v160
	v_sub_f32_e32 v154, v3, v160
	v_sub_f32_e32 v157, v147, v160
	v_sub_f32_e32 v156, v131, v160
	v_pk_mul_f32 v[158:159], v[162:163], v[156:157] op_sel_hi:[0,1]
	v_pk_mul_f32 v[168:169], v[162:163], v[154:155] op_sel_hi:[0,1]
	ds_read_b128 v[154:157], v244 offset:64
	ds_read_b128 v[182:185], v244 offset:320
	v_and_b32_e32 v130, 0xffff0000, v150
	v_lshlrev_b32_e32 v128, 16, v151
	s_waitcnt lgkmcnt(0)
; __device__ __forceinline__ u32x2 pk4(f32x4 v) { u32x2 r; r.x = pk2(v.x, v.y); r.y = pk2(v.z, v.w); return r; }
;     __device__ __forceinline__ void operator()(const f32x4 (&acc)[2][2][4][2], const pg8::Unit& u, int wr, int wc, int fr, int fq) const {
;     ...
;                 for (int bj = 0; bj < 2; ++bj)
; #pragma unroll
;                     for (int n = 0; n < 2; ++n) {
;                         const int col = u.pn * 256 + bj * 128 + wc * 32 + n * 16 + fq * 4;
;                         const u32x2 raw = *(const u32x2*)(src + (size_t)row * DM + col);
;                         f32x4 x = (f32x4){bflo(raw.x), bfhi(raw.x), bflo(raw.y), bfhi(raw.y)};
;                         if (ln) x = (x - mu) * rs * *(const f32x4*)(g + col) + *(const f32x4*)(b + col);
;                         const u32x2 pz = pk4(x * ALPHA + acc[ai][bj][m][n]);
;                         *(u32x2*)(dst + (size_t)row * DM + col) = pz;
;                         const float z0 = bflo(pz.x), z1 = bfhi(pz.x), z2 = bflo(pz.y), z3 = bfhi(pz.y);
;                         s1 += (z0 + z1) + (z2 + z3); s2 += (z0 * z0 + z1 * z1) + (z2 * z2 + z3 * z3);
;                     }
;                 s1 += __shfl_xor(s1, 16); s2 += __shfl_xor(s2, 16); s1 += __shfl_xor(s1, 32); s2 += __shfl_xor(s2, 32);
;                 if (fq == 0) { float* p = stm_n + (size_t)row * 32 + (u.pn * 4 + wc) * 2; p[0] = s1; p[1] = s2; }
	v_pk_fma_f32 v[154:155], v[154:155], v[168:169], v[182:183]
	s_nop 0
	v_pk_fma_f32 v[124:125], v[154:155], s[72:73], v[124:125] op_sel_hi:[1,0,1]
	s_waitcnt vmcnt(7)
	v_permlane16_swap_b32_e32 v202, v204
	v_permlane16_swap_b32_e32 v203, v205
	s_nop 0
	v_permlane32_swap_b32_e32 v202, v204
	v_permlane32_swap_b32_e32 v203, v205
	v_mov_b64_e32 v[154:155], v[202:203]
	v_pk_fma_f32 v[156:157], v[156:157], v[158:159], v[184:185]
	v_cvt_pk_bf16_f32 v158, v124, v125
	v_pk_fma_f32 v[126:127], v[156:157], s[72:73], v[126:127] op_sel_hi:[1,0,1]
	s_waitcnt lgkmcnt(0)
	v_lshlrev_b32_e32 v3, 16, v154
	v_cvt_pk_bf16_f32 v159, v126, v127
	v_lshlrev_b32_e32 v126, 16, v159
	v_and_b32_e32 v127, 0xffff0000, v159
	v_mul_f32_e32 v124, v126, v126
	v_pk_fma_f32 v[124:125], v[126:127], v[126:127], v[124:125] op_sel_hi:[1,1,0]
	v_lshlrev_b32_e32 v129, 16, v155
	v_and_b32_e32 v124, 0xffff0000, v154
	v_and_b32_e32 v131, 0xffff0000, v155
	global_store_dwordx2 v[152:153], v[158:159], off offset:32
	v_sub_f32_e32 v155, v124, v160
	v_sub_f32_e32 v154, v3, v160
	v_sub_f32_e32 v157, v131, v160
	v_sub_f32_e32 v156, v129, v160
	v_pk_mul_f32 v[168:169], v[162:163], v[156:157] op_sel_hi:[0,1]
	v_pk_mul_f32 v[186:187], v[162:163], v[154:155] op_sel_hi:[0,1]
	ds_read_b128 v[154:157], v244 offset:128
	ds_read_b128 v[182:185], v244 offset:384
	v_and_b32_e32 v159, 0xffff0000, v158
	s_waitcnt lgkmcnt(0)
	v_pk_fma_f32 v[154:155], v[154:155], v[186:187], v[182:183]
	v_pk_fma_f32 v[156:157], v[156:157], v[168:169], v[184:185]
	v_pk_fma_f32 v[120:121], v[154:155], s[72:73], v[120:121] op_sel_hi:[1,0,1]
	v_pk_fma_f32 v[122:123], v[156:157], s[72:73], v[122:123] op_sel_hi:[1,0,1]
	v_mov_b64_e32 v[168:169], v[204:205]
	v_lshrrev_b32_e32 v245, 4, v219
	v_lshl_add_u32 v245, v245, 3, v243
	global_load_dwordx4 v[202:205], v245, s[70:71] offset:256
	v_cvt_pk_bf16_f32 v120, v120, v121
	v_cvt_pk_bf16_f32 v121, v122, v123
	global_store_dwordx2 v[152:153], v[120:121], off offset:256
	ds_read_b128 v[182:185], v244 offset:192
	ds_read_b128 v[186:189], v244 offset:448
	v_lshlrev_b32_e32 v154, 16, v120
	v_and_b32_e32 v156, 0xffff0000, v120
	v_lshlrev_b32_e32 v120, 16, v121
	v_and_b32_e32 v122, 0xffff0000, v121
	v_mul_f32_e32 v155, v154, v154
	v_mul_f32_e32 v157, v156, v156
	v_mul_f32_e32 v121, v120, v120
	v_mul_f32_e32 v123, v122, v122
	v_pk_add_f32 v[120:121], v[120:121], v[122:123]
	s_waitcnt lgkmcnt(0)
	v_lshlrev_b32_e32 v3, 16, v168
	v_and_b32_e32 v124, 0xffff0000, v168
	v_lshlrev_b32_e32 v129, 16, v169
	v_and_b32_e32 v131, 0xffff0000, v169
	v_sub_f32_e32 v169, v124, v160
	v_sub_f32_e32 v168, v3, v160
	v_sub_f32_e32 v161, v131, v160
	v_sub_f32_e32 v160, v129, v160
	v_pk_mul_f32 v[160:161], v[162:163], v[160:161] op_sel_hi:[0,1]
	v_pk_mul_f32 v[162:163], v[162:163], v[168:169] op_sel_hi:[0,1]
	s_waitcnt lgkmcnt(0)
	v_pk_fma_f32 v[162:163], v[182:183], v[162:163], v[186:187]
	v_mov_b32_e32 v129, v159
	v_pk_fma_f32 v[116:117], v[162:163], s[72:73], v[116:117] op_sel_hi:[1,0,1]
	v_lshlrev_b32_e32 v163, 16, v158
	v_lshlrev_b32_e32 v162, 16, v150
	v_mov_b32_e32 v131, v163
	v_pk_mul_f32 v[168:169], v[162:163], v[162:163]
	v_pk_mul_f32 v[182:183], v[130:131], v[130:131]
	v_and_b32_e32 v158, 0xffff0000, v151
	v_pk_fma_f32 v[160:161], v[184:185], v[160:161], v[188:189]
	v_pk_mul_f32 v[150:151], v[128:129], v[128:129]
	v_pk_mul_f32 v[184:185], v[158:159], v[158:159]
	v_pk_mov_b32 v[186:187], v[162:163], v[168:169] op_sel:[1,0]
	v_pk_mov_b32 v[182:183], v[158:159], v[182:183] op_sel:[1,0]
	v_pk_add_f32 v[130:131], v[162:163], v[130:131]
	v_pk_add_f32 v[128:129], v[158:159], v[128:129]
	v_pk_fma_f32 v[118:119], v[160:161], s[72:73], v[118:119] op_sel_hi:[1,0,1]
	v_pk_add_f32 v[182:183], v[186:187], v[182:183]
	v_mov_b32_e32 v186, v126
	v_mov_b32_e32 v187, v150
	v_pk_mov_b32 v[126:127], v[126:127], v[184:185] op_sel:[1,0]
	v_mov_b32_e32 v131, v169
	v_mov_b32_e32 v129, v185
	v_cvt_pk_bf16_f32 v116, v116, v117
	v_cvt_pk_bf16_f32 v117, v118, v119
	v_pk_add_f32 v[126:127], v[186:187], v[126:127]
	v_pk_add_f32 v[128:129], v[130:131], v[128:129]
	v_mov_b32_e32 v3, v125
	global_store_dwordx2 v[152:153], v[116:117], off offset:288
	v_lshlrev_b32_e32 v152, 16, v116
	v_and_b32_e32 v160, 0xffff0000, v116
	v_lshlrev_b32_e32 v116, 16, v117
	v_and_b32_e32 v118, 0xffff0000, v117
	v_pk_add_f32 v[126:127], v[182:183], v[126:127]
	v_pk_add_f32 v[124:125], v[128:129], v[2:3]
	v_mul_f32_e32 v153, v152, v152
	v_mul_f32_e32 v161, v160, v160
	v_mul_f32_e32 v117, v116, v116
	v_mul_f32_e32 v119, v118, v118
	v_pk_add_f32 v[124:125], v[126:127], v[124:125]
	v_pk_add_f32 v[126:127], v[154:155], v[156:157]
	v_pk_add_f32 v[122:123], v[152:153], v[160:161]
	v_pk_add_f32 v[120:121], v[126:127], v[120:121]
	v_pk_add_f32 v[116:117], v[116:117], v[118:119]
	v_pk_add_f32 v[120:121], v[124:125], v[120:121]
	v_pk_add_f32 v[116:117], v[122:123], v[116:117]
	s_nop 0
	v_pk_add_f32 v[116:117], v[120:121], v[116:117]
	ds_bpermute_b32 v118, v181, v116
	ds_bpermute_b32 v119, v181, v117
	s_waitcnt lgkmcnt(0)
	v_pk_add_f32 v[116:117], v[116:117], v[118:119]
	ds_bpermute_b32 v118, v180, v116
	ds_bpermute_b32 v119, v180, v117
	s_and_saveexec_b64 s[0:1], s[40:41]
	s_cbranch_execz .LBB0_2205
	v_lshl_add_u64 v[120:121], s[50:51], 0, v[148:149]
	v_lshl_add_u64 v[120:121], s[60:61], 2, v[120:121]
	s_waitcnt lgkmcnt(0)
	v_pk_add_f32 v[116:117], v[116:117], v[118:119]
	global_store_dwordx2 v[120:121], v[116:117], off
; __device__ __forceinline__ u32x2 pk4(f32x4 v) { u32x2 r; r.x = pk2(v.x, v.y); r.y = pk2(v.z, v.w); return r; }
; __device__ __forceinline__ void stats_main(const float* stm, int row, int fq, float& mu, float& rs) {
;     const f32x4* p = (const f32x4*)(stm + (size_t)row * 32 + fq * 8);
;     const f32x4 a = p[0], b = p[1];
;     float s1 = (a.x + a.z) + (b.x + b.z), s2 = (a.y + a.w) + (b.y + b.w);
;     s1 += __shfl_xor(s1, 16); s2 += __shfl_xor(s2, 16); s1 += __shfl_xor(s1, 32); s2 += __shfl_xor(s2, 32);
;     mu = s1 * (1.f / DM); rs = __builtin_amdgcn_rsqf(fmaxf(s2 * (1.f / DM) - mu * mu, 0.f) + LN_EPS);
; }
;     __device__ __forceinline__ void operator()(const f32x4 (&acc)[2][2][4][2], const pg8::Unit& u, int wr, int wc, int fr, int fq) const {
;     ...
;                 const int row = u.pm * 256 + ai * 128 + wr * 64 + m * 16 + fr;
;                 float mu = 0.f, rs = 1.f; if (ln) stats_main(stm_p, row, fq, mu, rs);
;                 float s1 = 0.f, s2 = 0.f;
; #pragma unroll
;                 for (int bj = 0; bj < 2; ++bj)
; #pragma unroll
;                     for (int n = 0; n < 2; ++n) {
;                         const int col = u.pn * 256 + bj * 128 + wc * 32 + n * 16 + fq * 4;
;                         const u32x2 raw = *(const u32x2*)(src + (size_t)row * DM + col);
;                         f32x4 x = (f32x4){bflo(raw.x), bfhi(raw.x), bflo(raw.y), bfhi(raw.y)};
;                         if (ln) x = (x - mu) * rs * *(const f32x4*)(g + col) + *(const f32x4*)(b + col);
;                         const u32x2 pz = pk4(x * ALPHA + acc[ai][bj][m][n]);
;                         *(u32x2*)(dst + (size_t)row * DM + col) = pz;
;                         const float z0 = bflo(pz.x), z1 = bfhi(pz.x), z2 = bflo(pz.y), z3 = bfhi(pz.y);
;                         s1 += (z0 + z1) + (z2 + z3); s2 += (z0 * z0 + z1 * z1) + (z2 * z2 + z3 * z3);
;                     }
;                 s1 += __shfl_xor(s1, 16); s2 += __shfl_xor(s2, 16); s1 += __shfl_xor(s1, 32); s2 += __shfl_xor(s2, 32);
;                 if (fq == 0) { float* p = stm_n + (size_t)row * 32 + (u.pn * 4 + wc) * 2; p[0] = s1; p[1] = s2; }
.LBB0_2205:
	s_or_b64 exec, exec, s[0:1]
	v_or_b32_e32 v126, 16, v146
	v_ashrrev_i32_e32 v127, 31, v126
	v_lshlrev_b64 v[116:117], 7, v[126:127]
	v_lshl_add_u64 v[122:123], v[134:135], 0, v[116:117]
	s_waitcnt lgkmcnt(0)
	s_waitcnt vmcnt(7)
	v_mov_b64_e32 v[118:119], v[206:207]
	v_mov_b64_e32 v[120:121], v[208:209]
	global_load_dwordx4 v[206:209], v[246:247], off offset:2064
	s_nop 0
	s_waitcnt vmcnt(7)
	v_mov_b64_e32 v[122:123], v[214:215]
	v_mov_b64_e32 v[124:125], v[216:217]
	global_load_dwordx4 v[214:217], v[246:247], off offset:2048
	s_waitcnt lgkmcnt(0)
	v_pk_add_f32 v[118:119], v[118:119], v[120:121]
	s_waitcnt lgkmcnt(0)
	v_pk_add_f32 v[122:123], v[122:123], v[124:125]
	s_nop 0
	v_pk_add_f32 v[118:119], v[122:123], v[118:119]
	ds_bpermute_b32 v120, v181, v118
	ds_bpermute_b32 v121, v181, v119
	s_waitcnt lgkmcnt(0)
	v_pk_add_f32 v[118:119], v[118:119], v[120:121]
	ds_bpermute_b32 v120, v180, v118
	ds_bpermute_b32 v121, v180, v119
	s_waitcnt lgkmcnt(0)
	v_pk_add_f32 v[118:119], v[118:119], v[120:121]
	s_nop 0
	v_pk_mul_f32 v[128:129], v[118:119], s[82:83] op_sel_hi:[1,0]
	v_lshlrev_b64 v[118:119], 11, v[126:127]
	v_lshl_add_u64 v[118:119], s[70:71], 0, v[118:119]
	v_lshl_add_u64 v[124:125], v[144:145], 1, v[118:119]
	v_add_u32_e32 v243, 0x18000, v242
	s_waitcnt vmcnt(7)
	v_permlane16_swap_b32_e32 v234, v236
	v_permlane16_swap_b32_e32 v235, v237
	s_nop 0
	v_permlane32_swap_b32_e32 v234, v236
	v_permlane32_swap_b32_e32 v235, v237
	v_mov_b64_e32 v[118:119], v[234:235]
	v_fma_f32 v3, -v128, v128, v129
	v_max_f32_e32 v3, 0, v3
	v_add_f32_e32 v3, 0x3727c5ac, v3
	v_rsq_f32_e32 v130, v3
	s_waitcnt lgkmcnt(0)
	v_lshlrev_b32_e32 v3, 16, v118
	v_and_b32_e32 v118, 0xffff0000, v118
	v_lshlrev_b32_e32 v120, 16, v119
	v_and_b32_e32 v121, 0xffff0000, v119
	v_sub_f32_e32 v119, v118, v128
	v_sub_f32_e32 v118, v3, v128
	v_sub_f32_e32 v121, v121, v128
	v_sub_f32_e32 v120, v120, v128
	v_pk_mul_f32 v[122:123], v[120:121], v[130:131] op_sel_hi:[1,0]
	v_pk_mul_f32 v[126:127], v[118:119], v[130:131] op_sel_hi:[1,0]
	ds_read_b128 v[118:121], v244
	ds_read_b128 v[148:151], v244 offset:256
	s_waitcnt lgkmcnt(0)
	v_pk_fma_f32 v[120:121], v[120:121], v[122:123], v[150:151]
	s_nop 0
	v_pk_fma_f32 v[114:115], v[120:121], s[72:73], v[114:115] op_sel_hi:[1,0,1]
	v_mov_b64_e32 v[120:121], v[236:237]
	v_lshrrev_b32_e32 v245, 4, v219
	v_lshl_add_u32 v245, v245, 3, v243
	global_load_dwordx4 v[234:237], v245, s[70:71]
	v_pk_fma_f32 v[118:119], v[118:119], v[126:127], v[148:149]
	s_waitcnt lgkmcnt(0)
	v_lshlrev_b32_e32 v3, 16, v120
	v_pk_fma_f32 v[112:113], v[118:119], s[72:73], v[112:113] op_sel_hi:[1,0,1]
	v_cvt_pk_bf16_f32 v119, v114, v115
	v_cvt_pk_bf16_f32 v118, v112, v113
	v_and_b32_e32 v113, 0xffff0000, v120
	v_lshlrev_b32_e32 v115, 16, v121
	v_and_b32_e32 v122, 0xffff0000, v121
	global_store_dwordx2 v[124:125], v[118:119], off
	v_sub_f32_e32 v121, v113, v128
	v_sub_f32_e32 v120, v3, v128
	v_sub_f32_e32 v123, v122, v128
	v_sub_f32_e32 v122, v115, v128
	v_pk_mul_f32 v[126:127], v[130:131], v[122:123] op_sel_hi:[0,1]
	v_pk_mul_f32 v[152:153], v[130:131], v[120:121] op_sel_hi:[0,1]
	ds_read_b128 v[120:123], v244 offset:64
	ds_read_b128 v[148:151], v244 offset:320
	v_and_b32_e32 v114, 0xffff0000, v118
	v_lshlrev_b32_e32 v112, 16, v119
	s_waitcnt lgkmcnt(0)
	v_pk_fma_f32 v[120:121], v[120:121], v[152:153], v[148:149]
	s_nop 0
	v_pk_fma_f32 v[108:109], v[120:121], s[72:73], v[108:109] op_sel_hi:[1,0,1]
	s_waitcnt vmcnt(7)
	v_permlane16_swap_b32_e32 v238, v240
	v_permlane16_swap_b32_e32 v239, v241
	s_nop 0
	v_permlane32_swap_b32_e32 v238, v240
	v_permlane32_swap_b32_e32 v239, v241
	v_mov_b64_e32 v[120:121], v[238:239]
	v_pk_fma_f32 v[122:123], v[122:123], v[126:127], v[150:151]
	v_cvt_pk_bf16_f32 v126, v108, v109
	v_pk_fma_f32 v[110:111], v[122:123], s[72:73], v[110:111] op_sel_hi:[1,0,1]
	s_waitcnt lgkmcnt(0)
	v_lshlrev_b32_e32 v3, 16, v120
	v_cvt_pk_bf16_f32 v127, v110, v111
	v_lshlrev_b32_e32 v110, 16, v127
	v_and_b32_e32 v111, 0xffff0000, v127
	v_mul_f32_e32 v108, v110, v110
	v_pk_fma_f32 v[108:109], v[110:111], v[110:111], v[108:109] op_sel_hi:[1,1,0]
	v_lshlrev_b32_e32 v113, 16, v121
	v_and_b32_e32 v108, 0xffff0000, v120
	v_and_b32_e32 v115, 0xffff0000, v121
	global_store_dwordx2 v[124:125], v[126:127], off offset:32
	v_sub_f32_e32 v121, v108, v128
	v_sub_f32_e32 v120, v3, v128
	v_sub_f32_e32 v123, v115, v128
	v_sub_f32_e32 v122, v113, v128
	v_pk_mul_f32 v[152:153], v[130:131], v[122:123] op_sel_hi:[0,1]
	v_pk_mul_f32 v[154:155], v[130:131], v[120:121] op_sel_hi:[0,1]
	ds_read_b128 v[120:123], v244 offset:128
	ds_read_b128 v[148:151], v244 offset:384
	v_and_b32_e32 v127, 0xffff0000, v126
	s_waitcnt lgkmcnt(0)
	v_pk_fma_f32 v[120:121], v[120:121], v[154:155], v[148:149]
	v_mov_b64_e32 v[148:149], v[240:241]
	v_lshrrev_b32_e32 v245, 4, v219
	v_lshl_add_u32 v245, v245, 3, v243
	global_load_dwordx4 v[238:241], v245, s[70:71] offset:256
	v_pk_fma_f32 v[122:123], v[122:123], v[152:153], v[150:151]
	v_pk_fma_f32 v[104:105], v[120:121], s[72:73], v[104:105] op_sel_hi:[1,0,1]
	v_pk_fma_f32 v[106:107], v[122:123], s[72:73], v[106:107] op_sel_hi:[1,0,1]
	v_cvt_pk_bf16_f32 v104, v104, v105
	v_cvt_pk_bf16_f32 v105, v106, v107
	global_store_dwordx2 v[124:125], v[104:105], off offset:256
	v_lshlrev_b32_e32 v120, 16, v104
	v_and_b32_e32 v122, 0xffff0000, v104
	v_lshlrev_b32_e32 v104, 16, v105
	v_and_b32_e32 v106, 0xffff0000, v105
	v_mul_f32_e32 v121, v120, v120
	v_mul_f32_e32 v123, v122, v122
	v_mul_f32_e32 v105, v104, v104
	v_mul_f32_e32 v107, v106, v106
	v_pk_add_f32 v[104:105], v[104:105], v[106:107]
	s_waitcnt lgkmcnt(0)
; __device__ __forceinline__ void stats_main(const float* stm, int row, int fq, float& mu, float& rs) {
;     const f32x4* p = (const f32x4*)(stm + (size_t)row * 32 + fq * 8);
;     const f32x4 a = p[0], b = p[1];
;     float s1 = (a.x + a.z) + (b.x + b.z), s2 = (a.y + a.w) + (b.y + b.w);
;     s1 += __shfl_xor(s1, 16); s2 += __shfl_xor(s2, 16); s1 += __shfl_xor(s1, 32); s2 += __shfl_xor(s2, 32);
;     mu = s1 * (1.f / DM); rs = __builtin_amdgcn_rsqf(fmaxf(s2 * (1.f / DM) - mu * mu, 0.f) + LN_EPS);
; }
;     __device__ __forceinline__ void operator()(const f32x4 (&acc)[2][2][4][2], const pg8::Unit& u, int wr, int wc, int fr, int fq) const {
;     ...
;                 for (int bj = 0; bj < 2; ++bj)
; #pragma unroll
;                     for (int n = 0; n < 2; ++n) {
;                         const int col = u.pn * 256 + bj * 128 + wc * 32 + n * 16 + fq * 4;
;                         const u32x2 raw = *(const u32x2*)(src + (size_t)row * DM + col);
;     ...
;                         const float z0 = bflo(pz.x), z1 = bfhi(pz.x), z2 = bflo(pz.y), z3 = bfhi(pz.y);
;                         s1 += (z0 + z1) + (z2 + z3); s2 += (z0 * z0 + z1 * z1) + (z2 * z2 + z3 * z3);
;                     }
;                 s1 += __shfl_xor(s1, 16); s2 += __shfl_xor(s2, 16); s1 += __shfl_xor(s1, 32); s2 += __shfl_xor(s2, 32);
;                 if (fq == 0) { float* p = stm_n + (size_t)row * 32 + (u.pn * 4 + wc) * 2; p[0] = s1; p[1] = s2; }
	v_lshlrev_b32_e32 v3, 16, v148
	v_and_b32_e32 v108, 0xffff0000, v148
	v_lshlrev_b32_e32 v113, 16, v149
	v_and_b32_e32 v115, 0xffff0000, v149
	v_sub_f32_e32 v149, v108, v128
	v_sub_f32_e32 v148, v3, v128
	v_sub_f32_e32 v129, v115, v128
	v_sub_f32_e32 v128, v113, v128
	v_pk_mul_f32 v[128:129], v[130:131], v[128:129] op_sel_hi:[0,1]
	v_pk_mul_f32 v[130:131], v[130:131], v[148:149] op_sel_hi:[0,1]
	ds_read_b128 v[148:151], v244 offset:192
	ds_read_b128 v[152:155], v244 offset:448
	v_mov_b32_e32 v113, v127
	v_mov_b32_e32 v3, v109
	s_waitcnt lgkmcnt(0)
	v_pk_fma_f32 v[130:131], v[148:149], v[130:131], v[152:153]
	s_nop 0
	v_pk_fma_f32 v[100:101], v[130:131], s[72:73], v[100:101] op_sel_hi:[1,0,1]
	v_lshlrev_b32_e32 v131, 16, v126
	v_lshlrev_b32_e32 v130, 16, v118
	v_mov_b32_e32 v115, v131
	v_pk_fma_f32 v[128:129], v[150:151], v[128:129], v[154:155]
	v_pk_mul_f32 v[148:149], v[130:131], v[130:131]
	v_pk_mul_f32 v[150:151], v[114:115], v[114:115]
	v_and_b32_e32 v126, 0xffff0000, v119
	v_pk_mul_f32 v[118:119], v[112:113], v[112:113]
	v_pk_mul_f32 v[152:153], v[126:127], v[126:127]
	v_pk_mov_b32 v[154:155], v[130:131], v[148:149] op_sel:[1,0]
	v_pk_mov_b32 v[150:151], v[126:127], v[150:151] op_sel:[1,0]
	v_pk_add_f32 v[114:115], v[130:131], v[114:115]
	v_pk_add_f32 v[112:113], v[126:127], v[112:113]
	v_pk_fma_f32 v[102:103], v[128:129], s[72:73], v[102:103] op_sel_hi:[1,0,1]
	v_pk_add_f32 v[150:151], v[154:155], v[150:151]
	v_mov_b32_e32 v154, v110
	v_mov_b32_e32 v155, v118
	v_pk_mov_b32 v[110:111], v[110:111], v[152:153] op_sel:[1,0]
	v_mov_b32_e32 v115, v149
	v_mov_b32_e32 v113, v153
	v_cvt_pk_bf16_f32 v100, v100, v101
	v_cvt_pk_bf16_f32 v101, v102, v103
	v_pk_add_f32 v[110:111], v[154:155], v[110:111]
	v_pk_add_f32 v[112:113], v[114:115], v[112:113]
	global_store_dwordx2 v[124:125], v[100:101], off offset:288
	v_lshlrev_b32_e32 v124, 16, v100
	v_and_b32_e32 v128, 0xffff0000, v100
	v_lshlrev_b32_e32 v100, 16, v101
	v_and_b32_e32 v102, 0xffff0000, v101
	v_pk_add_f32 v[110:111], v[150:151], v[110:111]
	v_pk_add_f32 v[108:109], v[112:113], v[2:3]
	v_mul_f32_e32 v125, v124, v124
	v_mul_f32_e32 v129, v128, v128
	v_mul_f32_e32 v101, v100, v100
	v_mul_f32_e32 v103, v102, v102
	v_pk_add_f32 v[108:109], v[110:111], v[108:109]
	v_pk_add_f32 v[110:111], v[120:121], v[122:123]
	v_pk_add_f32 v[106:107], v[124:125], v[128:129]
	v_pk_add_f32 v[104:105], v[110:111], v[104:105]
	v_pk_add_f32 v[100:101], v[100:101], v[102:103]
	v_pk_add_f32 v[104:105], v[108:109], v[104:105]
	v_pk_add_f32 v[100:101], v[106:107], v[100:101]
	s_nop 0
	v_pk_add_f32 v[100:101], v[104:105], v[100:101]
	ds_bpermute_b32 v102, v181, v100
	ds_bpermute_b32 v103, v181, v101
	s_waitcnt lgkmcnt(0)
	v_pk_add_f32 v[100:101], v[100:101], v[102:103]
	ds_bpermute_b32 v102, v180, v100
	ds_bpermute_b32 v103, v180, v101
	s_and_saveexec_b64 s[0:1], s[40:41]
	s_cbranch_execz .LBB0_2207
	v_lshl_add_u64 v[104:105], s[50:51], 0, v[116:117]
	v_lshl_add_u64 v[104:105], s[60:61], 2, v[104:105]
	s_waitcnt lgkmcnt(0)
	v_pk_add_f32 v[100:101], v[100:101], v[102:103]
	global_store_dwordx2 v[104:105], v[100:101], off
.LBB0_2207:
	s_or_b64 exec, exec, s[0:1]
	v_or_b32_e32 v110, 32, v146
	v_ashrrev_i32_e32 v111, 31, v110
	v_lshlrev_b64 v[100:101], 7, v[110:111]
	v_lshl_add_u64 v[106:107], v[134:135], 0, v[100:101]
	s_waitcnt lgkmcnt(0)
	s_waitcnt vmcnt(7)
	v_mov_b64_e32 v[102:103], v[190:191]
	v_mov_b64_e32 v[104:105], v[192:193]
	global_load_dwordx4 v[190:193], v[248:249], off offset:-4080
	s_nop 0
	s_waitcnt vmcnt(7)
	v_mov_b64_e32 v[106:107], v[194:195]
	v_mov_b64_e32 v[108:109], v[196:197]
	global_load_dwordx4 v[194:197], v[248:249], off offset:-4096
	s_waitcnt lgkmcnt(0)
	v_pk_add_f32 v[102:103], v[102:103], v[104:105]
	s_waitcnt lgkmcnt(0)
	v_pk_add_f32 v[106:107], v[106:107], v[108:109]
	s_nop 0
	v_pk_add_f32 v[102:103], v[106:107], v[102:103]
	ds_bpermute_b32 v104, v181, v102
	ds_bpermute_b32 v105, v181, v103
	s_waitcnt lgkmcnt(0)
	v_pk_add_f32 v[102:103], v[102:103], v[104:105]
	ds_bpermute_b32 v104, v180, v102
	ds_bpermute_b32 v105, v180, v103
	s_waitcnt lgkmcnt(0)
	v_pk_add_f32 v[102:103], v[102:103], v[104:105]
	s_nop 0
	v_pk_mul_f32 v[112:113], v[102:103], s[82:83] op_sel_hi:[1,0]
	v_lshlrev_b64 v[102:103], 11, v[110:111]
	v_lshl_add_u64 v[102:103], s[70:71], 0, v[102:103]
	v_lshl_add_u64 v[108:109], v[144:145], 1, v[102:103]
	v_add_u32_e32 v243, 0x40000, v242
	s_waitcnt vmcnt(7)
	v_permlane16_swap_b32_e32 v198, v200
	v_permlane16_swap_b32_e32 v199, v201
	s_nop 0
	v_permlane32_swap_b32_e32 v198, v200
	v_permlane32_swap_b32_e32 v199, v201
	v_mov_b64_e32 v[102:103], v[198:199]
	v_fma_f32 v3, -v112, v112, v113
	v_max_f32_e32 v3, 0, v3
	v_add_f32_e32 v3, 0x3727c5ac, v3
	v_rsq_f32_e32 v114, v3
	s_waitcnt lgkmcnt(0)
	v_lshlrev_b32_e32 v3, 16, v102
	v_and_b32_e32 v102, 0xffff0000, v102
	v_lshlrev_b32_e32 v104, 16, v103
	v_and_b32_e32 v105, 0xffff0000, v103
	v_sub_f32_e32 v103, v102, v112
	v_sub_f32_e32 v102, v3, v112
	v_sub_f32_e32 v105, v105, v112
	v_sub_f32_e32 v104, v104, v112
	v_pk_mul_f32 v[106:107], v[104:105], v[114:115] op_sel_hi:[1,0]
	v_pk_mul_f32 v[110:111], v[102:103], v[114:115] op_sel_hi:[1,0]
	ds_read_b128 v[102:105], v244
	ds_read_b128 v[116:119], v244 offset:256
	s_waitcnt lgkmcnt(0)
	v_pk_fma_f32 v[104:105], v[104:105], v[106:107], v[118:119]
	s_nop 0
	v_pk_fma_f32 v[98:99], v[104:105], s[72:73], v[98:99] op_sel_hi:[1,0,1]
	v_mov_b64_e32 v[104:105], v[200:201]
	v_lshrrev_b32_e32 v245, 4, v219
	v_lshl_add_u32 v245, v245, 3, v243
	global_load_dwordx4 v[198:201], v245, s[70:71]
	v_pk_fma_f32 v[102:103], v[102:103], v[110:111], v[116:117]
	s_waitcnt lgkmcnt(0)
; __device__ __forceinline__ u32x2 pk4(f32x4 v) { u32x2 r; r.x = pk2(v.x, v.y); r.y = pk2(v.z, v.w); return r; }
;     __device__ __forceinline__ void operator()(const f32x4 (&acc)[2][2][4][2], const pg8::Unit& u, int wr, int wc, int fr, int fq) const {
;     ...
;                 for (int bj = 0; bj < 2; ++bj)
; #pragma unroll
;                     for (int n = 0; n < 2; ++n) {
;                         const int col = u.pn * 256 + bj * 128 + wc * 32 + n * 16 + fq * 4;
;                         const u32x2 raw = *(const u32x2*)(src + (size_t)row * DM + col);
;                         f32x4 x = (f32x4){bflo(raw.x), bfhi(raw.x), bflo(raw.y), bfhi(raw.y)};
;                         if (ln) x = (x - mu) * rs * *(const f32x4*)(g + col) + *(const f32x4*)(b + col);
;                         const u32x2 pz = pk4(x * ALPHA + acc[ai][bj][m][n]);
;                         *(u32x2*)(dst + (size_t)row * DM + col) = pz;
;                         const float z0 = bflo(pz.x), z1 = bfhi(pz.x), z2 = bflo(pz.y), z3 = bfhi(pz.y);
;                         s1 += (z0 + z1) + (z2 + z3); s2 += (z0 * z0 + z1 * z1) + (z2 * z2 + z3 * z3);
;                     }
;                 s1 += __shfl_xor(s1, 16); s2 += __shfl_xor(s2, 16); s1 += __shfl_xor(s1, 32); s2 += __shfl_xor(s2, 32);
;                 if (fq == 0) { float* p = stm_n + (size_t)row * 32 + (u.pn * 4 + wc) * 2; p[0] = s1; p[1] = s2; }
	v_lshlrev_b32_e32 v3, 16, v104
	v_pk_fma_f32 v[96:97], v[102:103], s[72:73], v[96:97] op_sel_hi:[1,0,1]
	v_cvt_pk_bf16_f32 v103, v98, v99
	v_cvt_pk_bf16_f32 v102, v96, v97
	v_and_b32_e32 v97, 0xffff0000, v104
	v_lshlrev_b32_e32 v99, 16, v105
	v_and_b32_e32 v106, 0xffff0000, v105
	v_mov_b64_e32 v[148:149], v[102:103]
	v_sub_f32_e32 v105, v97, v112
	v_sub_f32_e32 v104, v3, v112
	v_sub_f32_e32 v107, v106, v112
	v_sub_f32_e32 v106, v99, v112
	v_pk_mul_f32 v[110:111], v[114:115], v[106:107] op_sel_hi:[0,1]
	v_pk_mul_f32 v[120:121], v[114:115], v[104:105] op_sel_hi:[0,1]
	ds_read_b128 v[104:107], v244 offset:64
	ds_read_b128 v[116:119], v244 offset:320
	v_and_b32_e32 v98, 0xffff0000, v102
	v_lshlrev_b32_e32 v96, 16, v103
	s_waitcnt lgkmcnt(0)
	v_pk_fma_f32 v[104:105], v[104:105], v[120:121], v[116:117]
	s_nop 0
	v_pk_fma_f32 v[92:93], v[104:105], s[72:73], v[92:93] op_sel_hi:[1,0,1]
	s_waitcnt vmcnt(7)
	v_permlane16_swap_b32_e32 v202, v204
	v_permlane16_swap_b32_e32 v203, v205
	s_nop 0
	v_permlane32_swap_b32_e32 v202, v204
	v_permlane32_swap_b32_e32 v203, v205
	v_mov_b64_e32 v[104:105], v[202:203]
	v_pk_fma_f32 v[106:107], v[106:107], v[110:111], v[118:119]
	v_cvt_pk_bf16_f32 v110, v92, v93
	v_pk_fma_f32 v[94:95], v[106:107], s[72:73], v[94:95] op_sel_hi:[1,0,1]
	s_waitcnt lgkmcnt(0)
	v_lshlrev_b32_e32 v3, 16, v104
	v_cvt_pk_bf16_f32 v111, v94, v95
	v_lshlrev_b32_e32 v94, 16, v111
	v_and_b32_e32 v95, 0xffff0000, v111
	v_mul_f32_e32 v92, v94, v94
	v_pk_fma_f32 v[92:93], v[94:95], v[94:95], v[92:93] op_sel_hi:[1,1,0]
	v_lshlrev_b32_e32 v97, 16, v105
	v_and_b32_e32 v92, 0xffff0000, v104
	v_and_b32_e32 v99, 0xffff0000, v105
	v_mov_b64_e32 v[150:151], v[110:111]
	v_lshrrev_b32_e32 v122, 4, v219
	v_lshlrev_b32_e32 v122, 3, v122
	v_mov_b32_e32 v123, v2
	v_permlane32_swap_b32_e32 v148, v150
	v_permlane32_swap_b32_e32 v149, v151
	v_lshl_add_u64 v[122:123], v[122:123], 0, v[108:109]
	s_nop 0
	v_permlane16_swap_b32_e32 v148, v150
	v_permlane16_swap_b32_e32 v149, v151
	global_store_dwordx4 v[122:123], v[148:151], off sc0
	v_sub_f32_e32 v105, v92, v112
	v_sub_f32_e32 v104, v3, v112
	v_sub_f32_e32 v107, v99, v112
	v_sub_f32_e32 v106, v97, v112
	v_pk_mul_f32 v[120:121], v[114:115], v[106:107] op_sel_hi:[0,1]
	v_pk_mul_f32 v[122:123], v[114:115], v[104:105] op_sel_hi:[0,1]
	ds_read_b128 v[104:107], v244 offset:128
	ds_read_b128 v[116:119], v244 offset:384
	v_and_b32_e32 v111, 0xffff0000, v110
	s_waitcnt lgkmcnt(0)
	v_pk_fma_f32 v[104:105], v[104:105], v[122:123], v[116:117]
	v_mov_b64_e32 v[116:117], v[204:205]
	v_lshrrev_b32_e32 v245, 4, v219
	v_lshl_add_u32 v245, v245, 3, v243
	global_load_dwordx4 v[202:205], v245, s[70:71] offset:256
	v_pk_fma_f32 v[106:107], v[106:107], v[120:121], v[118:119]
	v_pk_fma_f32 v[88:89], v[104:105], s[72:73], v[88:89] op_sel_hi:[1,0,1]
	v_pk_fma_f32 v[90:91], v[106:107], s[72:73], v[90:91] op_sel_hi:[1,0,1]
	v_cvt_pk_bf16_f32 v88, v88, v89
	v_cvt_pk_bf16_f32 v89, v90, v91
	v_mov_b64_e32 v[148:149], v[88:89]
	v_lshlrev_b32_e32 v104, 16, v88
	v_and_b32_e32 v106, 0xffff0000, v88
	v_lshlrev_b32_e32 v88, 16, v89
	v_and_b32_e32 v90, 0xffff0000, v89
	v_mul_f32_e32 v105, v104, v104
	v_mul_f32_e32 v107, v106, v106
	v_mul_f32_e32 v89, v88, v88
	v_mul_f32_e32 v91, v90, v90
	v_pk_add_f32 v[88:89], v[88:89], v[90:91]
	s_waitcnt lgkmcnt(0)
	v_lshlrev_b32_e32 v3, 16, v116
	v_and_b32_e32 v92, 0xffff0000, v116
	v_lshlrev_b32_e32 v97, 16, v117
	v_and_b32_e32 v99, 0xffff0000, v117
	v_sub_f32_e32 v117, v92, v112
	v_sub_f32_e32 v116, v3, v112
	v_sub_f32_e32 v113, v99, v112
	v_sub_f32_e32 v112, v97, v112
	v_pk_mul_f32 v[112:113], v[114:115], v[112:113] op_sel_hi:[0,1]
	v_pk_mul_f32 v[114:115], v[114:115], v[116:117] op_sel_hi:[0,1]
	ds_read_b128 v[116:119], v244 offset:192
	ds_read_b128 v[120:123], v244 offset:448
	v_mov_b32_e32 v97, v111
	v_mov_b32_e32 v3, v93
	s_waitcnt lgkmcnt(0)
	v_pk_fma_f32 v[114:115], v[116:117], v[114:115], v[120:121]
	s_nop 0
	v_pk_fma_f32 v[84:85], v[114:115], s[72:73], v[84:85] op_sel_hi:[1,0,1]
	v_lshlrev_b32_e32 v115, 16, v110
	v_lshlrev_b32_e32 v114, 16, v102
	v_mov_b32_e32 v99, v115
	v_pk_fma_f32 v[112:113], v[118:119], v[112:113], v[122:123]
	v_pk_mul_f32 v[116:117], v[114:115], v[114:115]
	v_pk_mul_f32 v[118:119], v[98:99], v[98:99]
	v_and_b32_e32 v110, 0xffff0000, v103
	v_pk_mul_f32 v[102:103], v[96:97], v[96:97]
	v_pk_mul_f32 v[120:121], v[110:111], v[110:111]
	v_pk_mov_b32 v[122:123], v[114:115], v[116:117] op_sel:[1,0]
	v_pk_mov_b32 v[118:119], v[110:111], v[118:119] op_sel:[1,0]
	v_pk_add_f32 v[98:99], v[114:115], v[98:99]
	v_pk_add_f32 v[96:97], v[110:111], v[96:97]
	v_pk_fma_f32 v[86:87], v[112:113], s[72:73], v[86:87] op_sel_hi:[1,0,1]
	v_pk_add_f32 v[118:119], v[122:123], v[118:119]
	v_mov_b32_e32 v122, v94
	v_mov_b32_e32 v123, v102
	v_pk_mov_b32 v[94:95], v[94:95], v[120:121] op_sel:[1,0]
	v_mov_b32_e32 v99, v117
	v_mov_b32_e32 v97, v121
	v_cvt_pk_bf16_f32 v84, v84, v85
	v_cvt_pk_bf16_f32 v85, v86, v87
	v_pk_add_f32 v[94:95], v[122:123], v[94:95]
	v_pk_add_f32 v[96:97], v[98:99], v[96:97]
	v_mov_b64_e32 v[150:151], v[84:85]
	v_lshrrev_b32_e32 v152, 4, v219
	v_lshlrev_b32_e32 v152, 3, v152
	v_mov_b32_e32 v153, v2
	v_permlane32_swap_b32_e32 v148, v150
	v_permlane32_swap_b32_e32 v149, v151
	v_lshl_add_u64 v[152:153], v[152:153], 0, v[108:109]
	s_nop 0
	v_permlane16_swap_b32_e32 v148, v150
	v_permlane16_swap_b32_e32 v149, v151
	global_store_dwordx4 v[152:153], v[148:151], off offset:256 sc0
	v_lshlrev_b32_e32 v108, 16, v84
	v_and_b32_e32 v112, 0xffff0000, v84
	v_lshlrev_b32_e32 v84, 16, v85
	v_and_b32_e32 v86, 0xffff0000, v85
	v_pk_add_f32 v[94:95], v[118:119], v[94:95]
	v_pk_add_f32 v[92:93], v[96:97], v[2:3]
	v_mul_f32_e32 v109, v108, v108
	v_mul_f32_e32 v113, v112, v112
	v_mul_f32_e32 v85, v84, v84
	v_mul_f32_e32 v87, v86, v86
	v_pk_add_f32 v[92:93], v[94:95], v[92:93]
	v_pk_add_f32 v[94:95], v[104:105], v[106:107]
	v_pk_add_f32 v[90:91], v[108:109], v[112:113]
	v_pk_add_f32 v[88:89], v[94:95], v[88:89]
	v_pk_add_f32 v[84:85], v[84:85], v[86:87]
	v_pk_add_f32 v[88:89], v[92:93], v[88:89]
	v_pk_add_f32 v[84:85], v[90:91], v[84:85]
	s_nop 0
	v_pk_add_f32 v[84:85], v[88:89], v[84:85]
	ds_bpermute_b32 v86, v181, v84
	ds_bpermute_b32 v87, v181, v85
	s_waitcnt lgkmcnt(0)
	v_pk_add_f32 v[84:85], v[84:85], v[86:87]
	ds_bpermute_b32 v86, v180, v84
	ds_bpermute_b32 v87, v180, v85
	s_and_saveexec_b64 s[0:1], s[40:41]
	v_readlane_b32 s24, v251, 0
	v_readlane_b32 s25, v251, 1
	v_readlane_b32 s26, v251, 2
	v_readlane_b32 s27, v251, 3
	s_mov_b32 s76, 0x30000
	s_cbranch_execz .LBB0_2209
	v_lshl_add_u64 v[88:89], s[50:51], 0, v[100:101]
	v_lshl_add_u64 v[88:89], s[60:61], 2, v[88:89]
	s_waitcnt lgkmcnt(0)
	v_pk_add_f32 v[84:85], v[84:85], v[86:87]
	global_store_dwordx2 v[88:89], v[84:85], off
; __device__ __forceinline__ u32x2 pk4(f32x4 v) { u32x2 r; r.x = pk2(v.x, v.y); r.y = pk2(v.z, v.w); return r; }
; __device__ __forceinline__ void stats_main(const float* stm, int row, int fq, float& mu, float& rs) {
;     const f32x4* p = (const f32x4*)(stm + (size_t)row * 32 + fq * 8);
;     const f32x4 a = p[0], b = p[1];
;     float s1 = (a.x + a.z) + (b.x + b.z), s2 = (a.y + a.w) + (b.y + b.w);
;     s1 += __shfl_xor(s1, 16); s2 += __shfl_xor(s2, 16); s1 += __shfl_xor(s1, 32); s2 += __shfl_xor(s2, 32);
;     mu = s1 * (1.f / DM); rs = __builtin_amdgcn_rsqf(fmaxf(s2 * (1.f / DM) - mu * mu, 0.f) + LN_EPS);
; }
;     __device__ __forceinline__ void operator()(const f32x4 (&acc)[2][2][4][2], const pg8::Unit& u, int wr, int wc, int fr, int fq) const {
;     ...
;                 const int row = u.pm * 256 + ai * 128 + wr * 64 + m * 16 + fr;
;                 float mu = 0.f, rs = 1.f; if (ln) stats_main(stm_p, row, fq, mu, rs);
;                 float s1 = 0.f, s2 = 0.f;
; #pragma unroll
;                 for (int bj = 0; bj < 2; ++bj)
; #pragma unroll
;                     for (int n = 0; n < 2; ++n) {
;                         const int col = u.pn * 256 + bj * 128 + wc * 32 + n * 16 + fq * 4;
;                         const u32x2 raw = *(const u32x2*)(src + (size_t)row * DM + col);
;                         f32x4 x = (f32x4){bflo(raw.x), bfhi(raw.x), bflo(raw.y), bfhi(raw.y)};
;                         if (ln) x = (x - mu) * rs * *(const f32x4*)(g + col) + *(const f32x4*)(b + col);
;                         const u32x2 pz = pk4(x * ALPHA + acc[ai][bj][m][n]);
;                         *(u32x2*)(dst + (size_t)row * DM + col) = pz;
;                         const float z0 = bflo(pz.x), z1 = bfhi(pz.x), z2 = bflo(pz.y), z3 = bfhi(pz.y);
;                         s1 += (z0 + z1) + (z2 + z3); s2 += (z0 * z0 + z1 * z1) + (z2 * z2 + z3 * z3);
;                     }
;                 s1 += __shfl_xor(s1, 16); s2 += __shfl_xor(s2, 16); s1 += __shfl_xor(s1, 32); s2 += __shfl_xor(s2, 32);
;                 if (fq == 0) { float* p = stm_n + (size_t)row * 32 + (u.pn * 4 + wc) * 2; p[0] = s1; p[1] = s2; }
.LBB0_2209:
	s_or_b64 exec, exec, s[0:1]
	v_or_b32_e32 v94, 48, v146
	v_ashrrev_i32_e32 v95, 31, v94
	v_lshlrev_b64 v[84:85], 7, v[94:95]
	v_lshl_add_u64 v[90:91], v[134:135], 0, v[84:85]
	s_waitcnt lgkmcnt(0)
	s_waitcnt vmcnt(7)
	v_mov_b64_e32 v[86:87], v[206:207]
	v_mov_b64_e32 v[88:89], v[208:209]
	global_load_dwordx4 v[206:209], v[248:249], off offset:-2032
	s_nop 0
	s_waitcnt vmcnt(7)
	v_mov_b64_e32 v[90:91], v[214:215]
	v_mov_b64_e32 v[92:93], v[216:217]
	global_load_dwordx4 v[214:217], v[248:249], off offset:-2048
	s_waitcnt lgkmcnt(0)
	v_pk_add_f32 v[86:87], v[86:87], v[88:89]
	s_waitcnt lgkmcnt(0)
	v_pk_add_f32 v[90:91], v[90:91], v[92:93]
	s_nop 0
	v_pk_add_f32 v[86:87], v[90:91], v[86:87]
	ds_bpermute_b32 v88, v181, v86
	ds_bpermute_b32 v89, v181, v87
	s_waitcnt lgkmcnt(0)
	v_pk_add_f32 v[86:87], v[86:87], v[88:89]
	ds_bpermute_b32 v88, v180, v86
	ds_bpermute_b32 v89, v180, v87
	s_waitcnt lgkmcnt(0)
	v_pk_add_f32 v[86:87], v[86:87], v[88:89]
	s_nop 0
	v_pk_mul_f32 v[96:97], v[86:87], s[82:83] op_sel_hi:[1,0]
	v_lshlrev_b64 v[86:87], 11, v[94:95]
	v_lshl_add_u64 v[86:87], s[70:71], 0, v[86:87]
	v_lshl_add_u64 v[92:93], v[144:145], 1, v[86:87]
	v_add_u32_e32 v243, 0x48000, v242
	s_waitcnt vmcnt(7)
	v_permlane16_swap_b32_e32 v234, v236
	v_permlane16_swap_b32_e32 v235, v237
	s_nop 0
	v_permlane32_swap_b32_e32 v234, v236
	v_permlane32_swap_b32_e32 v235, v237
	v_mov_b64_e32 v[86:87], v[234:235]
	v_fma_f32 v3, -v96, v96, v97
	v_max_f32_e32 v3, 0, v3
	v_add_f32_e32 v3, 0x3727c5ac, v3
	v_rsq_f32_e32 v98, v3
	s_waitcnt lgkmcnt(0)
	v_lshlrev_b32_e32 v3, 16, v86
	v_and_b32_e32 v86, 0xffff0000, v86
	v_lshlrev_b32_e32 v88, 16, v87
	v_and_b32_e32 v89, 0xffff0000, v87
	v_sub_f32_e32 v87, v86, v96
	v_sub_f32_e32 v86, v3, v96
	v_sub_f32_e32 v89, v89, v96
	v_sub_f32_e32 v88, v88, v96
	v_pk_mul_f32 v[90:91], v[88:89], v[98:99] op_sel_hi:[1,0]
	v_pk_mul_f32 v[94:95], v[86:87], v[98:99] op_sel_hi:[1,0]
	ds_read_b128 v[86:89], v244
	ds_read_b128 v[100:103], v244 offset:256
	s_waitcnt lgkmcnt(0)
	v_pk_fma_f32 v[88:89], v[88:89], v[90:91], v[102:103]
	s_nop 0
	v_pk_fma_f32 v[82:83], v[88:89], s[72:73], v[82:83] op_sel_hi:[1,0,1]
	v_mov_b64_e32 v[88:89], v[236:237]
	v_lshrrev_b32_e32 v245, 4, v219
	v_lshl_add_u32 v245, v245, 3, v243
	global_load_dwordx4 v[234:237], v245, s[70:71]
	v_pk_fma_f32 v[86:87], v[86:87], v[94:95], v[100:101]
	s_waitcnt lgkmcnt(0)
	v_lshlrev_b32_e32 v3, 16, v88
	v_pk_fma_f32 v[80:81], v[86:87], s[72:73], v[80:81] op_sel_hi:[1,0,1]
	v_cvt_pk_bf16_f32 v87, v82, v83
	v_cvt_pk_bf16_f32 v86, v80, v81
	v_and_b32_e32 v81, 0xffff0000, v88
	v_lshlrev_b32_e32 v83, 16, v89
	v_and_b32_e32 v90, 0xffff0000, v89
	v_mov_b64_e32 v[148:149], v[86:87]
	v_sub_f32_e32 v89, v81, v96
	v_sub_f32_e32 v88, v3, v96
	v_sub_f32_e32 v91, v90, v96
	v_sub_f32_e32 v90, v83, v96
	v_pk_mul_f32 v[94:95], v[98:99], v[90:91] op_sel_hi:[0,1]
	v_pk_mul_f32 v[104:105], v[98:99], v[88:89] op_sel_hi:[0,1]
	ds_read_b128 v[88:91], v244 offset:64
	ds_read_b128 v[100:103], v244 offset:320
	v_and_b32_e32 v82, 0xffff0000, v86
	v_lshlrev_b32_e32 v80, 16, v87
	s_waitcnt lgkmcnt(0)
	v_pk_fma_f32 v[88:89], v[88:89], v[104:105], v[100:101]
	s_nop 0
	v_pk_fma_f32 v[76:77], v[88:89], s[72:73], v[76:77] op_sel_hi:[1,0,1]
	s_waitcnt vmcnt(7)
	v_permlane16_swap_b32_e32 v238, v240
	v_permlane16_swap_b32_e32 v239, v241
	s_nop 0
	v_permlane32_swap_b32_e32 v238, v240
	v_permlane32_swap_b32_e32 v239, v241
	v_mov_b64_e32 v[88:89], v[238:239]
	v_pk_fma_f32 v[90:91], v[90:91], v[94:95], v[102:103]
	v_cvt_pk_bf16_f32 v94, v76, v77
	v_pk_fma_f32 v[78:79], v[90:91], s[72:73], v[78:79] op_sel_hi:[1,0,1]
	s_waitcnt lgkmcnt(0)
	v_lshlrev_b32_e32 v3, 16, v88
	v_cvt_pk_bf16_f32 v95, v78, v79
	v_lshlrev_b32_e32 v78, 16, v95
	v_and_b32_e32 v79, 0xffff0000, v95
	v_mul_f32_e32 v76, v78, v78
	v_pk_fma_f32 v[76:77], v[78:79], v[78:79], v[76:77] op_sel_hi:[1,1,0]
	v_lshlrev_b32_e32 v81, 16, v89
	v_and_b32_e32 v76, 0xffff0000, v88
	v_and_b32_e32 v83, 0xffff0000, v89
	v_mov_b64_e32 v[150:151], v[94:95]
	v_lshrrev_b32_e32 v106, 4, v219
	v_lshlrev_b32_e32 v106, 3, v106
	v_mov_b32_e32 v107, v2
	v_permlane32_swap_b32_e32 v148, v150
	v_permlane32_swap_b32_e32 v149, v151
	v_lshl_add_u64 v[106:107], v[106:107], 0, v[92:93]
	s_nop 0
	v_permlane16_swap_b32_e32 v148, v150
	v_permlane16_swap_b32_e32 v149, v151
	global_store_dwordx4 v[106:107], v[148:151], off sc0
	v_sub_f32_e32 v89, v76, v96
	v_sub_f32_e32 v88, v3, v96
	v_sub_f32_e32 v91, v83, v96
	v_sub_f32_e32 v90, v81, v96
	v_pk_mul_f32 v[104:105], v[98:99], v[90:91] op_sel_hi:[0,1]
	v_pk_mul_f32 v[106:107], v[98:99], v[88:89] op_sel_hi:[0,1]
	ds_read_b128 v[88:91], v244 offset:128
	ds_read_b128 v[100:103], v244 offset:384
	v_and_b32_e32 v95, 0xffff0000, v94
	s_waitcnt lgkmcnt(0)
	v_pk_fma_f32 v[88:89], v[88:89], v[106:107], v[100:101]
	v_mov_b64_e32 v[100:101], v[240:241]
	v_lshrrev_b32_e32 v245, 4, v219
	v_lshl_add_u32 v245, v245, 3, v243
	global_load_dwordx4 v[238:241], v245, s[70:71] offset:256
	v_pk_fma_f32 v[90:91], v[90:91], v[104:105], v[102:103]
	v_pk_fma_f32 v[72:73], v[88:89], s[72:73], v[72:73] op_sel_hi:[1,0,1]
	v_pk_fma_f32 v[74:75], v[90:91], s[72:73], v[74:75] op_sel_hi:[1,0,1]
	v_cvt_pk_bf16_f32 v72, v72, v73
	v_cvt_pk_bf16_f32 v73, v74, v75
	v_mov_b64_e32 v[148:149], v[72:73]
	v_lshlrev_b32_e32 v88, 16, v72
	v_and_b32_e32 v90, 0xffff0000, v72
	v_lshlrev_b32_e32 v72, 16, v73
	v_and_b32_e32 v74, 0xffff0000, v73
	v_mul_f32_e32 v89, v88, v88
	v_mul_f32_e32 v91, v90, v90
	v_mul_f32_e32 v73, v72, v72
	v_mul_f32_e32 v75, v74, v74
	v_pk_add_f32 v[72:73], v[72:73], v[74:75]
	s_waitcnt lgkmcnt(0)
; __device__ __forceinline__ void stats_main(const float* stm, int row, int fq, float& mu, float& rs) {
;     const f32x4* p = (const f32x4*)(stm + (size_t)row * 32 + fq * 8);
;     const f32x4 a = p[0], b = p[1];
;     float s1 = (a.x + a.z) + (b.x + b.z), s2 = (a.y + a.w) + (b.y + b.w);
;     s1 += __shfl_xor(s1, 16); s2 += __shfl_xor(s2, 16); s1 += __shfl_xor(s1, 32); s2 += __shfl_xor(s2, 32);
;     mu = s1 * (1.f / DM); rs = __builtin_amdgcn_rsqf(fmaxf(s2 * (1.f / DM) - mu * mu, 0.f) + LN_EPS);
; }
;     __device__ __forceinline__ void operator()(const f32x4 (&acc)[2][2][4][2], const pg8::Unit& u, int wr, int wc, int fr, int fq) const {
;     ...
;                 for (int bj = 0; bj < 2; ++bj)
; #pragma unroll
;                     for (int n = 0; n < 2; ++n) {
;                         const int col = u.pn * 256 + bj * 128 + wc * 32 + n * 16 + fq * 4;
;                         const u32x2 raw = *(const u32x2*)(src + (size_t)row * DM + col);
;     ...
;                         const float z0 = bflo(pz.x), z1 = bfhi(pz.x), z2 = bflo(pz.y), z3 = bfhi(pz.y);
;                         s1 += (z0 + z1) + (z2 + z3); s2 += (z0 * z0 + z1 * z1) + (z2 * z2 + z3 * z3);
;                     }
;                 s1 += __shfl_xor(s1, 16); s2 += __shfl_xor(s2, 16); s1 += __shfl_xor(s1, 32); s2 += __shfl_xor(s2, 32);
;                 if (fq == 0) { float* p = stm_n + (size_t)row * 32 + (u.pn * 4 + wc) * 2; p[0] = s1; p[1] = s2; }
	v_lshlrev_b32_e32 v3, 16, v100
	v_and_b32_e32 v76, 0xffff0000, v100
	v_lshlrev_b32_e32 v81, 16, v101
	v_and_b32_e32 v83, 0xffff0000, v101
	v_sub_f32_e32 v101, v76, v96
	v_sub_f32_e32 v100, v3, v96
	v_sub_f32_e32 v97, v83, v96
	v_sub_f32_e32 v96, v81, v96
	v_pk_mul_f32 v[96:97], v[98:99], v[96:97] op_sel_hi:[0,1]
	v_pk_mul_f32 v[98:99], v[98:99], v[100:101] op_sel_hi:[0,1]
	ds_read_b128 v[100:103], v244 offset:192
	ds_read_b128 v[104:107], v244 offset:448
	v_mov_b32_e32 v81, v95
	v_mov_b32_e32 v3, v77
	s_waitcnt lgkmcnt(0)
	v_pk_fma_f32 v[98:99], v[100:101], v[98:99], v[104:105]
	s_nop 0
	v_pk_fma_f32 v[68:69], v[98:99], s[72:73], v[68:69] op_sel_hi:[1,0,1]
	v_lshlrev_b32_e32 v99, 16, v94
	v_lshlrev_b32_e32 v98, 16, v86
	v_mov_b32_e32 v83, v99
	v_pk_fma_f32 v[96:97], v[102:103], v[96:97], v[106:107]
	v_pk_mul_f32 v[100:101], v[98:99], v[98:99]
	v_pk_mul_f32 v[102:103], v[82:83], v[82:83]
	v_and_b32_e32 v94, 0xffff0000, v87
	v_pk_mul_f32 v[86:87], v[80:81], v[80:81]
	v_pk_mul_f32 v[104:105], v[94:95], v[94:95]
	v_pk_mov_b32 v[106:107], v[98:99], v[100:101] op_sel:[1,0]
	v_pk_mov_b32 v[102:103], v[94:95], v[102:103] op_sel:[1,0]
	v_pk_add_f32 v[82:83], v[98:99], v[82:83]
	v_pk_add_f32 v[80:81], v[94:95], v[80:81]
	v_pk_fma_f32 v[70:71], v[96:97], s[72:73], v[70:71] op_sel_hi:[1,0,1]
	v_pk_add_f32 v[102:103], v[106:107], v[102:103]
	v_mov_b32_e32 v106, v78
	v_mov_b32_e32 v107, v86
	v_pk_mov_b32 v[78:79], v[78:79], v[104:105] op_sel:[1,0]
	v_mov_b32_e32 v83, v101
	v_mov_b32_e32 v81, v105
	v_cvt_pk_bf16_f32 v68, v68, v69
	v_cvt_pk_bf16_f32 v69, v70, v71
	v_pk_add_f32 v[78:79], v[106:107], v[78:79]
	v_pk_add_f32 v[80:81], v[82:83], v[80:81]
	v_mov_b64_e32 v[150:151], v[68:69]
	v_lshrrev_b32_e32 v152, 4, v219
	v_lshlrev_b32_e32 v152, 3, v152
	v_mov_b32_e32 v153, v2
	v_permlane32_swap_b32_e32 v148, v150
	v_permlane32_swap_b32_e32 v149, v151
	v_lshl_add_u64 v[152:153], v[152:153], 0, v[92:93]
	s_nop 0
	v_permlane16_swap_b32_e32 v148, v150
	v_permlane16_swap_b32_e32 v149, v151
	global_store_dwordx4 v[152:153], v[148:151], off offset:256 sc0
	v_lshlrev_b32_e32 v92, 16, v68
	v_and_b32_e32 v96, 0xffff0000, v68
	v_lshlrev_b32_e32 v68, 16, v69
	v_and_b32_e32 v70, 0xffff0000, v69
	v_pk_add_f32 v[78:79], v[102:103], v[78:79]
	v_pk_add_f32 v[76:77], v[80:81], v[2:3]
	v_mul_f32_e32 v93, v92, v92
	v_mul_f32_e32 v97, v96, v96
	v_mul_f32_e32 v69, v68, v68
	v_mul_f32_e32 v71, v70, v70
	v_pk_add_f32 v[76:77], v[78:79], v[76:77]
	v_pk_add_f32 v[78:79], v[88:89], v[90:91]
	v_pk_add_f32 v[74:75], v[92:93], v[96:97]
	v_pk_add_f32 v[72:73], v[78:79], v[72:73]
	v_pk_add_f32 v[68:69], v[68:69], v[70:71]
	v_pk_add_f32 v[72:73], v[76:77], v[72:73]
	v_pk_add_f32 v[68:69], v[74:75], v[68:69]
	s_nop 0
	v_pk_add_f32 v[68:69], v[72:73], v[68:69]
	ds_bpermute_b32 v70, v181, v68
	ds_bpermute_b32 v71, v181, v69
	s_waitcnt lgkmcnt(0)
	v_pk_add_f32 v[68:69], v[68:69], v[70:71]
	ds_bpermute_b32 v70, v180, v68
	ds_bpermute_b32 v71, v180, v69
	s_and_saveexec_b64 s[0:1], s[40:41]
	s_cbranch_execz .LBB0_2211
	v_lshl_add_u64 v[72:73], s[50:51], 0, v[84:85]
	v_lshl_add_u64 v[72:73], s[60:61], 2, v[72:73]
	s_waitcnt lgkmcnt(0)
	v_pk_add_f32 v[68:69], v[68:69], v[70:71]
	global_store_dwordx2 v[72:73], v[68:69], off
.LBB0_2211:
	s_or_b64 exec, exec, s[0:1]
	v_add_u32_e32 v78, 0x80, v146
	v_ashrrev_i32_e32 v79, 31, v78
	v_lshlrev_b64 v[68:69], 7, v[78:79]
	v_lshl_add_u64 v[74:75], v[134:135], 0, v[68:69]
	s_waitcnt lgkmcnt(0)
	s_waitcnt vmcnt(7)
	v_mov_b64_e32 v[70:71], v[190:191]
	v_mov_b64_e32 v[72:73], v[192:193]
	global_load_dwordx4 v[190:193], v[248:249], off offset:16
	s_nop 0
	s_waitcnt vmcnt(7)
	v_mov_b64_e32 v[74:75], v[194:195]
	v_mov_b64_e32 v[76:77], v[196:197]
	global_load_dwordx4 v[194:197], v[248:249], off
	s_waitcnt lgkmcnt(0)
	v_pk_add_f32 v[70:71], v[70:71], v[72:73]
	s_waitcnt lgkmcnt(0)
	v_pk_add_f32 v[74:75], v[74:75], v[76:77]
	s_nop 0
	v_pk_add_f32 v[70:71], v[74:75], v[70:71]
	ds_bpermute_b32 v72, v181, v70
	ds_bpermute_b32 v73, v181, v71
	s_waitcnt lgkmcnt(0)
	v_pk_add_f32 v[70:71], v[70:71], v[72:73]
	ds_bpermute_b32 v72, v180, v70
	ds_bpermute_b32 v73, v180, v71
	s_waitcnt lgkmcnt(0)
	v_pk_add_f32 v[70:71], v[70:71], v[72:73]
	s_nop 0
	v_pk_mul_f32 v[80:81], v[70:71], s[82:83] op_sel_hi:[1,0]
	v_lshlrev_b64 v[70:71], 11, v[78:79]
	v_lshl_add_u64 v[70:71], s[70:71], 0, v[70:71]
	v_lshl_add_u64 v[76:77], v[144:145], 1, v[70:71]
	v_add_u32_e32 v243, 0x50000, v242
	s_waitcnt vmcnt(7)
	v_permlane16_swap_b32_e32 v198, v200
	v_permlane16_swap_b32_e32 v199, v201
	s_nop 0
	v_permlane32_swap_b32_e32 v198, v200
	v_permlane32_swap_b32_e32 v199, v201
	v_mov_b64_e32 v[70:71], v[198:199]
	v_fma_f32 v3, -v80, v80, v81
	v_max_f32_e32 v3, 0, v3
	v_add_f32_e32 v3, 0x3727c5ac, v3
	v_rsq_f32_e32 v82, v3
	s_waitcnt lgkmcnt(0)
	v_lshlrev_b32_e32 v3, 16, v70
	v_and_b32_e32 v70, 0xffff0000, v70
	v_lshlrev_b32_e32 v72, 16, v71
	v_and_b32_e32 v73, 0xffff0000, v71
	v_sub_f32_e32 v71, v70, v80
	v_sub_f32_e32 v70, v3, v80
	v_sub_f32_e32 v73, v73, v80
	v_sub_f32_e32 v72, v72, v80
	v_pk_mul_f32 v[74:75], v[72:73], v[82:83] op_sel_hi:[1,0]
	v_pk_mul_f32 v[78:79], v[70:71], v[82:83] op_sel_hi:[1,0]
	ds_read_b128 v[70:73], v244
	ds_read_b128 v[84:87], v244 offset:256
	s_waitcnt lgkmcnt(0)
	v_pk_fma_f32 v[72:73], v[72:73], v[74:75], v[86:87]
	s_nop 0
	v_pk_fma_f32 v[66:67], v[72:73], s[72:73], v[66:67] op_sel_hi:[1,0,1]
	v_mov_b64_e32 v[72:73], v[200:201]
	v_lshrrev_b32_e32 v245, 4, v219
	v_lshl_add_u32 v245, v245, 3, v243
	global_load_dwordx4 v[198:201], v245, s[70:71]
	v_pk_fma_f32 v[70:71], v[70:71], v[78:79], v[84:85]
	s_waitcnt lgkmcnt(0)
; __device__ __forceinline__ u32x2 pk4(f32x4 v) { u32x2 r; r.x = pk2(v.x, v.y); r.y = pk2(v.z, v.w); return r; }
;     __device__ __forceinline__ void operator()(const f32x4 (&acc)[2][2][4][2], const pg8::Unit& u, int wr, int wc, int fr, int fq) const {
;     ...
;                 for (int bj = 0; bj < 2; ++bj)
; #pragma unroll
;                     for (int n = 0; n < 2; ++n) {
;                         const int col = u.pn * 256 + bj * 128 + wc * 32 + n * 16 + fq * 4;
;                         const u32x2 raw = *(const u32x2*)(src + (size_t)row * DM + col);
;                         f32x4 x = (f32x4){bflo(raw.x), bfhi(raw.x), bflo(raw.y), bfhi(raw.y)};
;                         if (ln) x = (x - mu) * rs * *(const f32x4*)(g + col) + *(const f32x4*)(b + col);
;                         const u32x2 pz = pk4(x * ALPHA + acc[ai][bj][m][n]);
;                         *(u32x2*)(dst + (size_t)row * DM + col) = pz;
;                         const float z0 = bflo(pz.x), z1 = bfhi(pz.x), z2 = bflo(pz.y), z3 = bfhi(pz.y);
;                         s1 += (z0 + z1) + (z2 + z3); s2 += (z0 * z0 + z1 * z1) + (z2 * z2 + z3 * z3);
;                     }
;                 s1 += __shfl_xor(s1, 16); s2 += __shfl_xor(s2, 16); s1 += __shfl_xor(s1, 32); s2 += __shfl_xor(s2, 32);
;                 if (fq == 0) { float* p = stm_n + (size_t)row * 32 + (u.pn * 4 + wc) * 2; p[0] = s1; p[1] = s2; }
	v_lshlrev_b32_e32 v3, 16, v72
	v_pk_fma_f32 v[64:65], v[70:71], s[72:73], v[64:65] op_sel_hi:[1,0,1]
	v_cvt_pk_bf16_f32 v71, v66, v67
	v_cvt_pk_bf16_f32 v70, v64, v65
	v_and_b32_e32 v65, 0xffff0000, v72
	v_lshlrev_b32_e32 v67, 16, v73
	v_and_b32_e32 v74, 0xffff0000, v73
	v_mov_b64_e32 v[148:149], v[70:71]
	v_sub_f32_e32 v73, v65, v80
	v_sub_f32_e32 v72, v3, v80
	v_sub_f32_e32 v75, v74, v80
	v_sub_f32_e32 v74, v67, v80
	v_pk_mul_f32 v[78:79], v[82:83], v[74:75] op_sel_hi:[0,1]
	v_pk_mul_f32 v[88:89], v[82:83], v[72:73] op_sel_hi:[0,1]
	ds_read_b128 v[72:75], v244 offset:64
	ds_read_b128 v[84:87], v244 offset:320
	v_and_b32_e32 v66, 0xffff0000, v70
	v_lshlrev_b32_e32 v64, 16, v71
	s_waitcnt lgkmcnt(0)
	v_pk_fma_f32 v[72:73], v[72:73], v[88:89], v[84:85]
	s_nop 0
	v_pk_fma_f32 v[60:61], v[72:73], s[72:73], v[60:61] op_sel_hi:[1,0,1]
	s_waitcnt vmcnt(7)
	v_permlane16_swap_b32_e32 v202, v204
	v_permlane16_swap_b32_e32 v203, v205
	s_nop 0
	v_permlane32_swap_b32_e32 v202, v204
	v_permlane32_swap_b32_e32 v203, v205
	v_mov_b64_e32 v[72:73], v[202:203]
	v_pk_fma_f32 v[74:75], v[74:75], v[78:79], v[86:87]
	v_cvt_pk_bf16_f32 v78, v60, v61
	v_pk_fma_f32 v[62:63], v[74:75], s[72:73], v[62:63] op_sel_hi:[1,0,1]
	s_waitcnt lgkmcnt(0)
	v_lshlrev_b32_e32 v3, 16, v72
	v_cvt_pk_bf16_f32 v79, v62, v63
	v_lshlrev_b32_e32 v62, 16, v79
	v_and_b32_e32 v63, 0xffff0000, v79
	v_mul_f32_e32 v60, v62, v62
	v_pk_fma_f32 v[60:61], v[62:63], v[62:63], v[60:61] op_sel_hi:[1,1,0]
	v_lshlrev_b32_e32 v65, 16, v73
	v_and_b32_e32 v60, 0xffff0000, v72
	v_and_b32_e32 v67, 0xffff0000, v73
	v_mov_b64_e32 v[150:151], v[78:79]
	v_lshrrev_b32_e32 v90, 4, v219
	v_lshlrev_b32_e32 v90, 3, v90
	v_mov_b32_e32 v91, v2
	v_permlane32_swap_b32_e32 v148, v150
	v_permlane32_swap_b32_e32 v149, v151
	v_lshl_add_u64 v[90:91], v[90:91], 0, v[76:77]
	s_nop 0
	v_permlane16_swap_b32_e32 v148, v150
	v_permlane16_swap_b32_e32 v149, v151
	global_store_dwordx4 v[90:91], v[148:151], off sc0
	v_sub_f32_e32 v73, v60, v80
	v_sub_f32_e32 v72, v3, v80
	v_sub_f32_e32 v75, v67, v80
	v_sub_f32_e32 v74, v65, v80
	v_pk_mul_f32 v[88:89], v[82:83], v[74:75] op_sel_hi:[0,1]
	v_pk_mul_f32 v[90:91], v[82:83], v[72:73] op_sel_hi:[0,1]
	ds_read_b128 v[72:75], v244 offset:128
	ds_read_b128 v[84:87], v244 offset:384
	v_and_b32_e32 v79, 0xffff0000, v78
	s_waitcnt lgkmcnt(0)
	v_pk_fma_f32 v[72:73], v[72:73], v[90:91], v[84:85]
	v_mov_b64_e32 v[84:85], v[204:205]
	v_lshrrev_b32_e32 v245, 4, v219
	v_lshl_add_u32 v245, v245, 3, v243
	global_load_dwordx4 v[202:205], v245, s[70:71] offset:256
	v_pk_fma_f32 v[74:75], v[74:75], v[88:89], v[86:87]
	v_pk_fma_f32 v[56:57], v[72:73], s[72:73], v[56:57] op_sel_hi:[1,0,1]
	v_pk_fma_f32 v[58:59], v[74:75], s[72:73], v[58:59] op_sel_hi:[1,0,1]
	v_cvt_pk_bf16_f32 v56, v56, v57
	v_cvt_pk_bf16_f32 v57, v58, v59
	v_mov_b64_e32 v[148:149], v[56:57]
	v_lshlrev_b32_e32 v72, 16, v56
	v_and_b32_e32 v74, 0xffff0000, v56
	v_lshlrev_b32_e32 v56, 16, v57
	v_and_b32_e32 v58, 0xffff0000, v57
	v_mul_f32_e32 v73, v72, v72
	v_mul_f32_e32 v75, v74, v74
	v_mul_f32_e32 v57, v56, v56
	v_mul_f32_e32 v59, v58, v58
	v_pk_add_f32 v[56:57], v[56:57], v[58:59]
	s_waitcnt lgkmcnt(0)
	v_lshlrev_b32_e32 v3, 16, v84
	v_and_b32_e32 v60, 0xffff0000, v84
	v_lshlrev_b32_e32 v65, 16, v85
	v_and_b32_e32 v67, 0xffff0000, v85
	v_sub_f32_e32 v85, v60, v80
	v_sub_f32_e32 v84, v3, v80
	v_sub_f32_e32 v81, v67, v80
	v_sub_f32_e32 v80, v65, v80
	v_pk_mul_f32 v[80:81], v[82:83], v[80:81] op_sel_hi:[0,1]
	v_pk_mul_f32 v[82:83], v[82:83], v[84:85] op_sel_hi:[0,1]
	ds_read_b128 v[84:87], v244 offset:192
	ds_read_b128 v[88:91], v244 offset:448
	v_mov_b32_e32 v65, v79
	v_mov_b32_e32 v3, v61
	s_waitcnt lgkmcnt(0)
	v_pk_fma_f32 v[82:83], v[84:85], v[82:83], v[88:89]
	s_nop 0
	v_pk_fma_f32 v[52:53], v[82:83], s[72:73], v[52:53] op_sel_hi:[1,0,1]
	v_lshlrev_b32_e32 v83, 16, v78
	v_lshlrev_b32_e32 v82, 16, v70
	v_mov_b32_e32 v67, v83
	v_pk_fma_f32 v[80:81], v[86:87], v[80:81], v[90:91]
	v_pk_mul_f32 v[84:85], v[82:83], v[82:83]
	v_pk_mul_f32 v[86:87], v[66:67], v[66:67]
	v_and_b32_e32 v78, 0xffff0000, v71
	v_pk_mul_f32 v[70:71], v[64:65], v[64:65]
	v_pk_mul_f32 v[88:89], v[78:79], v[78:79]
	v_pk_mov_b32 v[90:91], v[82:83], v[84:85] op_sel:[1,0]
	v_pk_mov_b32 v[86:87], v[78:79], v[86:87] op_sel:[1,0]
	v_pk_add_f32 v[66:67], v[82:83], v[66:67]
	v_pk_add_f32 v[64:65], v[78:79], v[64:65]
	v_pk_fma_f32 v[54:55], v[80:81], s[72:73], v[54:55] op_sel_hi:[1,0,1]
	v_pk_add_f32 v[86:87], v[90:91], v[86:87]
	v_mov_b32_e32 v90, v62
	v_mov_b32_e32 v91, v70
	v_pk_mov_b32 v[62:63], v[62:63], v[88:89] op_sel:[1,0]
	v_mov_b32_e32 v67, v85
	v_mov_b32_e32 v65, v89
	v_cvt_pk_bf16_f32 v52, v52, v53
	v_cvt_pk_bf16_f32 v53, v54, v55
	v_pk_add_f32 v[62:63], v[90:91], v[62:63]
	v_pk_add_f32 v[64:65], v[66:67], v[64:65]
	v_mov_b64_e32 v[150:151], v[52:53]
	v_lshrrev_b32_e32 v152, 4, v219
	v_lshlrev_b32_e32 v152, 3, v152
	v_mov_b32_e32 v153, v2
	v_permlane32_swap_b32_e32 v148, v150
	v_permlane32_swap_b32_e32 v149, v151
	v_lshl_add_u64 v[152:153], v[152:153], 0, v[76:77]
	s_nop 0
	v_permlane16_swap_b32_e32 v148, v150
	v_permlane16_swap_b32_e32 v149, v151
	global_store_dwordx4 v[152:153], v[148:151], off offset:256 sc0
	v_lshlrev_b32_e32 v76, 16, v52
	v_and_b32_e32 v80, 0xffff0000, v52
	v_lshlrev_b32_e32 v52, 16, v53
	v_and_b32_e32 v54, 0xffff0000, v53
	v_pk_add_f32 v[62:63], v[86:87], v[62:63]
	v_pk_add_f32 v[60:61], v[64:65], v[2:3]
	v_mul_f32_e32 v77, v76, v76
	v_mul_f32_e32 v81, v80, v80
	v_mul_f32_e32 v53, v52, v52
	v_mul_f32_e32 v55, v54, v54
	v_pk_add_f32 v[60:61], v[62:63], v[60:61]
	v_pk_add_f32 v[62:63], v[72:73], v[74:75]
	v_pk_add_f32 v[58:59], v[76:77], v[80:81]
	v_pk_add_f32 v[56:57], v[62:63], v[56:57]
	v_pk_add_f32 v[52:53], v[52:53], v[54:55]
	v_pk_add_f32 v[56:57], v[60:61], v[56:57]
	v_pk_add_f32 v[52:53], v[58:59], v[52:53]
	s_nop 0
	v_pk_add_f32 v[52:53], v[56:57], v[52:53]
	ds_bpermute_b32 v54, v181, v52
	ds_bpermute_b32 v55, v181, v53
	s_waitcnt lgkmcnt(0)
	v_pk_add_f32 v[52:53], v[52:53], v[54:55]
	ds_bpermute_b32 v54, v180, v52
	ds_bpermute_b32 v55, v180, v53
	s_and_saveexec_b64 s[0:1], s[40:41]
	s_cbranch_execz .LBB0_2213
	v_lshl_add_u64 v[56:57], s[50:51], 0, v[68:69]
	v_lshl_add_u64 v[56:57], s[60:61], 2, v[56:57]
	s_waitcnt lgkmcnt(0)
	v_pk_add_f32 v[52:53], v[52:53], v[54:55]
	global_store_dwordx2 v[56:57], v[52:53], off
; __device__ __forceinline__ u32x2 pk4(f32x4 v) { u32x2 r; r.x = pk2(v.x, v.y); r.y = pk2(v.z, v.w); return r; }
; __device__ __forceinline__ void stats_main(const float* stm, int row, int fq, float& mu, float& rs) {
;     const f32x4* p = (const f32x4*)(stm + (size_t)row * 32 + fq * 8);
;     const f32x4 a = p[0], b = p[1];
;     float s1 = (a.x + a.z) + (b.x + b.z), s2 = (a.y + a.w) + (b.y + b.w);
;     s1 += __shfl_xor(s1, 16); s2 += __shfl_xor(s2, 16); s1 += __shfl_xor(s1, 32); s2 += __shfl_xor(s2, 32);
;     mu = s1 * (1.f / DM); rs = __builtin_amdgcn_rsqf(fmaxf(s2 * (1.f / DM) - mu * mu, 0.f) + LN_EPS);
; }
;     __device__ __forceinline__ void operator()(const f32x4 (&acc)[2][2][4][2], const pg8::Unit& u, int wr, int wc, int fr, int fq) const {
;     ...
;                 const int row = u.pm * 256 + ai * 128 + wr * 64 + m * 16 + fr;
;                 float mu = 0.f, rs = 1.f; if (ln) stats_main(stm_p, row, fq, mu, rs);
;                 float s1 = 0.f, s2 = 0.f;
; #pragma unroll
;                 for (int bj = 0; bj < 2; ++bj)
; #pragma unroll
;                     for (int n = 0; n < 2; ++n) {
;                         const int col = u.pn * 256 + bj * 128 + wc * 32 + n * 16 + fq * 4;
;                         const u32x2 raw = *(const u32x2*)(src + (size_t)row * DM + col);
;                         f32x4 x = (f32x4){bflo(raw.x), bfhi(raw.x), bflo(raw.y), bfhi(raw.y)};
;                         if (ln) x = (x - mu) * rs * *(const f32x4*)(g + col) + *(const f32x4*)(b + col);
;                         const u32x2 pz = pk4(x * ALPHA + acc[ai][bj][m][n]);
;                         *(u32x2*)(dst + (size_t)row * DM + col) = pz;
;                         const float z0 = bflo(pz.x), z1 = bfhi(pz.x), z2 = bflo(pz.y), z3 = bfhi(pz.y);
;                         s1 += (z0 + z1) + (z2 + z3); s2 += (z0 * z0 + z1 * z1) + (z2 * z2 + z3 * z3);
;                     }
;                 s1 += __shfl_xor(s1, 16); s2 += __shfl_xor(s2, 16); s1 += __shfl_xor(s1, 32); s2 += __shfl_xor(s2, 32);
;                 if (fq == 0) { float* p = stm_n + (size_t)row * 32 + (u.pn * 4 + wc) * 2; p[0] = s1; p[1] = s2; }
.LBB0_2213:
	s_or_b64 exec, exec, s[0:1]
	v_add_u32_e32 v62, 0x90, v146
	v_ashrrev_i32_e32 v63, 31, v62
	v_lshlrev_b64 v[52:53], 7, v[62:63]
	v_lshl_add_u64 v[58:59], v[134:135], 0, v[52:53]
	s_waitcnt lgkmcnt(0)
	s_waitcnt vmcnt(7)
	v_mov_b64_e32 v[54:55], v[206:207]
	v_mov_b64_e32 v[56:57], v[208:209]
	global_load_dwordx4 v[206:209], v[248:249], off offset:2064
	s_nop 0
	s_waitcnt vmcnt(7)
	v_mov_b64_e32 v[58:59], v[214:215]
	v_mov_b64_e32 v[60:61], v[216:217]
	global_load_dwordx4 v[214:217], v[248:249], off offset:2048
	s_waitcnt lgkmcnt(0)
	v_pk_add_f32 v[54:55], v[54:55], v[56:57]
	s_waitcnt lgkmcnt(0)
	v_pk_add_f32 v[58:59], v[58:59], v[60:61]
	s_nop 0
	v_pk_add_f32 v[54:55], v[58:59], v[54:55]
	ds_bpermute_b32 v56, v181, v54
	ds_bpermute_b32 v57, v181, v55
	s_waitcnt lgkmcnt(0)
	v_pk_add_f32 v[54:55], v[54:55], v[56:57]
	ds_bpermute_b32 v56, v180, v54
	ds_bpermute_b32 v57, v180, v55
	s_waitcnt lgkmcnt(0)
	v_pk_add_f32 v[54:55], v[54:55], v[56:57]
	s_nop 0
	v_pk_mul_f32 v[64:65], v[54:55], s[82:83] op_sel_hi:[1,0]
	v_lshlrev_b64 v[54:55], 11, v[62:63]
	v_lshl_add_u64 v[54:55], s[70:71], 0, v[54:55]
	v_lshl_add_u64 v[60:61], v[144:145], 1, v[54:55]
	v_add_u32_e32 v243, 0x58000, v242
	s_waitcnt vmcnt(7)
	v_permlane16_swap_b32_e32 v234, v236
	v_permlane16_swap_b32_e32 v235, v237
	s_nop 0
	v_permlane32_swap_b32_e32 v234, v236
	v_permlane32_swap_b32_e32 v235, v237
	v_mov_b64_e32 v[54:55], v[234:235]
	v_fma_f32 v3, -v64, v64, v65
	v_max_f32_e32 v3, 0, v3
	v_add_f32_e32 v3, 0x3727c5ac, v3
	v_rsq_f32_e32 v66, v3
	s_waitcnt lgkmcnt(0)
	v_lshlrev_b32_e32 v3, 16, v54
	v_and_b32_e32 v54, 0xffff0000, v54
	v_lshlrev_b32_e32 v56, 16, v55
	v_and_b32_e32 v57, 0xffff0000, v55
	v_sub_f32_e32 v55, v54, v64
	v_sub_f32_e32 v54, v3, v64
	v_sub_f32_e32 v57, v57, v64
	v_sub_f32_e32 v56, v56, v64
	v_pk_mul_f32 v[58:59], v[56:57], v[66:67] op_sel_hi:[1,0]
	v_pk_mul_f32 v[62:63], v[54:55], v[66:67] op_sel_hi:[1,0]
	ds_read_b128 v[54:57], v244
	ds_read_b128 v[68:71], v244 offset:256
	s_waitcnt lgkmcnt(0)
	v_pk_fma_f32 v[56:57], v[56:57], v[58:59], v[70:71]
	s_nop 0
	v_pk_fma_f32 v[50:51], v[56:57], s[72:73], v[50:51] op_sel_hi:[1,0,1]
	v_mov_b64_e32 v[56:57], v[236:237]
	v_lshrrev_b32_e32 v245, 4, v219
	v_lshl_add_u32 v245, v245, 3, v243
	global_load_dwordx4 v[234:237], v245, s[70:71]
	v_pk_fma_f32 v[54:55], v[54:55], v[62:63], v[68:69]
	s_waitcnt lgkmcnt(0)
	v_lshlrev_b32_e32 v3, 16, v56
	v_pk_fma_f32 v[48:49], v[54:55], s[72:73], v[48:49] op_sel_hi:[1,0,1]
	v_cvt_pk_bf16_f32 v55, v50, v51
	v_cvt_pk_bf16_f32 v54, v48, v49
	v_and_b32_e32 v49, 0xffff0000, v56
	v_lshlrev_b32_e32 v51, 16, v57
	v_and_b32_e32 v58, 0xffff0000, v57
	v_mov_b64_e32 v[148:149], v[54:55]
	v_sub_f32_e32 v57, v49, v64
	v_sub_f32_e32 v56, v3, v64
	v_sub_f32_e32 v59, v58, v64
	v_sub_f32_e32 v58, v51, v64
	v_pk_mul_f32 v[62:63], v[66:67], v[58:59] op_sel_hi:[0,1]
	v_pk_mul_f32 v[72:73], v[66:67], v[56:57] op_sel_hi:[0,1]
	ds_read_b128 v[56:59], v244 offset:64
	ds_read_b128 v[68:71], v244 offset:320
	v_and_b32_e32 v50, 0xffff0000, v54
	v_lshlrev_b32_e32 v48, 16, v55
	s_waitcnt lgkmcnt(0)
	v_pk_fma_f32 v[56:57], v[56:57], v[72:73], v[68:69]
	s_nop 0
	v_pk_fma_f32 v[44:45], v[56:57], s[72:73], v[44:45] op_sel_hi:[1,0,1]
	s_waitcnt vmcnt(7)
	v_permlane16_swap_b32_e32 v238, v240
	v_permlane16_swap_b32_e32 v239, v241
	s_nop 0
	v_permlane32_swap_b32_e32 v238, v240
	v_permlane32_swap_b32_e32 v239, v241
	v_mov_b64_e32 v[56:57], v[238:239]
	v_pk_fma_f32 v[58:59], v[58:59], v[62:63], v[70:71]
	v_cvt_pk_bf16_f32 v62, v44, v45
	v_pk_fma_f32 v[46:47], v[58:59], s[72:73], v[46:47] op_sel_hi:[1,0,1]
	s_waitcnt lgkmcnt(0)
	v_lshlrev_b32_e32 v3, 16, v56
	v_cvt_pk_bf16_f32 v63, v46, v47
	v_lshlrev_b32_e32 v46, 16, v63
	v_and_b32_e32 v47, 0xffff0000, v63
	v_mul_f32_e32 v44, v46, v46
	v_pk_fma_f32 v[44:45], v[46:47], v[46:47], v[44:45] op_sel_hi:[1,1,0]
	v_lshlrev_b32_e32 v49, 16, v57
	v_and_b32_e32 v44, 0xffff0000, v56
	v_and_b32_e32 v51, 0xffff0000, v57
	v_mov_b64_e32 v[150:151], v[62:63]
	v_lshrrev_b32_e32 v74, 4, v219
	v_lshlrev_b32_e32 v74, 3, v74
	v_mov_b32_e32 v75, v2
	v_permlane32_swap_b32_e32 v148, v150
	v_permlane32_swap_b32_e32 v149, v151
	v_lshl_add_u64 v[74:75], v[74:75], 0, v[60:61]
	s_nop 0
	v_permlane16_swap_b32_e32 v148, v150
	v_permlane16_swap_b32_e32 v149, v151
	global_store_dwordx4 v[74:75], v[148:151], off sc0
	v_sub_f32_e32 v57, v44, v64
	v_sub_f32_e32 v56, v3, v64
	v_sub_f32_e32 v59, v51, v64
	v_sub_f32_e32 v58, v49, v64
	v_pk_mul_f32 v[72:73], v[66:67], v[58:59] op_sel_hi:[0,1]
	v_pk_mul_f32 v[74:75], v[66:67], v[56:57] op_sel_hi:[0,1]
	ds_read_b128 v[56:59], v244 offset:128
	ds_read_b128 v[68:71], v244 offset:384
	v_and_b32_e32 v63, 0xffff0000, v62
	s_waitcnt lgkmcnt(0)
	v_pk_fma_f32 v[56:57], v[56:57], v[74:75], v[68:69]
	v_mov_b64_e32 v[68:69], v[240:241]
	v_lshrrev_b32_e32 v245, 4, v219
	v_lshl_add_u32 v245, v245, 3, v243
	global_load_dwordx4 v[238:241], v245, s[70:71] offset:256
	v_pk_fma_f32 v[58:59], v[58:59], v[72:73], v[70:71]
	v_pk_fma_f32 v[40:41], v[56:57], s[72:73], v[40:41] op_sel_hi:[1,0,1]
	v_pk_fma_f32 v[42:43], v[58:59], s[72:73], v[42:43] op_sel_hi:[1,0,1]
	v_cvt_pk_bf16_f32 v40, v40, v41
	v_cvt_pk_bf16_f32 v41, v42, v43
	v_mov_b64_e32 v[148:149], v[40:41]
	v_lshlrev_b32_e32 v56, 16, v40
	v_and_b32_e32 v58, 0xffff0000, v40
	v_lshlrev_b32_e32 v40, 16, v41
	v_and_b32_e32 v42, 0xffff0000, v41
	v_mul_f32_e32 v57, v56, v56
	v_mul_f32_e32 v59, v58, v58
	v_mul_f32_e32 v41, v40, v40
	v_mul_f32_e32 v43, v42, v42
	v_pk_add_f32 v[40:41], v[40:41], v[42:43]
	s_waitcnt lgkmcnt(0)
; __device__ __forceinline__ void stats_main(const float* stm, int row, int fq, float& mu, float& rs) {
;     const f32x4* p = (const f32x4*)(stm + (size_t)row * 32 + fq * 8);
;     const f32x4 a = p[0], b = p[1];
;     float s1 = (a.x + a.z) + (b.x + b.z), s2 = (a.y + a.w) + (b.y + b.w);
;     s1 += __shfl_xor(s1, 16); s2 += __shfl_xor(s2, 16); s1 += __shfl_xor(s1, 32); s2 += __shfl_xor(s2, 32);
;     mu = s1 * (1.f / DM); rs = __builtin_amdgcn_rsqf(fmaxf(s2 * (1.f / DM) - mu * mu, 0.f) + LN_EPS);
; }
;     __device__ __forceinline__ void operator()(const f32x4 (&acc)[2][2][4][2], const pg8::Unit& u, int wr, int wc, int fr, int fq) const {
;     ...
;                 for (int bj = 0; bj < 2; ++bj)
; #pragma unroll
;                     for (int n = 0; n < 2; ++n) {
;                         const int col = u.pn * 256 + bj * 128 + wc * 32 + n * 16 + fq * 4;
;                         const u32x2 raw = *(const u32x2*)(src + (size_t)row * DM + col);
;     ...
;                         const float z0 = bflo(pz.x), z1 = bfhi(pz.x), z2 = bflo(pz.y), z3 = bfhi(pz.y);
;                         s1 += (z0 + z1) + (z2 + z3); s2 += (z0 * z0 + z1 * z1) + (z2 * z2 + z3 * z3);
;                     }
;                 s1 += __shfl_xor(s1, 16); s2 += __shfl_xor(s2, 16); s1 += __shfl_xor(s1, 32); s2 += __shfl_xor(s2, 32);
;                 if (fq == 0) { float* p = stm_n + (size_t)row * 32 + (u.pn * 4 + wc) * 2; p[0] = s1; p[1] = s2; }
	v_lshlrev_b32_e32 v3, 16, v68
	v_and_b32_e32 v44, 0xffff0000, v68
	v_lshlrev_b32_e32 v49, 16, v69
	v_and_b32_e32 v51, 0xffff0000, v69
	v_sub_f32_e32 v69, v44, v64
	v_sub_f32_e32 v68, v3, v64
	v_sub_f32_e32 v65, v51, v64
	v_sub_f32_e32 v64, v49, v64
	v_pk_mul_f32 v[64:65], v[66:67], v[64:65] op_sel_hi:[0,1]
	v_pk_mul_f32 v[66:67], v[66:67], v[68:69] op_sel_hi:[0,1]
	ds_read_b128 v[68:71], v244 offset:192
	ds_read_b128 v[72:75], v244 offset:448
	v_mov_b32_e32 v49, v63
	v_mov_b32_e32 v3, v45
	s_waitcnt lgkmcnt(0)
	v_pk_fma_f32 v[66:67], v[68:69], v[66:67], v[72:73]
	s_nop 0
	v_pk_fma_f32 v[36:37], v[66:67], s[72:73], v[36:37] op_sel_hi:[1,0,1]
	v_lshlrev_b32_e32 v67, 16, v62
	v_lshlrev_b32_e32 v66, 16, v54
	v_mov_b32_e32 v51, v67
	v_pk_fma_f32 v[64:65], v[70:71], v[64:65], v[74:75]
	v_pk_mul_f32 v[68:69], v[66:67], v[66:67]
	v_pk_mul_f32 v[70:71], v[50:51], v[50:51]
	v_and_b32_e32 v62, 0xffff0000, v55
	v_pk_mul_f32 v[54:55], v[48:49], v[48:49]
	v_pk_mul_f32 v[72:73], v[62:63], v[62:63]
	v_pk_mov_b32 v[74:75], v[66:67], v[68:69] op_sel:[1,0]
	v_pk_mov_b32 v[70:71], v[62:63], v[70:71] op_sel:[1,0]
	v_pk_add_f32 v[50:51], v[66:67], v[50:51]
	v_pk_add_f32 v[48:49], v[62:63], v[48:49]
	v_pk_fma_f32 v[38:39], v[64:65], s[72:73], v[38:39] op_sel_hi:[1,0,1]
	v_pk_add_f32 v[70:71], v[74:75], v[70:71]
	v_mov_b32_e32 v74, v46
	v_mov_b32_e32 v75, v54
	v_pk_mov_b32 v[46:47], v[46:47], v[72:73] op_sel:[1,0]
	v_mov_b32_e32 v51, v69
	v_mov_b32_e32 v49, v73
	v_cvt_pk_bf16_f32 v36, v36, v37
	v_cvt_pk_bf16_f32 v37, v38, v39
	v_pk_add_f32 v[46:47], v[74:75], v[46:47]
	v_pk_add_f32 v[48:49], v[50:51], v[48:49]
	v_mov_b64_e32 v[150:151], v[36:37]
	v_lshrrev_b32_e32 v152, 4, v219
	v_lshlrev_b32_e32 v152, 3, v152
	v_mov_b32_e32 v153, v2
	v_permlane32_swap_b32_e32 v148, v150
	v_permlane32_swap_b32_e32 v149, v151
	v_lshl_add_u64 v[152:153], v[152:153], 0, v[60:61]
	s_nop 0
	v_permlane16_swap_b32_e32 v148, v150
	v_permlane16_swap_b32_e32 v149, v151
	global_store_dwordx4 v[152:153], v[148:151], off offset:256 sc0
	v_lshlrev_b32_e32 v60, 16, v36
	v_and_b32_e32 v64, 0xffff0000, v36
	v_lshlrev_b32_e32 v36, 16, v37
	v_and_b32_e32 v38, 0xffff0000, v37
	v_pk_add_f32 v[46:47], v[70:71], v[46:47]
	v_pk_add_f32 v[44:45], v[48:49], v[2:3]
	v_mul_f32_e32 v61, v60, v60
	v_mul_f32_e32 v65, v64, v64
	v_mul_f32_e32 v37, v36, v36
	v_mul_f32_e32 v39, v38, v38
	v_pk_add_f32 v[44:45], v[46:47], v[44:45]
	v_pk_add_f32 v[46:47], v[56:57], v[58:59]
	v_pk_add_f32 v[42:43], v[60:61], v[64:65]
	v_pk_add_f32 v[40:41], v[46:47], v[40:41]
	v_pk_add_f32 v[36:37], v[36:37], v[38:39]
	v_pk_add_f32 v[40:41], v[44:45], v[40:41]
	v_pk_add_f32 v[36:37], v[42:43], v[36:37]
	s_nop 0
	v_pk_add_f32 v[36:37], v[40:41], v[36:37]
	ds_bpermute_b32 v38, v181, v36
	ds_bpermute_b32 v39, v181, v37
	s_waitcnt lgkmcnt(0)
	v_pk_add_f32 v[36:37], v[36:37], v[38:39]
	ds_bpermute_b32 v38, v180, v36
	ds_bpermute_b32 v39, v180, v37
	s_and_saveexec_b64 s[0:1], s[40:41]
	s_cbranch_execz .LBB0_2215
	v_lshl_add_u64 v[40:41], s[50:51], 0, v[52:53]
	v_lshl_add_u64 v[40:41], s[60:61], 2, v[40:41]
	s_waitcnt lgkmcnt(0)
	v_pk_add_f32 v[36:37], v[36:37], v[38:39]
	global_store_dwordx2 v[40:41], v[36:37], off
.LBB0_2215:
	s_or_b64 exec, exec, s[0:1]
	v_add_u32_e32 v46, 0xa0, v146
	v_ashrrev_i32_e32 v47, 31, v46
	v_lshlrev_b64 v[36:37], 7, v[46:47]
	v_lshl_add_u64 v[42:43], v[134:135], 0, v[36:37]
	s_waitcnt lgkmcnt(0)
	s_waitcnt vmcnt(7)
	v_mov_b64_e32 v[38:39], v[190:191]
	v_mov_b64_e32 v[40:41], v[192:193]
	s_nop 0
	s_waitcnt vmcnt(6)
	v_mov_b64_e32 v[42:43], v[194:195]
	v_mov_b64_e32 v[44:45], v[196:197]
	s_waitcnt lgkmcnt(0)
	v_pk_add_f32 v[38:39], v[38:39], v[40:41]
	s_waitcnt lgkmcnt(0)
	v_pk_add_f32 v[42:43], v[42:43], v[44:45]
	s_nop 0
	v_pk_add_f32 v[38:39], v[42:43], v[38:39]
	ds_bpermute_b32 v40, v181, v38
	ds_bpermute_b32 v41, v181, v39
	s_waitcnt lgkmcnt(0)
	v_pk_add_f32 v[38:39], v[38:39], v[40:41]
	ds_bpermute_b32 v40, v180, v38
	ds_bpermute_b32 v41, v180, v39
	s_waitcnt lgkmcnt(0)
	v_pk_add_f32 v[38:39], v[38:39], v[40:41]
	s_nop 0
	v_pk_mul_f32 v[48:49], v[38:39], s[82:83] op_sel_hi:[1,0]
	v_lshlrev_b64 v[38:39], 11, v[46:47]
	v_lshl_add_u64 v[38:39], s[70:71], 0, v[38:39]
	v_lshl_add_u64 v[44:45], v[144:145], 1, v[38:39]
	s_waitcnt vmcnt(5)
	v_permlane16_swap_b32_e32 v198, v200
	v_permlane16_swap_b32_e32 v199, v201
	s_nop 0
	v_permlane32_swap_b32_e32 v198, v200
	v_permlane32_swap_b32_e32 v199, v201
	v_mov_b64_e32 v[38:39], v[198:199]
	v_fma_f32 v3, -v48, v48, v49
	v_max_f32_e32 v3, 0, v3
	v_add_f32_e32 v3, 0x3727c5ac, v3
	v_rsq_f32_e32 v50, v3
	s_waitcnt lgkmcnt(0)
	v_lshlrev_b32_e32 v3, 16, v38
	v_and_b32_e32 v38, 0xffff0000, v38
	v_lshlrev_b32_e32 v40, 16, v39
	v_and_b32_e32 v41, 0xffff0000, v39
	v_sub_f32_e32 v39, v38, v48
	v_sub_f32_e32 v38, v3, v48
	v_sub_f32_e32 v41, v41, v48
	v_sub_f32_e32 v40, v40, v48
	v_pk_mul_f32 v[42:43], v[40:41], v[50:51] op_sel_hi:[1,0]
	v_pk_mul_f32 v[46:47], v[38:39], v[50:51] op_sel_hi:[1,0]
	ds_read_b128 v[38:41], v244
	ds_read_b128 v[52:55], v244 offset:256
	s_waitcnt lgkmcnt(0)
	v_pk_fma_f32 v[40:41], v[40:41], v[42:43], v[54:55]
	s_nop 0
	v_pk_fma_f32 v[34:35], v[40:41], s[72:73], v[34:35] op_sel_hi:[1,0,1]
	v_mov_b64_e32 v[40:41], v[200:201]
	v_pk_fma_f32 v[38:39], v[38:39], v[46:47], v[52:53]
	s_waitcnt lgkmcnt(0)
	v_lshlrev_b32_e32 v3, 16, v40
	v_pk_fma_f32 v[32:33], v[38:39], s[72:73], v[32:33] op_sel_hi:[1,0,1]
	v_cvt_pk_bf16_f32 v39, v34, v35
	v_cvt_pk_bf16_f32 v38, v32, v33
	v_and_b32_e32 v33, 0xffff0000, v40
	v_lshlrev_b32_e32 v35, 16, v41
	v_and_b32_e32 v42, 0xffff0000, v41
	v_mov_b64_e32 v[148:149], v[38:39]
	v_sub_f32_e32 v41, v33, v48
	v_sub_f32_e32 v40, v3, v48
	v_sub_f32_e32 v43, v42, v48
	v_sub_f32_e32 v42, v35, v48
	v_pk_mul_f32 v[46:47], v[50:51], v[42:43] op_sel_hi:[0,1]
	v_pk_mul_f32 v[56:57], v[50:51], v[40:41] op_sel_hi:[0,1]
	ds_read_b128 v[40:43], v244 offset:64
	ds_read_b128 v[52:55], v244 offset:320
	v_and_b32_e32 v34, 0xffff0000, v38
	v_lshlrev_b32_e32 v32, 16, v39
	s_waitcnt lgkmcnt(0)
; __device__ __forceinline__ u32x2 pk4(f32x4 v) { u32x2 r; r.x = pk2(v.x, v.y); r.y = pk2(v.z, v.w); return r; }
;     __device__ __forceinline__ void operator()(const f32x4 (&acc)[2][2][4][2], const pg8::Unit& u, int wr, int wc, int fr, int fq) const {
;     ...
;                 for (int bj = 0; bj < 2; ++bj)
; #pragma unroll
;                     for (int n = 0; n < 2; ++n) {
;                         const int col = u.pn * 256 + bj * 128 + wc * 32 + n * 16 + fq * 4;
;                         const u32x2 raw = *(const u32x2*)(src + (size_t)row * DM + col);
;                         f32x4 x = (f32x4){bflo(raw.x), bfhi(raw.x), bflo(raw.y), bfhi(raw.y)};
;                         if (ln) x = (x - mu) * rs * *(const f32x4*)(g + col) + *(const f32x4*)(b + col);
;                         const u32x2 pz = pk4(x * ALPHA + acc[ai][bj][m][n]);
;                         *(u32x2*)(dst + (size_t)row * DM + col) = pz;
;                         const float z0 = bflo(pz.x), z1 = bfhi(pz.x), z2 = bflo(pz.y), z3 = bfhi(pz.y);
;                         s1 += (z0 + z1) + (z2 + z3); s2 += (z0 * z0 + z1 * z1) + (z2 * z2 + z3 * z3);
;                     }
;                 s1 += __shfl_xor(s1, 16); s2 += __shfl_xor(s2, 16); s1 += __shfl_xor(s1, 32); s2 += __shfl_xor(s2, 32);
;                 if (fq == 0) { float* p = stm_n + (size_t)row * 32 + (u.pn * 4 + wc) * 2; p[0] = s1; p[1] = s2; }
	v_pk_fma_f32 v[40:41], v[40:41], v[56:57], v[52:53]
	s_nop 0
	v_pk_fma_f32 v[28:29], v[40:41], s[72:73], v[28:29] op_sel_hi:[1,0,1]
	s_waitcnt vmcnt(4)
	v_permlane16_swap_b32_e32 v202, v204
	v_permlane16_swap_b32_e32 v203, v205
	s_nop 0
	v_permlane32_swap_b32_e32 v202, v204
	v_permlane32_swap_b32_e32 v203, v205
	v_mov_b64_e32 v[40:41], v[202:203]
	v_pk_fma_f32 v[42:43], v[42:43], v[46:47], v[54:55]
	v_cvt_pk_bf16_f32 v46, v28, v29
	v_pk_fma_f32 v[30:31], v[42:43], s[72:73], v[30:31] op_sel_hi:[1,0,1]
	s_waitcnt lgkmcnt(0)
	v_lshlrev_b32_e32 v3, 16, v40
	v_cvt_pk_bf16_f32 v47, v30, v31
	v_lshlrev_b32_e32 v30, 16, v47
	v_and_b32_e32 v31, 0xffff0000, v47
	v_mul_f32_e32 v28, v30, v30
	v_pk_fma_f32 v[28:29], v[30:31], v[30:31], v[28:29] op_sel_hi:[1,1,0]
	v_lshlrev_b32_e32 v33, 16, v41
	v_and_b32_e32 v28, 0xffff0000, v40
	v_and_b32_e32 v35, 0xffff0000, v41
	v_mov_b64_e32 v[150:151], v[46:47]
	v_lshrrev_b32_e32 v58, 4, v219
	v_lshlrev_b32_e32 v58, 3, v58
	v_mov_b32_e32 v59, v2
	v_permlane32_swap_b32_e32 v148, v150
	v_permlane32_swap_b32_e32 v149, v151
	v_lshl_add_u64 v[58:59], v[58:59], 0, v[44:45]
	s_nop 0
	v_permlane16_swap_b32_e32 v148, v150
	v_permlane16_swap_b32_e32 v149, v151
	global_store_dwordx4 v[58:59], v[148:151], off sc0
	v_sub_f32_e32 v41, v28, v48
	v_sub_f32_e32 v40, v3, v48
	v_sub_f32_e32 v43, v35, v48
	v_sub_f32_e32 v42, v33, v48
	v_pk_mul_f32 v[56:57], v[50:51], v[42:43] op_sel_hi:[0,1]
	v_pk_mul_f32 v[58:59], v[50:51], v[40:41] op_sel_hi:[0,1]
	ds_read_b128 v[40:43], v244 offset:128
	ds_read_b128 v[52:55], v244 offset:384
	v_and_b32_e32 v47, 0xffff0000, v46
	s_waitcnt lgkmcnt(0)
	v_pk_fma_f32 v[40:41], v[40:41], v[58:59], v[52:53]
	v_mov_b64_e32 v[52:53], v[204:205]
	v_pk_fma_f32 v[42:43], v[42:43], v[56:57], v[54:55]
	v_pk_fma_f32 v[24:25], v[40:41], s[72:73], v[24:25] op_sel_hi:[1,0,1]
	v_pk_fma_f32 v[26:27], v[42:43], s[72:73], v[26:27] op_sel_hi:[1,0,1]
	v_cvt_pk_bf16_f32 v24, v24, v25
	v_cvt_pk_bf16_f32 v25, v26, v27
	v_mov_b64_e32 v[148:149], v[24:25]
	v_lshlrev_b32_e32 v40, 16, v24
	v_and_b32_e32 v42, 0xffff0000, v24
	v_lshlrev_b32_e32 v24, 16, v25
	v_and_b32_e32 v26, 0xffff0000, v25
	v_mul_f32_e32 v41, v40, v40
	v_mul_f32_e32 v43, v42, v42
	v_mul_f32_e32 v25, v24, v24
	v_mul_f32_e32 v27, v26, v26
	v_pk_add_f32 v[24:25], v[24:25], v[26:27]
	s_waitcnt lgkmcnt(0)
	v_lshlrev_b32_e32 v3, 16, v52
	v_and_b32_e32 v28, 0xffff0000, v52
	v_lshlrev_b32_e32 v33, 16, v53
	v_and_b32_e32 v35, 0xffff0000, v53
	v_sub_f32_e32 v53, v28, v48
	v_sub_f32_e32 v52, v3, v48
	v_sub_f32_e32 v49, v35, v48
	v_sub_f32_e32 v48, v33, v48
	v_pk_mul_f32 v[48:49], v[50:51], v[48:49] op_sel_hi:[0,1]
	v_pk_mul_f32 v[50:51], v[50:51], v[52:53] op_sel_hi:[0,1]
	ds_read_b128 v[52:55], v244 offset:192
	ds_read_b128 v[56:59], v244 offset:448
	v_mov_b32_e32 v33, v47
	v_mov_b32_e32 v3, v29
	s_waitcnt lgkmcnt(0)
	v_pk_fma_f32 v[50:51], v[52:53], v[50:51], v[56:57]
	s_nop 0
	v_pk_fma_f32 v[20:21], v[50:51], s[72:73], v[20:21] op_sel_hi:[1,0,1]
	v_lshlrev_b32_e32 v51, 16, v46
	v_lshlrev_b32_e32 v50, 16, v38
	v_mov_b32_e32 v35, v51
	v_pk_fma_f32 v[48:49], v[54:55], v[48:49], v[58:59]
	v_pk_mul_f32 v[52:53], v[50:51], v[50:51]
	v_pk_mul_f32 v[54:55], v[34:35], v[34:35]
	v_and_b32_e32 v46, 0xffff0000, v39
	v_pk_mul_f32 v[38:39], v[32:33], v[32:33]
	v_pk_mul_f32 v[56:57], v[46:47], v[46:47]
	v_pk_mov_b32 v[58:59], v[50:51], v[52:53] op_sel:[1,0]
	v_pk_mov_b32 v[54:55], v[46:47], v[54:55] op_sel:[1,0]
	v_pk_add_f32 v[34:35], v[50:51], v[34:35]
	v_pk_add_f32 v[32:33], v[46:47], v[32:33]
	v_pk_fma_f32 v[22:23], v[48:49], s[72:73], v[22:23] op_sel_hi:[1,0,1]
	v_pk_add_f32 v[54:55], v[58:59], v[54:55]
	v_mov_b32_e32 v58, v30
	v_mov_b32_e32 v59, v38
	v_pk_mov_b32 v[30:31], v[30:31], v[56:57] op_sel:[1,0]
	v_mov_b32_e32 v35, v53
	v_mov_b32_e32 v33, v57
	v_cvt_pk_bf16_f32 v20, v20, v21
	v_cvt_pk_bf16_f32 v21, v22, v23
	v_pk_add_f32 v[30:31], v[58:59], v[30:31]
	v_pk_add_f32 v[32:33], v[34:35], v[32:33]
	v_mov_b64_e32 v[150:151], v[20:21]
	v_lshrrev_b32_e32 v152, 4, v219
	v_lshlrev_b32_e32 v152, 3, v152
	v_mov_b32_e32 v153, v2
	v_permlane32_swap_b32_e32 v148, v150
	v_permlane32_swap_b32_e32 v149, v151
	v_lshl_add_u64 v[152:153], v[152:153], 0, v[44:45]
	s_nop 0
	v_permlane16_swap_b32_e32 v148, v150
	v_permlane16_swap_b32_e32 v149, v151
	global_store_dwordx4 v[152:153], v[148:151], off offset:256 sc0
	v_lshlrev_b32_e32 v44, 16, v20
	v_and_b32_e32 v48, 0xffff0000, v20
	v_lshlrev_b32_e32 v20, 16, v21
	v_and_b32_e32 v22, 0xffff0000, v21
	v_pk_add_f32 v[30:31], v[54:55], v[30:31]
	v_pk_add_f32 v[28:29], v[32:33], v[2:3]
	v_mul_f32_e32 v45, v44, v44
	v_mul_f32_e32 v49, v48, v48
	v_mul_f32_e32 v21, v20, v20
	v_mul_f32_e32 v23, v22, v22
	v_pk_add_f32 v[28:29], v[30:31], v[28:29]
	v_pk_add_f32 v[30:31], v[40:41], v[42:43]
	v_pk_add_f32 v[26:27], v[44:45], v[48:49]
	v_pk_add_f32 v[24:25], v[30:31], v[24:25]
	v_pk_add_f32 v[20:21], v[20:21], v[22:23]
	v_pk_add_f32 v[24:25], v[28:29], v[24:25]
	v_pk_add_f32 v[20:21], v[26:27], v[20:21]
	s_nop 0
	v_pk_add_f32 v[20:21], v[24:25], v[20:21]
	ds_bpermute_b32 v22, v181, v20
	ds_bpermute_b32 v23, v181, v21
	s_waitcnt lgkmcnt(0)
	v_pk_add_f32 v[20:21], v[20:21], v[22:23]
	ds_bpermute_b32 v22, v180, v20
	ds_bpermute_b32 v23, v180, v21
	s_and_saveexec_b64 s[0:1], s[40:41]
	s_cbranch_execz .LBB0_2217
	v_lshl_add_u64 v[24:25], s[50:51], 0, v[36:37]
	v_lshl_add_u64 v[24:25], s[60:61], 2, v[24:25]
	s_waitcnt lgkmcnt(0)
	v_pk_add_f32 v[20:21], v[20:21], v[22:23]
	global_store_dwordx2 v[24:25], v[20:21], off
; __device__ __forceinline__ u32x2 pk4(f32x4 v) { u32x2 r; r.x = pk2(v.x, v.y); r.y = pk2(v.z, v.w); return r; }
; __device__ __forceinline__ void stats_main(const float* stm, int row, int fq, float& mu, float& rs) {
;     const f32x4* p = (const f32x4*)(stm + (size_t)row * 32 + fq * 8);
;     const f32x4 a = p[0], b = p[1];
;     float s1 = (a.x + a.z) + (b.x + b.z), s2 = (a.y + a.w) + (b.y + b.w);
;     s1 += __shfl_xor(s1, 16); s2 += __shfl_xor(s2, 16); s1 += __shfl_xor(s1, 32); s2 += __shfl_xor(s2, 32);
;     mu = s1 * (1.f / DM); rs = __builtin_amdgcn_rsqf(fmaxf(s2 * (1.f / DM) - mu * mu, 0.f) + LN_EPS);
; }
;     __device__ __forceinline__ void operator()(const f32x4 (&acc)[2][2][4][2], const pg8::Unit& u, int wr, int wc, int fr, int fq) const {
;     ...
;                 for (int bj = 0; bj < 2; ++bj)
; #pragma unroll
;                     for (int n = 0; n < 2; ++n) {
;                         const int col = u.pn * 256 + bj * 128 + wc * 32 + n * 16 + fq * 4;
;                         const u32x2 raw = *(const u32x2*)(src + (size_t)row * DM + col);
;                         f32x4 x = (f32x4){bflo(raw.x), bfhi(raw.x), bflo(raw.y), bfhi(raw.y)};
;                         if (ln) x = (x - mu) * rs * *(const f32x4*)(g + col) + *(const f32x4*)(b + col);
;                         const u32x2 pz = pk4(x * ALPHA + acc[ai][bj][m][n]);
;                         *(u32x2*)(dst + (size_t)row * DM + col) = pz;
;                         const float z0 = bflo(pz.x), z1 = bfhi(pz.x), z2 = bflo(pz.y), z3 = bfhi(pz.y);
;                         s1 += (z0 + z1) + (z2 + z3); s2 += (z0 * z0 + z1 * z1) + (z2 * z2 + z3 * z3);
;                     }
;                 s1 += __shfl_xor(s1, 16); s2 += __shfl_xor(s2, 16); s1 += __shfl_xor(s1, 32); s2 += __shfl_xor(s2, 32);
;                 if (fq == 0) { float* p = stm_n + (size_t)row * 32 + (u.pn * 4 + wc) * 2; p[0] = s1; p[1] = s2; }
.LBB0_2217:
	s_or_b64 exec, exec, s[0:1]
	v_add_u32_e32 v30, 0xb0, v146
	v_ashrrev_i32_e32 v31, 31, v30
	v_lshlrev_b64 v[20:21], 7, v[30:31]
	v_lshl_add_u64 v[26:27], v[134:135], 0, v[20:21]
	s_waitcnt lgkmcnt(0)
	s_waitcnt vmcnt(3)
	v_mov_b64_e32 v[22:23], v[206:207]
	v_mov_b64_e32 v[24:25], v[208:209]
	s_nop 0
	s_waitcnt vmcnt(2)
	v_mov_b64_e32 v[26:27], v[214:215]
	v_mov_b64_e32 v[28:29], v[216:217]
	s_waitcnt lgkmcnt(0)
	v_pk_add_f32 v[22:23], v[22:23], v[24:25]
	s_waitcnt lgkmcnt(0)
	v_pk_add_f32 v[26:27], v[26:27], v[28:29]
	s_nop 0
	v_pk_add_f32 v[22:23], v[26:27], v[22:23]
	ds_bpermute_b32 v24, v181, v22
	ds_bpermute_b32 v25, v181, v23
	s_waitcnt lgkmcnt(0)
	v_pk_add_f32 v[22:23], v[22:23], v[24:25]
	ds_bpermute_b32 v24, v180, v22
	ds_bpermute_b32 v25, v180, v23
	s_waitcnt lgkmcnt(0)
	v_pk_add_f32 v[22:23], v[22:23], v[24:25]
	s_nop 0
	v_pk_mul_f32 v[32:33], v[22:23], s[82:83] op_sel_hi:[1,0]
	v_lshlrev_b64 v[22:23], 11, v[30:31]
	v_lshl_add_u64 v[22:23], s[70:71], 0, v[22:23]
	v_lshl_add_u64 v[28:29], v[144:145], 1, v[22:23]
	s_waitcnt vmcnt(1)
	v_permlane16_swap_b32_e32 v234, v236
	v_permlane16_swap_b32_e32 v235, v237
	s_nop 0
	v_permlane32_swap_b32_e32 v234, v236
	v_permlane32_swap_b32_e32 v235, v237
	v_mov_b64_e32 v[22:23], v[234:235]
	v_fma_f32 v3, -v32, v32, v33
	v_max_f32_e32 v3, 0, v3
	v_add_f32_e32 v3, 0x3727c5ac, v3
	v_rsq_f32_e32 v34, v3
	s_waitcnt lgkmcnt(0)
	v_lshlrev_b32_e32 v3, 16, v22
	v_and_b32_e32 v22, 0xffff0000, v22
	v_lshlrev_b32_e32 v24, 16, v23
	v_and_b32_e32 v25, 0xffff0000, v23
	v_sub_f32_e32 v23, v22, v32
	v_sub_f32_e32 v22, v3, v32
	v_sub_f32_e32 v25, v25, v32
	v_sub_f32_e32 v24, v24, v32
	v_pk_mul_f32 v[26:27], v[24:25], v[34:35] op_sel_hi:[1,0]
	v_pk_mul_f32 v[30:31], v[22:23], v[34:35] op_sel_hi:[1,0]
	ds_read_b128 v[22:25], v244
	ds_read_b128 v[36:39], v244 offset:256
	s_waitcnt lgkmcnt(0)
	v_pk_fma_f32 v[24:25], v[24:25], v[26:27], v[38:39]
	s_nop 0
	v_pk_fma_f32 v[18:19], v[24:25], s[72:73], v[18:19] op_sel_hi:[1,0,1]
	v_mov_b64_e32 v[24:25], v[236:237]
	v_pk_fma_f32 v[22:23], v[22:23], v[30:31], v[36:37]
	s_waitcnt lgkmcnt(0)
	v_lshlrev_b32_e32 v3, 16, v24
	v_pk_fma_f32 v[16:17], v[22:23], s[72:73], v[16:17] op_sel_hi:[1,0,1]
	v_cvt_pk_bf16_f32 v23, v18, v19
	v_cvt_pk_bf16_f32 v22, v16, v17
	v_and_b32_e32 v17, 0xffff0000, v24
	v_lshlrev_b32_e32 v19, 16, v25
	v_and_b32_e32 v26, 0xffff0000, v25
	v_mov_b64_e32 v[148:149], v[22:23]
	v_sub_f32_e32 v25, v17, v32
	v_sub_f32_e32 v24, v3, v32
	v_sub_f32_e32 v27, v26, v32
	v_sub_f32_e32 v26, v19, v32
	v_pk_mul_f32 v[30:31], v[34:35], v[26:27] op_sel_hi:[0,1]
	v_pk_mul_f32 v[40:41], v[34:35], v[24:25] op_sel_hi:[0,1]
	ds_read_b128 v[24:27], v244 offset:64
	ds_read_b128 v[36:39], v244 offset:320
	v_and_b32_e32 v18, 0xffff0000, v22
	v_lshlrev_b32_e32 v16, 16, v23
	s_waitcnt lgkmcnt(0)
	v_pk_fma_f32 v[24:25], v[24:25], v[40:41], v[36:37]
	s_nop 0
	v_pk_fma_f32 v[12:13], v[24:25], s[72:73], v[12:13] op_sel_hi:[1,0,1]
	s_waitcnt vmcnt(0)
	v_permlane16_swap_b32_e32 v238, v240
	v_permlane16_swap_b32_e32 v239, v241
	s_nop 0
	v_permlane32_swap_b32_e32 v238, v240
	v_permlane32_swap_b32_e32 v239, v241
	v_mov_b64_e32 v[24:25], v[238:239]
	v_pk_fma_f32 v[26:27], v[26:27], v[30:31], v[38:39]
	v_cvt_pk_bf16_f32 v30, v12, v13
	v_pk_fma_f32 v[14:15], v[26:27], s[72:73], v[14:15] op_sel_hi:[1,0,1]
	s_waitcnt lgkmcnt(0)
	v_lshlrev_b32_e32 v3, 16, v24
	v_cvt_pk_bf16_f32 v31, v14, v15
	v_lshlrev_b32_e32 v14, 16, v31
	v_and_b32_e32 v15, 0xffff0000, v31
	v_mul_f32_e32 v12, v14, v14
	v_pk_fma_f32 v[12:13], v[14:15], v[14:15], v[12:13] op_sel_hi:[1,1,0]
	v_lshlrev_b32_e32 v17, 16, v25
	v_and_b32_e32 v12, 0xffff0000, v24
	v_and_b32_e32 v19, 0xffff0000, v25
	v_mov_b64_e32 v[150:151], v[30:31]
	v_lshrrev_b32_e32 v42, 4, v219
	v_lshlrev_b32_e32 v42, 3, v42
	v_mov_b32_e32 v43, v2
	v_permlane32_swap_b32_e32 v148, v150
	v_permlane32_swap_b32_e32 v149, v151
	v_lshl_add_u64 v[42:43], v[42:43], 0, v[28:29]
	s_nop 0
	v_permlane16_swap_b32_e32 v148, v150
	v_permlane16_swap_b32_e32 v149, v151
	global_store_dwordx4 v[42:43], v[148:151], off sc0
	v_sub_f32_e32 v25, v12, v32
	v_sub_f32_e32 v24, v3, v32
	v_sub_f32_e32 v27, v19, v32
	v_sub_f32_e32 v26, v17, v32
	v_pk_mul_f32 v[40:41], v[34:35], v[26:27] op_sel_hi:[0,1]
	v_pk_mul_f32 v[42:43], v[34:35], v[24:25] op_sel_hi:[0,1]
	ds_read_b128 v[24:27], v244 offset:128
	ds_read_b128 v[36:39], v244 offset:384
	v_and_b32_e32 v31, 0xffff0000, v30
	s_waitcnt lgkmcnt(0)
; __device__ __forceinline__ u32x2 pk4(f32x4 v) { u32x2 r; r.x = pk2(v.x, v.y); r.y = pk2(v.z, v.w); return r; }
;     __device__ __forceinline__ void operator()(const f32x4 (&acc)[2][2][4][2], const pg8::Unit& u, int wr, int wc, int fr, int fq) const {
;     ...
;                         const int col = u.pn * 256 + bj * 128 + wc * 32 + n * 16 + fq * 4;
;                         const u32x2 raw = *(const u32x2*)(src + (size_t)row * DM + col);
;                         f32x4 x = (f32x4){bflo(raw.x), bfhi(raw.x), bflo(raw.y), bfhi(raw.y)};
;                         if (ln) x = (x - mu) * rs * *(const f32x4*)(g + col) + *(const f32x4*)(b + col);
;                         const u32x2 pz = pk4(x * ALPHA + acc[ai][bj][m][n]);
;                         *(u32x2*)(dst + (size_t)row * DM + col) = pz;
;                         const float z0 = bflo(pz.x), z1 = bfhi(pz.x), z2 = bflo(pz.y), z3 = bfhi(pz.y);
;                         s1 += (z0 + z1) + (z2 + z3); s2 += (z0 * z0 + z1 * z1) + (z2 * z2 + z3 * z3);
;                     }
;                 s1 += __shfl_xor(s1, 16); s2 += __shfl_xor(s2, 16); s1 += __shfl_xor(s1, 32); s2 += __shfl_xor(s2, 32);
;                 if (fq == 0) { float* p = stm_n + (size_t)row * 32 + (u.pn * 4 + wc) * 2; p[0] = s1; p[1] = s2; }
	v_pk_fma_f32 v[24:25], v[24:25], v[42:43], v[36:37]
	v_mov_b64_e32 v[36:37], v[240:241]
	v_pk_fma_f32 v[26:27], v[26:27], v[40:41], v[38:39]
	v_pk_fma_f32 v[8:9], v[24:25], s[72:73], v[8:9] op_sel_hi:[1,0,1]
	v_pk_fma_f32 v[10:11], v[26:27], s[72:73], v[10:11] op_sel_hi:[1,0,1]
	v_cvt_pk_bf16_f32 v8, v8, v9
	v_cvt_pk_bf16_f32 v9, v10, v11
	v_mov_b64_e32 v[148:149], v[8:9]
	v_lshlrev_b32_e32 v24, 16, v8
	v_and_b32_e32 v26, 0xffff0000, v8
	v_lshlrev_b32_e32 v8, 16, v9
	v_and_b32_e32 v10, 0xffff0000, v9
	v_mul_f32_e32 v25, v24, v24
	v_mul_f32_e32 v27, v26, v26
	v_mul_f32_e32 v9, v8, v8
	v_mul_f32_e32 v11, v10, v10
	v_pk_add_f32 v[8:9], v[8:9], v[10:11]
	s_waitcnt lgkmcnt(0)
	v_lshlrev_b32_e32 v3, 16, v36
	v_and_b32_e32 v12, 0xffff0000, v36
	v_lshlrev_b32_e32 v17, 16, v37
	v_and_b32_e32 v19, 0xffff0000, v37
	v_sub_f32_e32 v37, v12, v32
	v_sub_f32_e32 v36, v3, v32
	v_sub_f32_e32 v33, v19, v32
	v_sub_f32_e32 v32, v17, v32
	v_pk_mul_f32 v[32:33], v[34:35], v[32:33] op_sel_hi:[0,1]
	v_pk_mul_f32 v[34:35], v[34:35], v[36:37] op_sel_hi:[0,1]
	ds_read_b128 v[36:39], v244 offset:192
	ds_read_b128 v[40:43], v244 offset:448
	v_mov_b32_e32 v17, v31
	v_mov_b32_e32 v3, v13
	s_waitcnt lgkmcnt(0)
	v_pk_fma_f32 v[34:35], v[36:37], v[34:35], v[40:41]
	s_nop 0
	v_pk_fma_f32 v[4:5], v[34:35], s[72:73], v[4:5] op_sel_hi:[1,0,1]
	v_lshlrev_b32_e32 v35, 16, v30
	v_lshlrev_b32_e32 v34, 16, v22
	v_mov_b32_e32 v19, v35
	v_pk_fma_f32 v[32:33], v[38:39], v[32:33], v[42:43]
	v_pk_mul_f32 v[36:37], v[34:35], v[34:35]
	v_pk_mul_f32 v[38:39], v[18:19], v[18:19]
	v_and_b32_e32 v30, 0xffff0000, v23
	v_pk_mul_f32 v[22:23], v[16:17], v[16:17]
	v_pk_mul_f32 v[40:41], v[30:31], v[30:31]
	v_pk_mov_b32 v[42:43], v[34:35], v[36:37] op_sel:[1,0]
	v_pk_mov_b32 v[38:39], v[30:31], v[38:39] op_sel:[1,0]
	v_pk_add_f32 v[18:19], v[34:35], v[18:19]
	v_pk_add_f32 v[16:17], v[30:31], v[16:17]
	v_pk_fma_f32 v[6:7], v[32:33], s[72:73], v[6:7] op_sel_hi:[1,0,1]
	v_pk_add_f32 v[38:39], v[42:43], v[38:39]
	v_mov_b32_e32 v42, v14
	v_mov_b32_e32 v43, v22
	v_pk_mov_b32 v[14:15], v[14:15], v[40:41] op_sel:[1,0]
	v_mov_b32_e32 v19, v37
	v_mov_b32_e32 v17, v41
	v_cvt_pk_bf16_f32 v4, v4, v5
	v_cvt_pk_bf16_f32 v5, v6, v7
	v_pk_add_f32 v[14:15], v[42:43], v[14:15]
	v_pk_add_f32 v[16:17], v[18:19], v[16:17]
	v_mov_b64_e32 v[150:151], v[4:5]
	v_lshrrev_b32_e32 v146, 4, v219
	v_lshlrev_b32_e32 v146, 3, v146
	v_mov_b32_e32 v147, v2
	v_permlane32_swap_b32_e32 v148, v150
	v_permlane32_swap_b32_e32 v149, v151
	v_lshl_add_u64 v[146:147], v[146:147], 0, v[28:29]
	s_nop 0
	v_permlane16_swap_b32_e32 v148, v150
	v_permlane16_swap_b32_e32 v149, v151
	global_store_dwordx4 v[146:147], v[148:151], off offset:256 sc0
	v_lshlrev_b32_e32 v28, 16, v4
	v_and_b32_e32 v32, 0xffff0000, v4
	v_lshlrev_b32_e32 v4, 16, v5
	v_and_b32_e32 v6, 0xffff0000, v5
	v_pk_add_f32 v[14:15], v[38:39], v[14:15]
	v_pk_add_f32 v[12:13], v[16:17], v[2:3]
	v_mul_f32_e32 v29, v28, v28
	v_mul_f32_e32 v33, v32, v32
	v_mul_f32_e32 v5, v4, v4
	v_mul_f32_e32 v7, v6, v6
	v_pk_add_f32 v[12:13], v[14:15], v[12:13]
	v_pk_add_f32 v[14:15], v[24:25], v[26:27]
	v_pk_add_f32 v[10:11], v[28:29], v[32:33]
	v_pk_add_f32 v[8:9], v[14:15], v[8:9]
	v_pk_add_f32 v[4:5], v[4:5], v[6:7]
	v_pk_add_f32 v[8:9], v[12:13], v[8:9]
	v_pk_add_f32 v[4:5], v[10:11], v[4:5]
	s_nop 0
	v_pk_add_f32 v[4:5], v[8:9], v[4:5]
	ds_bpermute_b32 v6, v181, v4
	ds_bpermute_b32 v7, v181, v5
	s_waitcnt lgkmcnt(0)
	v_pk_add_f32 v[4:5], v[4:5], v[6:7]
	ds_bpermute_b32 v6, v180, v4
	ds_bpermute_b32 v7, v180, v5
	s_and_saveexec_b64 s[0:1], s[40:41]
	s_cbranch_execz .LBB0_2219
	v_lshl_add_u64 v[8:9], s[50:51], 0, v[20:21]
	v_lshl_add_u64 v[8:9], s[60:61], 2, v[8:9]
	s_waitcnt lgkmcnt(0)
	v_pk_add_f32 v[4:5], v[4:5], v[6:7]
	global_store_dwordx2 v[8:9], v[4:5], off

; __device__ __forceinline__ u32x2 pk4(f32x4 v) { u32x2 r; r.x = pk2(v.x, v.y); r.y = pk2(v.z, v.w); return r; }
; __device__ __forceinline__ void stats_main(const float* stm, int row, int fq, float& mu, float& rs) {
;     const f32x4* p = (const f32x4*)(stm + (size_t)row * 32 + fq * 8);
;     const f32x4 a = p[0], b = p[1];
;     float s1 = (a.x + a.z) + (b.x + b.z), s2 = (a.y + a.w) + (b.y + b.w);
;     s1 += __shfl_xor(s1, 16); s2 += __shfl_xor(s2, 16); s1 += __shfl_xor(s1, 32); s2 += __shfl_xor(s2, 32);
;     mu = s1 * (1.f / DM); rs = __builtin_amdgcn_rsqf(fmaxf(s2 * (1.f / DM) - mu * mu, 0.f) + LN_EPS);
; }
;     __device__ __forceinline__ void operator()(const f32x4 (&acc)[2][2][4][2], const pg8::Unit& u, int wr, int wc, int fr, int fq) const {
;     ...
;                 const int row = u.pm * 256 + ai * 128 + wr * 64 + m * 16 + fr;
;                 float mu = 0.f, rs = 1.f; if (ln) stats_main(stm_p, row, fq, mu, rs);
;                 float s1 = 0.f, s2 = 0.f;
; #pragma unroll
;                 for (int bj = 0; bj < 2; ++bj)
; #pragma unroll
;                     for (int n = 0; n < 2; ++n) {
;                         const int col = u.pn * 256 + bj * 128 + wc * 32 + n * 16 + fq * 4;
;                         const u32x2 raw = *(const u32x2*)(src + (size_t)row * DM + col);
;                         f32x4 x = (f32x4){bflo(raw.x), bfhi(raw.x), bflo(raw.y), bfhi(raw.y)};
;                         if (ln) x = (x - mu) * rs * *(const f32x4*)(g + col) + *(const f32x4*)(b + col);
;                         const u32x2 pz = pk4(x * ALPHA + acc[ai][bj][m][n]);
;                         *(u32x2*)(dst + (size_t)row * DM + col) = pz;
;                         const float z0 = bflo(pz.x), z1 = bfhi(pz.x), z2 = bflo(pz.y), z3 = bfhi(pz.y);
;                         s1 += (z0 + z1) + (z2 + z3); s2 += (z0 * z0 + z1 * z1) + (z2 * z2 + z3 * z3);
.LBB0_2377:
	v_readlane_b32 s70, v250, 30
	v_readlane_b32 s71, v250, 31
	v_and_b32_e32 v244, 0xfffffff0, v166
	v_lshl_add_u32 v244, s22, 8, v244
	v_and_b32_e32 v245, 31, v219
	v_add_u32_e32 v244, v244, v245
	v_lshrrev_b32_e32 v245, 5, v219
	v_lshl_add_u32 v244, v245, 7, v244
	v_lshlrev_b32_e32 v244, 2, v244
	global_load_dword v214, v244, s[46:47]
	global_load_dword v215, v244, s[48:49]
	v_lshl_add_u32 v245, s23, 8, v164
	v_lshl_add_u32 v244, s22, 8, v166
	v_lshlrev_b32_e32 v242, 11, v245
	v_lshl_add_u32 v242, v244, 1, v242
	v_lshlrev_b32_e32 v246, 7, v245
	v_mov_b32_e32 v247, 0
	v_lshlrev_b32_e32 v248, 7, v245
	v_mov_b32_e32 v249, 0
	v_add_u32_e32 v246, 0x1000, v246
	v_add_u32_e32 v248, 0x5000, v248
	v_lshl_add_u64 v[246:247], v[246:247], 0, v[134:135]
	v_lshl_add_u64 v[248:249], v[248:249], 0, v[134:135]
	global_load_dwordx4 v[190:193], v[246:247], off offset:-4080
	global_load_dwordx4 v[194:197], v[246:247], off offset:-4096
	v_lshrrev_b32_e32 v245, 4, v219
	v_lshl_add_u32 v245, v245, 3, v242
	global_load_dwordx4 v[198:201], v245, s[70:71]
	v_lshrrev_b32_e32 v245, 4, v219
	v_lshl_add_u32 v245, v245, 3, v242
	global_load_dwordx4 v[202:205], v245, s[70:71] offset:256
	v_lshrrev_b32_e32 v245, 6, v164
	v_lshrrev_b32_e32 v244, 5, v166
	v_lshl_add_u32 v245, v245, 2, v244
	v_lshlrev_b32_e32 v245, 9, v245
	v_and_b32_e32 v244, 12, v166
	v_lshl_add_u32 v244, v244, 2, v245
	v_add_u32_e32 v244, 0x20000, v244
	v_lshl_add_u32 v245, v219, 2, v245
	v_add_u32_e32 v245, 0x20000, v245
	s_waitcnt vmcnt(5)
	ds_write_b32 v245, v214
	s_waitcnt vmcnt(4)
	ds_write_b32 v245, v215 offset:256
	v_add_u32_e32 v243, 0x8000, v242
	global_load_dwordx4 v[206:209], v[246:247], off offset:-2032
	global_load_dwordx4 v[214:217], v[246:247], off offset:-2048
	v_lshrrev_b32_e32 v245, 4, v219
	v_lshl_add_u32 v245, v245, 3, v243
	global_load_dwordx4 v[234:237], v245, s[70:71]
	v_lshrrev_b32_e32 v245, 4, v219
	v_lshl_add_u32 v245, v245, 3, v243
	global_load_dwordx4 v[238:241], v245, s[70:71] offset:256
	s_waitcnt lgkmcnt(0)
	v_and_b32_e32 v140, 64, v219
	v_lshl_add_u32 v146, s23, 8, v164
	v_xor_b32_e32 v3, 16, v219
	v_add_u32_e32 v140, 64, v140
	v_cmp_lt_i32_e32 vcc, v3, v140
	v_ashrrev_i32_e32 v147, 31, v146
	v_lshlrev_b64 v[148:149], 7, v[146:147]
	v_cndmask_b32_e32 v3, v219, v3, vcc
	v_lshlrev_b32_e32 v181, 2, v3
	v_xor_b32_e32 v3, 32, v219
	v_lshl_add_u64 v[150:151], v[134:135], 0, v[148:149]
	v_cmp_lt_i32_e32 vcc, v3, v140
	s_waitcnt vmcnt(7)
	v_mov_b64_e32 v[140:141], v[190:191]
	v_mov_b64_e32 v[142:143], v[192:193]
	global_load_dwordx4 v[190:193], v[246:247], off offset:16
	s_nop 0
	s_waitcnt vmcnt(7)
	v_mov_b64_e32 v[150:151], v[194:195]
	v_mov_b64_e32 v[152:153], v[196:197]
	global_load_dwordx4 v[194:197], v[246:247], off
	v_cndmask_b32_e32 v3, v219, v3, vcc
	v_lshlrev_b32_e32 v180, 2, v3
	v_readlane_b32 s70, v250, 30
	v_lshl_add_u32 v144, s22, 8, v166
	v_readlane_b32 s71, v250, 31
	v_ashrrev_i32_e32 v145, 31, v144
	s_lshl_b32 s0, s22, 3
	v_readlane_b32 s1, v252, 30
	s_or_b32 s68, s0, s1
	s_ashr_i32 s69, s68, 31
	s_waitcnt lgkmcnt(0)
	v_pk_add_f32 v[140:141], v[140:141], v[142:143]
	v_pk_add_f32 v[150:151], v[150:151], v[152:153]
	s_nop 0
	v_pk_add_f32 v[140:141], v[150:151], v[140:141]
	ds_bpermute_b32 v142, v181, v140
	ds_bpermute_b32 v143, v181, v141
	s_waitcnt lgkmcnt(0)
	v_pk_add_f32 v[140:141], v[140:141], v[142:143]
	ds_bpermute_b32 v142, v180, v140
	ds_bpermute_b32 v143, v180, v141
	s_waitcnt lgkmcnt(0)
	v_pk_add_f32 v[140:141], v[140:141], v[142:143]
	s_nop 0
	v_pk_mul_f32 v[160:161], v[140:141], s[82:83] op_sel_hi:[1,0]
	v_lshlrev_b64 v[140:141], 11, v[146:147]
	v_lshl_add_u64 v[140:141], s[70:71], 0, v[140:141]
	v_lshl_add_u64 v[152:153], v[144:145], 1, v[140:141]
	v_add_u32_e32 v243, 0x10000, v242
	s_waitcnt vmcnt(7)
	v_permlane16_swap_b32_e32 v198, v200
	v_permlane16_swap_b32_e32 v199, v201
	s_nop 0
	v_permlane32_swap_b32_e32 v198, v200
	v_permlane32_swap_b32_e32 v199, v201
	v_mov_b64_e32 v[140:141], v[198:199]
	v_fma_f32 v3, -v160, v160, v161
	v_max_f32_e32 v3, 0, v3
	v_add_f32_e32 v3, 0x3727c5ac, v3
	v_rsq_f32_e32 v162, v3
	s_waitcnt lgkmcnt(0)
	v_lshlrev_b32_e32 v142, 16, v141
	v_and_b32_e32 v143, 0xffff0000, v141
	v_lshlrev_b32_e32 v3, 16, v140
	v_and_b32_e32 v140, 0xffff0000, v140
	v_sub_f32_e32 v143, v143, v160
	v_sub_f32_e32 v142, v142, v160
	v_sub_f32_e32 v141, v140, v160
	v_sub_f32_e32 v140, v3, v160
	v_pk_mul_f32 v[150:151], v[142:143], v[162:163] op_sel_hi:[1,0]
	v_lshlrev_b64 v[142:143], 2, v[144:145]
	v_pk_mul_f32 v[158:159], v[140:141], v[162:163] op_sel_hi:[1,0]
	v_lshl_add_u64 v[140:141], s[46:47], 0, v[142:143]
	v_lshl_add_u64 v[142:143], s[48:49], 0, v[142:143]
	ds_read_b128 v[154:157], v244
	ds_read_b128 v[182:185], v244 offset:256
	s_waitcnt lgkmcnt(0)
	v_pk_fma_f32 v[154:155], v[154:155], v[158:159], v[182:183]
	s_nop 0
	v_pk_fma_f32 v[128:129], v[154:155], s[72:73], v[128:129] op_sel_hi:[1,0,1]
	v_mov_b64_e32 v[154:155], v[200:201]
	v_lshrrev_b32_e32 v245, 4, v219
	v_lshl_add_u32 v245, v245, 3, v243
	global_load_dwordx4 v[198:201], v245, s[70:71]
	v_pk_fma_f32 v[150:151], v[156:157], v[150:151], v[184:185]
	s_waitcnt lgkmcnt(0)
	v_lshlrev_b32_e32 v3, 16, v154
	v_pk_fma_f32 v[130:131], v[150:151], s[72:73], v[130:131] op_sel_hi:[1,0,1]
	v_cvt_pk_bf16_f32 v150, v128, v129
	v_cvt_pk_bf16_f32 v151, v130, v131
	v_and_b32_e32 v129, 0xffff0000, v154
	v_lshlrev_b32_e32 v131, 16, v155
	v_and_b32_e32 v147, 0xffff0000, v155
	global_store_dwordx2 v[152:153], v[150:151], off
	v_sub_f32_e32 v155, v129, v160
	v_sub_f32_e32 v154, v3, v160
	v_sub_f32_e32 v157, v147, v160
	v_sub_f32_e32 v156, v131, v160
	v_pk_mul_f32 v[158:159], v[162:163], v[156:157] op_sel_hi:[0,1]
	v_pk_mul_f32 v[168:169], v[162:163], v[154:155] op_sel_hi:[0,1]
	ds_read_b128 v[154:157], v244 offset:64
	ds_read_b128 v[182:185], v244 offset:320
	v_and_b32_e32 v130, 0xffff0000, v150
	v_lshlrev_b32_e32 v128, 16, v151
	s_waitcnt lgkmcnt(0)
; __device__ __forceinline__ u32x2 pk4(f32x4 v) { u32x2 r; r.x = pk2(v.x, v.y); r.y = pk2(v.z, v.w); return r; }
;     __device__ __forceinline__ void operator()(const f32x4 (&acc)[2][2][4][2], const pg8::Unit& u, int wr, int wc, int fr, int fq) const {
;     ...
;                 for (int bj = 0; bj < 2; ++bj)
; #pragma unroll
;                     for (int n = 0; n < 2; ++n) {
;                         const int col = u.pn * 256 + bj * 128 + wc * 32 + n * 16 + fq * 4;
;                         const u32x2 raw = *(const u32x2*)(src + (size_t)row * DM + col);
;                         f32x4 x = (f32x4){bflo(raw.x), bfhi(raw.x), bflo(raw.y), bfhi(raw.y)};
;                         if (ln) x = (x - mu) * rs * *(const f32x4*)(g + col) + *(const f32x4*)(b + col);
;                         const u32x2 pz = pk4(x * ALPHA + acc[ai][bj][m][n]);
;                         *(u32x2*)(dst + (size_t)row * DM + col) = pz;
;                         const float z0 = bflo(pz.x), z1 = bfhi(pz.x), z2 = bflo(pz.y), z3 = bfhi(pz.y);
;                         s1 += (z0 + z1) + (z2 + z3); s2 += (z0 * z0 + z1 * z1) + (z2 * z2 + z3 * z3);
;                     }
;                 s1 += __shfl_xor(s1, 16); s2 += __shfl_xor(s2, 16); s1 += __shfl_xor(s1, 32); s2 += __shfl_xor(s2, 32);
;                 if (fq == 0) { float* p = stm_n + (size_t)row * 32 + (u.pn * 4 + wc) * 2; p[0] = s1; p[1] = s2; }
	v_pk_fma_f32 v[154:155], v[154:155], v[168:169], v[182:183]
	s_nop 0
	v_pk_fma_f32 v[124:125], v[154:155], s[72:73], v[124:125] op_sel_hi:[1,0,1]
	s_waitcnt vmcnt(7)
	v_permlane16_swap_b32_e32 v202, v204
	v_permlane16_swap_b32_e32 v203, v205
	s_nop 0
	v_permlane32_swap_b32_e32 v202, v204
	v_permlane32_swap_b32_e32 v203, v205
	v_mov_b64_e32 v[154:155], v[202:203]
	v_pk_fma_f32 v[156:157], v[156:157], v[158:159], v[184:185]
	v_cvt_pk_bf16_f32 v158, v124, v125
	v_pk_fma_f32 v[126:127], v[156:157], s[72:73], v[126:127] op_sel_hi:[1,0,1]
	s_waitcnt lgkmcnt(0)
	v_lshlrev_b32_e32 v3, 16, v154
	v_cvt_pk_bf16_f32 v159, v126, v127
	v_lshlrev_b32_e32 v126, 16, v159
	v_and_b32_e32 v127, 0xffff0000, v159
	v_mul_f32_e32 v124, v126, v126
	v_pk_fma_f32 v[124:125], v[126:127], v[126:127], v[124:125] op_sel_hi:[1,1,0]
	v_lshlrev_b32_e32 v129, 16, v155
	v_and_b32_e32 v124, 0xffff0000, v154
	v_and_b32_e32 v131, 0xffff0000, v155
	global_store_dwordx2 v[152:153], v[158:159], off offset:32
	v_sub_f32_e32 v155, v124, v160
	v_sub_f32_e32 v154, v3, v160
	v_sub_f32_e32 v157, v131, v160
	v_sub_f32_e32 v156, v129, v160
	v_pk_mul_f32 v[168:169], v[162:163], v[156:157] op_sel_hi:[0,1]
	v_pk_mul_f32 v[186:187], v[162:163], v[154:155] op_sel_hi:[0,1]
	ds_read_b128 v[154:157], v244 offset:128
	ds_read_b128 v[182:185], v244 offset:384
	v_and_b32_e32 v159, 0xffff0000, v158
	s_waitcnt lgkmcnt(0)
	v_pk_fma_f32 v[154:155], v[154:155], v[186:187], v[182:183]
	v_pk_fma_f32 v[156:157], v[156:157], v[168:169], v[184:185]
	v_pk_fma_f32 v[120:121], v[154:155], s[72:73], v[120:121] op_sel_hi:[1,0,1]
	v_pk_fma_f32 v[122:123], v[156:157], s[72:73], v[122:123] op_sel_hi:[1,0,1]
	v_mov_b64_e32 v[168:169], v[204:205]
	v_lshrrev_b32_e32 v245, 4, v219
	v_lshl_add_u32 v245, v245, 3, v243
	global_load_dwordx4 v[202:205], v245, s[70:71] offset:256
	v_cvt_pk_bf16_f32 v120, v120, v121
	v_cvt_pk_bf16_f32 v121, v122, v123
	global_store_dwordx2 v[152:153], v[120:121], off offset:256
	ds_read_b128 v[182:185], v244 offset:192
	ds_read_b128 v[186:189], v244 offset:448
	v_lshlrev_b32_e32 v154, 16, v120
	v_and_b32_e32 v156, 0xffff0000, v120
	v_lshlrev_b32_e32 v120, 16, v121
	v_and_b32_e32 v122, 0xffff0000, v121
	v_mul_f32_e32 v155, v154, v154
	v_mul_f32_e32 v157, v156, v156
	v_mul_f32_e32 v121, v120, v120
	v_mul_f32_e32 v123, v122, v122
	v_pk_add_f32 v[120:121], v[120:121], v[122:123]
	s_waitcnt lgkmcnt(0)
	v_lshlrev_b32_e32 v3, 16, v168
	v_and_b32_e32 v124, 0xffff0000, v168
	v_lshlrev_b32_e32 v129, 16, v169
	v_and_b32_e32 v131, 0xffff0000, v169
	v_sub_f32_e32 v169, v124, v160
	v_sub_f32_e32 v168, v3, v160
	v_sub_f32_e32 v161, v131, v160
	v_sub_f32_e32 v160, v129, v160
	v_pk_mul_f32 v[160:161], v[162:163], v[160:161] op_sel_hi:[0,1]
	v_pk_mul_f32 v[162:163], v[162:163], v[168:169] op_sel_hi:[0,1]
	s_waitcnt lgkmcnt(0)
	v_pk_fma_f32 v[162:163], v[182:183], v[162:163], v[186:187]
	v_mov_b32_e32 v129, v159
	v_pk_fma_f32 v[116:117], v[162:163], s[72:73], v[116:117] op_sel_hi:[1,0,1]
	v_lshlrev_b32_e32 v163, 16, v158
	v_lshlrev_b32_e32 v162, 16, v150
	v_mov_b32_e32 v131, v163
	v_pk_mul_f32 v[168:169], v[162:163], v[162:163]
	v_pk_mul_f32 v[182:183], v[130:131], v[130:131]
	v_and_b32_e32 v158, 0xffff0000, v151
	v_pk_fma_f32 v[160:161], v[184:185], v[160:161], v[188:189]
	v_pk_mul_f32 v[150:151], v[128:129], v[128:129]
	v_pk_mul_f32 v[184:185], v[158:159], v[158:159]
	v_pk_mov_b32 v[186:187], v[162:163], v[168:169] op_sel:[1,0]
	v_pk_mov_b32 v[182:183], v[158:159], v[182:183] op_sel:[1,0]
	v_pk_add_f32 v[130:131], v[162:163], v[130:131]
	v_pk_add_f32 v[128:129], v[158:159], v[128:129]
	v_pk_fma_f32 v[118:119], v[160:161], s[72:73], v[118:119] op_sel_hi:[1,0,1]
	v_pk_add_f32 v[182:183], v[186:187], v[182:183]
	v_mov_b32_e32 v186, v126
	v_mov_b32_e32 v187, v150
	v_pk_mov_b32 v[126:127], v[126:127], v[184:185] op_sel:[1,0]
	v_mov_b32_e32 v131, v169
	v_mov_b32_e32 v129, v185
	v_cvt_pk_bf16_f32 v116, v116, v117
	v_cvt_pk_bf16_f32 v117, v118, v119
	v_pk_add_f32 v[126:127], v[186:187], v[126:127]
	v_pk_add_f32 v[128:129], v[130:131], v[128:129]
	v_mov_b32_e32 v3, v125
	global_store_dwordx2 v[152:153], v[116:117], off offset:288
	v_lshlrev_b32_e32 v152, 16, v116
	v_and_b32_e32 v160, 0xffff0000, v116
	v_lshlrev_b32_e32 v116, 16, v117
	v_and_b32_e32 v118, 0xffff0000, v117
	v_pk_add_f32 v[126:127], v[182:183], v[126:127]
	v_pk_add_f32 v[124:125], v[128:129], v[2:3]
	v_mul_f32_e32 v153, v152, v152
	v_mul_f32_e32 v161, v160, v160
	v_mul_f32_e32 v117, v116, v116
	v_mul_f32_e32 v119, v118, v118
	v_pk_add_f32 v[124:125], v[126:127], v[124:125]
	v_pk_add_f32 v[126:127], v[154:155], v[156:157]
	v_pk_add_f32 v[122:123], v[152:153], v[160:161]
	v_pk_add_f32 v[120:121], v[126:127], v[120:121]
	v_pk_add_f32 v[116:117], v[116:117], v[118:119]
	v_pk_add_f32 v[120:121], v[124:125], v[120:121]
	v_pk_add_f32 v[116:117], v[122:123], v[116:117]
	s_nop 0
	v_pk_add_f32 v[116:117], v[120:121], v[116:117]
	ds_bpermute_b32 v118, v181, v116
	ds_bpermute_b32 v119, v181, v117
	s_waitcnt lgkmcnt(0)
	v_pk_add_f32 v[116:117], v[116:117], v[118:119]
	ds_bpermute_b32 v118, v180, v116
	ds_bpermute_b32 v119, v180, v117
	s_and_saveexec_b64 s[0:1], s[40:41]
	s_cbranch_execz .LBB0_2379
	v_lshl_add_u64 v[120:121], s[52:53], 0, v[148:149]
	v_lshl_add_u64 v[120:121], s[68:69], 2, v[120:121]
	s_waitcnt lgkmcnt(0)
	v_pk_add_f32 v[116:117], v[116:117], v[118:119]
	global_store_dwordx2 v[120:121], v[116:117], off
; __device__ __forceinline__ u32x2 pk4(f32x4 v) { u32x2 r; r.x = pk2(v.x, v.y); r.y = pk2(v.z, v.w); return r; }
; __device__ __forceinline__ void stats_main(const float* stm, int row, int fq, float& mu, float& rs) {
;     const f32x4* p = (const f32x4*)(stm + (size_t)row * 32 + fq * 8);
;     const f32x4 a = p[0], b = p[1];
;     float s1 = (a.x + a.z) + (b.x + b.z), s2 = (a.y + a.w) + (b.y + b.w);
;     s1 += __shfl_xor(s1, 16); s2 += __shfl_xor(s2, 16); s1 += __shfl_xor(s1, 32); s2 += __shfl_xor(s2, 32);
;     mu = s1 * (1.f / DM); rs = __builtin_amdgcn_rsqf(fmaxf(s2 * (1.f / DM) - mu * mu, 0.f) + LN_EPS);
; }
;     __device__ __forceinline__ void operator()(const f32x4 (&acc)[2][2][4][2], const pg8::Unit& u, int wr, int wc, int fr, int fq) const {
;     ...
;                 const int row = u.pm * 256 + ai * 128 + wr * 64 + m * 16 + fr;
;                 float mu = 0.f, rs = 1.f; if (ln) stats_main(stm_p, row, fq, mu, rs);
;                 float s1 = 0.f, s2 = 0.f;
; #pragma unroll
;                 for (int bj = 0; bj < 2; ++bj)
; #pragma unroll
;                     for (int n = 0; n < 2; ++n) {
;                         const int col = u.pn * 256 + bj * 128 + wc * 32 + n * 16 + fq * 4;
;                         const u32x2 raw = *(const u32x2*)(src + (size_t)row * DM + col);
;                         f32x4 x = (f32x4){bflo(raw.x), bfhi(raw.x), bflo(raw.y), bfhi(raw.y)};
;                         if (ln) x = (x - mu) * rs * *(const f32x4*)(g + col) + *(const f32x4*)(b + col);
;                         const u32x2 pz = pk4(x * ALPHA + acc[ai][bj][m][n]);
;                         *(u32x2*)(dst + (size_t)row * DM + col) = pz;
;                         const float z0 = bflo(pz.x), z1 = bfhi(pz.x), z2 = bflo(pz.y), z3 = bfhi(pz.y);
;                         s1 += (z0 + z1) + (z2 + z3); s2 += (z0 * z0 + z1 * z1) + (z2 * z2 + z3 * z3);
;                     }
;                 s1 += __shfl_xor(s1, 16); s2 += __shfl_xor(s2, 16); s1 += __shfl_xor(s1, 32); s2 += __shfl_xor(s2, 32);
;                 if (fq == 0) { float* p = stm_n + (size_t)row * 32 + (u.pn * 4 + wc) * 2; p[0] = s1; p[1] = s2; }
.LBB0_2379:
	s_or_b64 exec, exec, s[0:1]
	v_or_b32_e32 v126, 16, v146
	v_ashrrev_i32_e32 v127, 31, v126
	v_lshlrev_b64 v[116:117], 7, v[126:127]
	v_lshl_add_u64 v[122:123], v[134:135], 0, v[116:117]
	s_waitcnt lgkmcnt(0)
	s_waitcnt vmcnt(7)
	v_mov_b64_e32 v[118:119], v[206:207]
	v_mov_b64_e32 v[120:121], v[208:209]
	global_load_dwordx4 v[206:209], v[246:247], off offset:2064
	s_nop 0
	s_waitcnt vmcnt(7)
	v_mov_b64_e32 v[122:123], v[214:215]
	v_mov_b64_e32 v[124:125], v[216:217]
	global_load_dwordx4 v[214:217], v[246:247], off offset:2048
	s_waitcnt lgkmcnt(0)
	v_pk_add_f32 v[118:119], v[118:119], v[120:121]
	s_waitcnt lgkmcnt(0)
	v_pk_add_f32 v[122:123], v[122:123], v[124:125]
	s_nop 0
	v_pk_add_f32 v[118:119], v[122:123], v[118:119]
	ds_bpermute_b32 v120, v181, v118
	ds_bpermute_b32 v121, v181, v119
	s_waitcnt lgkmcnt(0)
	v_pk_add_f32 v[118:119], v[118:119], v[120:121]
	ds_bpermute_b32 v120, v180, v118
	ds_bpermute_b32 v121, v180, v119
	s_waitcnt lgkmcnt(0)
	v_pk_add_f32 v[118:119], v[118:119], v[120:121]
	s_nop 0
	v_pk_mul_f32 v[128:129], v[118:119], s[82:83] op_sel_hi:[1,0]
	v_lshlrev_b64 v[118:119], 11, v[126:127]
	v_lshl_add_u64 v[118:119], s[70:71], 0, v[118:119]
	v_lshl_add_u64 v[124:125], v[144:145], 1, v[118:119]
	v_add_u32_e32 v243, 0x18000, v242
	s_waitcnt vmcnt(7)
	v_permlane16_swap_b32_e32 v234, v236
	v_permlane16_swap_b32_e32 v235, v237
	s_nop 0
	v_permlane32_swap_b32_e32 v234, v236
	v_permlane32_swap_b32_e32 v235, v237
	v_mov_b64_e32 v[118:119], v[234:235]
	v_fma_f32 v3, -v128, v128, v129
	v_max_f32_e32 v3, 0, v3
	v_add_f32_e32 v3, 0x3727c5ac, v3
	v_rsq_f32_e32 v130, v3
	s_waitcnt lgkmcnt(0)
	v_lshlrev_b32_e32 v3, 16, v118
	v_and_b32_e32 v118, 0xffff0000, v118
	v_lshlrev_b32_e32 v120, 16, v119
	v_and_b32_e32 v121, 0xffff0000, v119
	v_sub_f32_e32 v119, v118, v128
	v_sub_f32_e32 v118, v3, v128
	v_sub_f32_e32 v121, v121, v128
	v_sub_f32_e32 v120, v120, v128
	v_pk_mul_f32 v[122:123], v[120:121], v[130:131] op_sel_hi:[1,0]
	v_pk_mul_f32 v[126:127], v[118:119], v[130:131] op_sel_hi:[1,0]
	ds_read_b128 v[118:121], v244
	ds_read_b128 v[148:151], v244 offset:256
	s_waitcnt lgkmcnt(0)
	v_pk_fma_f32 v[120:121], v[120:121], v[122:123], v[150:151]
	s_nop 0
	v_pk_fma_f32 v[114:115], v[120:121], s[72:73], v[114:115] op_sel_hi:[1,0,1]
	v_mov_b64_e32 v[120:121], v[236:237]
	v_lshrrev_b32_e32 v245, 4, v219
	v_lshl_add_u32 v245, v245, 3, v243
	global_load_dwordx4 v[234:237], v245, s[70:71]
	v_pk_fma_f32 v[118:119], v[118:119], v[126:127], v[148:149]
	s_waitcnt lgkmcnt(0)
	v_lshlrev_b32_e32 v3, 16, v120
	v_pk_fma_f32 v[112:113], v[118:119], s[72:73], v[112:113] op_sel_hi:[1,0,1]
	v_cvt_pk_bf16_f32 v119, v114, v115
	v_cvt_pk_bf16_f32 v118, v112, v113
	v_and_b32_e32 v113, 0xffff0000, v120
	v_lshlrev_b32_e32 v115, 16, v121
	v_and_b32_e32 v122, 0xffff0000, v121
	global_store_dwordx2 v[124:125], v[118:119], off
	v_sub_f32_e32 v121, v113, v128
	v_sub_f32_e32 v120, v3, v128
	v_sub_f32_e32 v123, v122, v128
	v_sub_f32_e32 v122, v115, v128
	v_pk_mul_f32 v[126:127], v[130:131], v[122:123] op_sel_hi:[0,1]
	v_pk_mul_f32 v[152:153], v[130:131], v[120:121] op_sel_hi:[0,1]
	ds_read_b128 v[120:123], v244 offset:64
	ds_read_b128 v[148:151], v244 offset:320
	v_and_b32_e32 v114, 0xffff0000, v118
	v_lshlrev_b32_e32 v112, 16, v119
	s_waitcnt lgkmcnt(0)
	v_pk_fma_f32 v[120:121], v[120:121], v[152:153], v[148:149]
	s_nop 0
	v_pk_fma_f32 v[108:109], v[120:121], s[72:73], v[108:109] op_sel_hi:[1,0,1]
	s_waitcnt vmcnt(7)
	v_permlane16_swap_b32_e32 v238, v240
	v_permlane16_swap_b32_e32 v239, v241
	s_nop 0
	v_permlane32_swap_b32_e32 v238, v240
	v_permlane32_swap_b32_e32 v239, v241
	v_mov_b64_e32 v[120:121], v[238:239]
	v_pk_fma_f32 v[122:123], v[122:123], v[126:127], v[150:151]
	v_cvt_pk_bf16_f32 v126, v108, v109
	v_pk_fma_f32 v[110:111], v[122:123], s[72:73], v[110:111] op_sel_hi:[1,0,1]
	s_waitcnt lgkmcnt(0)
	v_lshlrev_b32_e32 v3, 16, v120
	v_cvt_pk_bf16_f32 v127, v110, v111
	v_lshlrev_b32_e32 v110, 16, v127
	v_and_b32_e32 v111, 0xffff0000, v127
	v_mul_f32_e32 v108, v110, v110
	v_pk_fma_f32 v[108:109], v[110:111], v[110:111], v[108:109] op_sel_hi:[1,1,0]
	v_lshlrev_b32_e32 v113, 16, v121
	v_and_b32_e32 v108, 0xffff0000, v120
	v_and_b32_e32 v115, 0xffff0000, v121
	global_store_dwordx2 v[124:125], v[126:127], off offset:32
	v_sub_f32_e32 v121, v108, v128
	v_sub_f32_e32 v120, v3, v128
	v_sub_f32_e32 v123, v115, v128
	v_sub_f32_e32 v122, v113, v128
	v_pk_mul_f32 v[152:153], v[130:131], v[122:123] op_sel_hi:[0,1]
	v_pk_mul_f32 v[154:155], v[130:131], v[120:121] op_sel_hi:[0,1]
	ds_read_b128 v[120:123], v244 offset:128
	ds_read_b128 v[148:151], v244 offset:384
	v_and_b32_e32 v127, 0xffff0000, v126
	s_waitcnt lgkmcnt(0)
	v_pk_fma_f32 v[120:121], v[120:121], v[154:155], v[148:149]
	v_mov_b64_e32 v[148:149], v[240:241]
	v_lshrrev_b32_e32 v245, 4, v219
	v_lshl_add_u32 v245, v245, 3, v243
	global_load_dwordx4 v[238:241], v245, s[70:71] offset:256
	v_pk_fma_f32 v[122:123], v[122:123], v[152:153], v[150:151]
	v_pk_fma_f32 v[104:105], v[120:121], s[72:73], v[104:105] op_sel_hi:[1,0,1]
	v_pk_fma_f32 v[106:107], v[122:123], s[72:73], v[106:107] op_sel_hi:[1,0,1]
	v_cvt_pk_bf16_f32 v104, v104, v105
	v_cvt_pk_bf16_f32 v105, v106, v107
	global_store_dwordx2 v[124:125], v[104:105], off offset:256
	v_lshlrev_b32_e32 v120, 16, v104
	v_and_b32_e32 v122, 0xffff0000, v104
	v_lshlrev_b32_e32 v104, 16, v105
	v_and_b32_e32 v106, 0xffff0000, v105
	v_mul_f32_e32 v121, v120, v120
	v_mul_f32_e32 v123, v122, v122
	v_mul_f32_e32 v105, v104, v104
	v_mul_f32_e32 v107, v106, v106
	v_pk_add_f32 v[104:105], v[104:105], v[106:107]
	s_waitcnt lgkmcnt(0)
; __device__ __forceinline__ void stats_main(const float* stm, int row, int fq, float& mu, float& rs) {
;     const f32x4* p = (const f32x4*)(stm + (size_t)row * 32 + fq * 8);
;     const f32x4 a = p[0], b = p[1];
;     float s1 = (a.x + a.z) + (b.x + b.z), s2 = (a.y + a.w) + (b.y + b.w);
;     s1 += __shfl_xor(s1, 16); s2 += __shfl_xor(s2, 16); s1 += __shfl_xor(s1, 32); s2 += __shfl_xor(s2, 32);
;     mu = s1 * (1.f / DM); rs = __builtin_amdgcn_rsqf(fmaxf(s2 * (1.f / DM) - mu * mu, 0.f) + LN_EPS);
; }
;     __device__ __forceinline__ void operator()(const f32x4 (&acc)[2][2][4][2], const pg8::Unit& u, int wr, int wc, int fr, int fq) const {
;     ...
;                 for (int bj = 0; bj < 2; ++bj)
; #pragma unroll
;                     for (int n = 0; n < 2; ++n) {
;                         const int col = u.pn * 256 + bj * 128 + wc * 32 + n * 16 + fq * 4;
;                         const u32x2 raw = *(const u32x2*)(src + (size_t)row * DM + col);
;     ...
;                         const float z0 = bflo(pz.x), z1 = bfhi(pz.x), z2 = bflo(pz.y), z3 = bfhi(pz.y);
;                         s1 += (z0 + z1) + (z2 + z3); s2 += (z0 * z0 + z1 * z1) + (z2 * z2 + z3 * z3);
;                     }
;                 s1 += __shfl_xor(s1, 16); s2 += __shfl_xor(s2, 16); s1 += __shfl_xor(s1, 32); s2 += __shfl_xor(s2, 32);
;                 if (fq == 0) { float* p = stm_n + (size_t)row * 32 + (u.pn * 4 + wc) * 2; p[0] = s1; p[1] = s2; }
	v_lshlrev_b32_e32 v3, 16, v148
	v_and_b32_e32 v108, 0xffff0000, v148
	v_lshlrev_b32_e32 v113, 16, v149
	v_and_b32_e32 v115, 0xffff0000, v149
	v_sub_f32_e32 v149, v108, v128
	v_sub_f32_e32 v148, v3, v128
	v_sub_f32_e32 v129, v115, v128
	v_sub_f32_e32 v128, v113, v128
	v_pk_mul_f32 v[128:129], v[130:131], v[128:129] op_sel_hi:[0,1]
	v_pk_mul_f32 v[130:131], v[130:131], v[148:149] op_sel_hi:[0,1]
	ds_read_b128 v[148:151], v244 offset:192
	ds_read_b128 v[152:155], v244 offset:448
	v_mov_b32_e32 v113, v127
	v_mov_b32_e32 v3, v109
	s_waitcnt lgkmcnt(0)
	v_pk_fma_f32 v[130:131], v[148:149], v[130:131], v[152:153]
	s_nop 0
	v_pk_fma_f32 v[100:101], v[130:131], s[72:73], v[100:101] op_sel_hi:[1,0,1]
	v_lshlrev_b32_e32 v131, 16, v126
	v_lshlrev_b32_e32 v130, 16, v118
	v_mov_b32_e32 v115, v131
	v_pk_fma_f32 v[128:129], v[150:151], v[128:129], v[154:155]
	v_pk_mul_f32 v[148:149], v[130:131], v[130:131]
	v_pk_mul_f32 v[150:151], v[114:115], v[114:115]
	v_and_b32_e32 v126, 0xffff0000, v119
	v_pk_mul_f32 v[118:119], v[112:113], v[112:113]
	v_pk_mul_f32 v[152:153], v[126:127], v[126:127]
	v_pk_mov_b32 v[154:155], v[130:131], v[148:149] op_sel:[1,0]
	v_pk_mov_b32 v[150:151], v[126:127], v[150:151] op_sel:[1,0]
	v_pk_add_f32 v[114:115], v[130:131], v[114:115]
	v_pk_add_f32 v[112:113], v[126:127], v[112:113]
	v_pk_fma_f32 v[102:103], v[128:129], s[72:73], v[102:103] op_sel_hi:[1,0,1]
	v_pk_add_f32 v[150:151], v[154:155], v[150:151]
	v_mov_b32_e32 v154, v110
	v_mov_b32_e32 v155, v118
	v_pk_mov_b32 v[110:111], v[110:111], v[152:153] op_sel:[1,0]
	v_mov_b32_e32 v115, v149
	v_mov_b32_e32 v113, v153
	v_cvt_pk_bf16_f32 v100, v100, v101
	v_cvt_pk_bf16_f32 v101, v102, v103
	v_pk_add_f32 v[110:111], v[154:155], v[110:111]
	v_pk_add_f32 v[112:113], v[114:115], v[112:113]
	global_store_dwordx2 v[124:125], v[100:101], off offset:288
	v_lshlrev_b32_e32 v124, 16, v100
	v_and_b32_e32 v128, 0xffff0000, v100
	v_lshlrev_b32_e32 v100, 16, v101
	v_and_b32_e32 v102, 0xffff0000, v101
	v_pk_add_f32 v[110:111], v[150:151], v[110:111]
	v_pk_add_f32 v[108:109], v[112:113], v[2:3]
	v_mul_f32_e32 v125, v124, v124
	v_mul_f32_e32 v129, v128, v128
	v_mul_f32_e32 v101, v100, v100
	v_mul_f32_e32 v103, v102, v102
	v_pk_add_f32 v[108:109], v[110:111], v[108:109]
	v_pk_add_f32 v[110:111], v[120:121], v[122:123]
	v_pk_add_f32 v[106:107], v[124:125], v[128:129]
	v_pk_add_f32 v[104:105], v[110:111], v[104:105]
	v_pk_add_f32 v[100:101], v[100:101], v[102:103]
	v_pk_add_f32 v[104:105], v[108:109], v[104:105]
	v_pk_add_f32 v[100:101], v[106:107], v[100:101]
	s_nop 0
	v_pk_add_f32 v[100:101], v[104:105], v[100:101]
	ds_bpermute_b32 v102, v181, v100
	ds_bpermute_b32 v103, v181, v101
	s_waitcnt lgkmcnt(0)
	v_pk_add_f32 v[100:101], v[100:101], v[102:103]
	ds_bpermute_b32 v102, v180, v100
	ds_bpermute_b32 v103, v180, v101
	s_and_saveexec_b64 s[0:1], s[40:41]
	s_cbranch_execz .LBB0_2381
	v_lshl_add_u64 v[104:105], s[52:53], 0, v[116:117]
	v_lshl_add_u64 v[104:105], s[68:69], 2, v[104:105]
	s_waitcnt lgkmcnt(0)
	v_pk_add_f32 v[100:101], v[100:101], v[102:103]
	global_store_dwordx2 v[104:105], v[100:101], off
.LBB0_2381:
	s_or_b64 exec, exec, s[0:1]
	v_or_b32_e32 v110, 32, v146
	v_ashrrev_i32_e32 v111, 31, v110
	v_lshlrev_b64 v[100:101], 7, v[110:111]
	v_lshl_add_u64 v[106:107], v[134:135], 0, v[100:101]
	s_waitcnt lgkmcnt(0)
	s_waitcnt vmcnt(7)
	v_mov_b64_e32 v[102:103], v[190:191]
	v_mov_b64_e32 v[104:105], v[192:193]
	global_load_dwordx4 v[190:193], v[248:249], off offset:-4080
	s_nop 0
	s_waitcnt vmcnt(7)
	v_mov_b64_e32 v[106:107], v[194:195]
	v_mov_b64_e32 v[108:109], v[196:197]
	global_load_dwordx4 v[194:197], v[248:249], off offset:-4096
	s_waitcnt lgkmcnt(0)
	v_pk_add_f32 v[102:103], v[102:103], v[104:105]
	s_waitcnt lgkmcnt(0)
	v_pk_add_f32 v[106:107], v[106:107], v[108:109]
	s_nop 0
	v_pk_add_f32 v[102:103], v[106:107], v[102:103]
	ds_bpermute_b32 v104, v181, v102
	ds_bpermute_b32 v105, v181, v103
	s_waitcnt lgkmcnt(0)
	v_pk_add_f32 v[102:103], v[102:103], v[104:105]
	ds_bpermute_b32 v104, v180, v102
	ds_bpermute_b32 v105, v180, v103
	s_waitcnt lgkmcnt(0)
	v_pk_add_f32 v[102:103], v[102:103], v[104:105]
	s_nop 0
	v_pk_mul_f32 v[112:113], v[102:103], s[82:83] op_sel_hi:[1,0]
	v_lshlrev_b64 v[102:103], 11, v[110:111]
	v_lshl_add_u64 v[102:103], s[70:71], 0, v[102:103]
	v_lshl_add_u64 v[108:109], v[144:145], 1, v[102:103]
	v_add_u32_e32 v243, 0x40000, v242
	s_waitcnt vmcnt(7)
	v_permlane16_swap_b32_e32 v198, v200
	v_permlane16_swap_b32_e32 v199, v201
	s_nop 0
	v_permlane32_swap_b32_e32 v198, v200
	v_permlane32_swap_b32_e32 v199, v201
	v_mov_b64_e32 v[102:103], v[198:199]
	v_fma_f32 v3, -v112, v112, v113
	v_max_f32_e32 v3, 0, v3
	v_add_f32_e32 v3, 0x3727c5ac, v3
	v_rsq_f32_e32 v114, v3
	s_waitcnt lgkmcnt(0)
	v_lshlrev_b32_e32 v3, 16, v102
	v_and_b32_e32 v102, 0xffff0000, v102
	v_lshlrev_b32_e32 v104, 16, v103
	v_and_b32_e32 v105, 0xffff0000, v103
	v_sub_f32_e32 v103, v102, v112
	v_sub_f32_e32 v102, v3, v112
	v_sub_f32_e32 v105, v105, v112
	v_sub_f32_e32 v104, v104, v112
	v_pk_mul_f32 v[106:107], v[104:105], v[114:115] op_sel_hi:[1,0]
	v_pk_mul_f32 v[110:111], v[102:103], v[114:115] op_sel_hi:[1,0]
	ds_read_b128 v[102:105], v244
	ds_read_b128 v[116:119], v244 offset:256
	s_waitcnt lgkmcnt(0)
	v_pk_fma_f32 v[104:105], v[104:105], v[106:107], v[118:119]
	s_nop 0
	v_pk_fma_f32 v[98:99], v[104:105], s[72:73], v[98:99] op_sel_hi:[1,0,1]
	v_mov_b64_e32 v[104:105], v[200:201]
	v_lshrrev_b32_e32 v245, 4, v219
	v_lshl_add_u32 v245, v245, 3, v243
	global_load_dwordx4 v[198:201], v245, s[70:71]
	v_pk_fma_f32 v[102:103], v[102:103], v[110:111], v[116:117]
	s_waitcnt lgkmcnt(0)
; __device__ __forceinline__ u32x2 pk4(f32x4 v) { u32x2 r; r.x = pk2(v.x, v.y); r.y = pk2(v.z, v.w); return r; }
;     __device__ __forceinline__ void operator()(const f32x4 (&acc)[2][2][4][2], const pg8::Unit& u, int wr, int wc, int fr, int fq) const {
;     ...
;                 for (int bj = 0; bj < 2; ++bj)
; #pragma unroll
;                     for (int n = 0; n < 2; ++n) {
;                         const int col = u.pn * 256 + bj * 128 + wc * 32 + n * 16 + fq * 4;
;                         const u32x2 raw = *(const u32x2*)(src + (size_t)row * DM + col);
;                         f32x4 x = (f32x4){bflo(raw.x), bfhi(raw.x), bflo(raw.y), bfhi(raw.y)};
;                         if (ln) x = (x - mu) * rs * *(const f32x4*)(g + col) + *(const f32x4*)(b + col);
;                         const u32x2 pz = pk4(x * ALPHA + acc[ai][bj][m][n]);
;                         *(u32x2*)(dst + (size_t)row * DM + col) = pz;
;                         const float z0 = bflo(pz.x), z1 = bfhi(pz.x), z2 = bflo(pz.y), z3 = bfhi(pz.y);
;                         s1 += (z0 + z1) + (z2 + z3); s2 += (z0 * z0 + z1 * z1) + (z2 * z2 + z3 * z3);
;                     }
;                 s1 += __shfl_xor(s1, 16); s2 += __shfl_xor(s2, 16); s1 += __shfl_xor(s1, 32); s2 += __shfl_xor(s2, 32);
;                 if (fq == 0) { float* p = stm_n + (size_t)row * 32 + (u.pn * 4 + wc) * 2; p[0] = s1; p[1] = s2; }
	v_lshlrev_b32_e32 v3, 16, v104
	v_pk_fma_f32 v[96:97], v[102:103], s[72:73], v[96:97] op_sel_hi:[1,0,1]
	v_cvt_pk_bf16_f32 v103, v98, v99
	v_cvt_pk_bf16_f32 v102, v96, v97
	v_and_b32_e32 v97, 0xffff0000, v104
	v_lshlrev_b32_e32 v99, 16, v105
	v_and_b32_e32 v106, 0xffff0000, v105
	v_mov_b64_e32 v[148:149], v[102:103]
	v_sub_f32_e32 v105, v97, v112
	v_sub_f32_e32 v104, v3, v112
	v_sub_f32_e32 v107, v106, v112
	v_sub_f32_e32 v106, v99, v112
	v_pk_mul_f32 v[110:111], v[114:115], v[106:107] op_sel_hi:[0,1]
	v_pk_mul_f32 v[120:121], v[114:115], v[104:105] op_sel_hi:[0,1]
	ds_read_b128 v[104:107], v244 offset:64
	ds_read_b128 v[116:119], v244 offset:320
	v_and_b32_e32 v98, 0xffff0000, v102
	v_lshlrev_b32_e32 v96, 16, v103
	s_waitcnt lgkmcnt(0)
	v_pk_fma_f32 v[104:105], v[104:105], v[120:121], v[116:117]
	s_nop 0
	v_pk_fma_f32 v[92:93], v[104:105], s[72:73], v[92:93] op_sel_hi:[1,0,1]
	s_waitcnt vmcnt(7)
	v_permlane16_swap_b32_e32 v202, v204
	v_permlane16_swap_b32_e32 v203, v205
	s_nop 0
	v_permlane32_swap_b32_e32 v202, v204
	v_permlane32_swap_b32_e32 v203, v205
	v_mov_b64_e32 v[104:105], v[202:203]
	v_pk_fma_f32 v[106:107], v[106:107], v[110:111], v[118:119]
	v_cvt_pk_bf16_f32 v110, v92, v93
	v_pk_fma_f32 v[94:95], v[106:107], s[72:73], v[94:95] op_sel_hi:[1,0,1]
	s_waitcnt lgkmcnt(0)
	v_lshlrev_b32_e32 v3, 16, v104
	v_cvt_pk_bf16_f32 v111, v94, v95
	v_lshlrev_b32_e32 v94, 16, v111
	v_and_b32_e32 v95, 0xffff0000, v111
	v_mul_f32_e32 v92, v94, v94
	v_pk_fma_f32 v[92:93], v[94:95], v[94:95], v[92:93] op_sel_hi:[1,1,0]
	v_lshlrev_b32_e32 v97, 16, v105
	v_and_b32_e32 v92, 0xffff0000, v104
	v_and_b32_e32 v99, 0xffff0000, v105
	v_mov_b64_e32 v[150:151], v[110:111]
	v_lshrrev_b32_e32 v122, 4, v219
	v_lshlrev_b32_e32 v122, 3, v122
	v_mov_b32_e32 v123, v2
	v_permlane32_swap_b32_e32 v148, v150
	v_permlane32_swap_b32_e32 v149, v151
	v_lshl_add_u64 v[122:123], v[122:123], 0, v[108:109]
	s_nop 0
	v_permlane16_swap_b32_e32 v148, v150
	v_permlane16_swap_b32_e32 v149, v151
	global_store_dwordx4 v[122:123], v[148:151], off sc0
	v_sub_f32_e32 v105, v92, v112
	v_sub_f32_e32 v104, v3, v112
	v_sub_f32_e32 v107, v99, v112
	v_sub_f32_e32 v106, v97, v112
	v_pk_mul_f32 v[120:121], v[114:115], v[106:107] op_sel_hi:[0,1]
	v_pk_mul_f32 v[122:123], v[114:115], v[104:105] op_sel_hi:[0,1]
	ds_read_b128 v[104:107], v244 offset:128
	ds_read_b128 v[116:119], v244 offset:384
	v_and_b32_e32 v111, 0xffff0000, v110
	s_waitcnt lgkmcnt(0)
	v_pk_fma_f32 v[104:105], v[104:105], v[122:123], v[116:117]
	v_mov_b64_e32 v[116:117], v[204:205]
	v_lshrrev_b32_e32 v245, 4, v219
	v_lshl_add_u32 v245, v245, 3, v243
	global_load_dwordx4 v[202:205], v245, s[70:71] offset:256
	v_pk_fma_f32 v[106:107], v[106:107], v[120:121], v[118:119]
	v_pk_fma_f32 v[88:89], v[104:105], s[72:73], v[88:89] op_sel_hi:[1,0,1]
	v_pk_fma_f32 v[90:91], v[106:107], s[72:73], v[90:91] op_sel_hi:[1,0,1]
	v_cvt_pk_bf16_f32 v88, v88, v89
	v_cvt_pk_bf16_f32 v89, v90, v91
	v_mov_b64_e32 v[148:149], v[88:89]
	v_lshlrev_b32_e32 v104, 16, v88
	v_and_b32_e32 v106, 0xffff0000, v88
	v_lshlrev_b32_e32 v88, 16, v89
	v_and_b32_e32 v90, 0xffff0000, v89
	v_mul_f32_e32 v105, v104, v104
	v_mul_f32_e32 v107, v106, v106
	v_mul_f32_e32 v89, v88, v88
	v_mul_f32_e32 v91, v90, v90
	v_pk_add_f32 v[88:89], v[88:89], v[90:91]
	s_waitcnt lgkmcnt(0)
	v_lshlrev_b32_e32 v3, 16, v116
	v_and_b32_e32 v92, 0xffff0000, v116
	v_lshlrev_b32_e32 v97, 16, v117
	v_and_b32_e32 v99, 0xffff0000, v117
	v_sub_f32_e32 v117, v92, v112
	v_sub_f32_e32 v116, v3, v112
	v_sub_f32_e32 v113, v99, v112
	v_sub_f32_e32 v112, v97, v112
	v_pk_mul_f32 v[112:113], v[114:115], v[112:113] op_sel_hi:[0,1]
	v_pk_mul_f32 v[114:115], v[114:115], v[116:117] op_sel_hi:[0,1]
	ds_read_b128 v[116:119], v244 offset:192
	ds_read_b128 v[120:123], v244 offset:448
	v_mov_b32_e32 v97, v111
	v_mov_b32_e32 v3, v93
	s_waitcnt lgkmcnt(0)
	v_pk_fma_f32 v[114:115], v[116:117], v[114:115], v[120:121]
	s_nop 0
	v_pk_fma_f32 v[84:85], v[114:115], s[72:73], v[84:85] op_sel_hi:[1,0,1]
	v_lshlrev_b32_e32 v115, 16, v110
	v_lshlrev_b32_e32 v114, 16, v102
	v_mov_b32_e32 v99, v115
	v_pk_fma_f32 v[112:113], v[118:119], v[112:113], v[122:123]
	v_pk_mul_f32 v[116:117], v[114:115], v[114:115]
	v_pk_mul_f32 v[118:119], v[98:99], v[98:99]
	v_and_b32_e32 v110, 0xffff0000, v103
	v_pk_mul_f32 v[102:103], v[96:97], v[96:97]
	v_pk_mul_f32 v[120:121], v[110:111], v[110:111]
	v_pk_mov_b32 v[122:123], v[114:115], v[116:117] op_sel:[1,0]
	v_pk_mov_b32 v[118:119], v[110:111], v[118:119] op_sel:[1,0]
	v_pk_add_f32 v[98:99], v[114:115], v[98:99]
	v_pk_add_f32 v[96:97], v[110:111], v[96:97]
	v_pk_fma_f32 v[86:87], v[112:113], s[72:73], v[86:87] op_sel_hi:[1,0,1]
	v_pk_add_f32 v[118:119], v[122:123], v[118:119]
	v_mov_b32_e32 v122, v94
	v_mov_b32_e32 v123, v102
	v_pk_mov_b32 v[94:95], v[94:95], v[120:121] op_sel:[1,0]
	v_mov_b32_e32 v99, v117
	v_mov_b32_e32 v97, v121
	v_cvt_pk_bf16_f32 v84, v84, v85
	v_cvt_pk_bf16_f32 v85, v86, v87
	v_pk_add_f32 v[94:95], v[122:123], v[94:95]
	v_pk_add_f32 v[96:97], v[98:99], v[96:97]
	v_mov_b64_e32 v[150:151], v[84:85]
	v_lshrrev_b32_e32 v152, 4, v219
	v_lshlrev_b32_e32 v152, 3, v152
	v_mov_b32_e32 v153, v2
	v_permlane32_swap_b32_e32 v148, v150
	v_permlane32_swap_b32_e32 v149, v151
	v_lshl_add_u64 v[152:153], v[152:153], 0, v[108:109]
	s_nop 0
	v_permlane16_swap_b32_e32 v148, v150
	v_permlane16_swap_b32_e32 v149, v151
	global_store_dwordx4 v[152:153], v[148:151], off offset:256 sc0
	v_lshlrev_b32_e32 v108, 16, v84
	v_and_b32_e32 v112, 0xffff0000, v84
	v_lshlrev_b32_e32 v84, 16, v85
	v_and_b32_e32 v86, 0xffff0000, v85
	v_pk_add_f32 v[94:95], v[118:119], v[94:95]
	v_pk_add_f32 v[92:93], v[96:97], v[2:3]
	v_mul_f32_e32 v109, v108, v108
	v_mul_f32_e32 v113, v112, v112
	v_mul_f32_e32 v85, v84, v84
	v_mul_f32_e32 v87, v86, v86
	v_pk_add_f32 v[92:93], v[94:95], v[92:93]
	v_pk_add_f32 v[94:95], v[104:105], v[106:107]
	v_pk_add_f32 v[90:91], v[108:109], v[112:113]
	v_pk_add_f32 v[88:89], v[94:95], v[88:89]
	v_pk_add_f32 v[84:85], v[84:85], v[86:87]
	v_pk_add_f32 v[88:89], v[92:93], v[88:89]
	v_pk_add_f32 v[84:85], v[90:91], v[84:85]
	s_nop 0
	v_pk_add_f32 v[84:85], v[88:89], v[84:85]
	ds_bpermute_b32 v86, v181, v84
	ds_bpermute_b32 v87, v181, v85
	s_waitcnt lgkmcnt(0)
	v_pk_add_f32 v[84:85], v[84:85], v[86:87]
	ds_bpermute_b32 v86, v180, v84
	ds_bpermute_b32 v87, v180, v85
	s_and_saveexec_b64 s[0:1], s[40:41]
	s_mov_b32 s78, 0x20000
	s_mov_b32 s76, 0x30000
	s_cbranch_execz .LBB0_2383
	v_lshl_add_u64 v[88:89], s[52:53], 0, v[100:101]
	v_lshl_add_u64 v[88:89], s[68:69], 2, v[88:89]
	s_waitcnt lgkmcnt(0)
	v_pk_add_f32 v[84:85], v[84:85], v[86:87]
	global_store_dwordx2 v[88:89], v[84:85], off
; __device__ __forceinline__ u32x2 pk4(f32x4 v) { u32x2 r; r.x = pk2(v.x, v.y); r.y = pk2(v.z, v.w); return r; }
; __device__ __forceinline__ void stats_main(const float* stm, int row, int fq, float& mu, float& rs) {
;     const f32x4* p = (const f32x4*)(stm + (size_t)row * 32 + fq * 8);
;     const f32x4 a = p[0], b = p[1];
;     float s1 = (a.x + a.z) + (b.x + b.z), s2 = (a.y + a.w) + (b.y + b.w);
;     s1 += __shfl_xor(s1, 16); s2 += __shfl_xor(s2, 16); s1 += __shfl_xor(s1, 32); s2 += __shfl_xor(s2, 32);
;     mu = s1 * (1.f / DM); rs = __builtin_amdgcn_rsqf(fmaxf(s2 * (1.f / DM) - mu * mu, 0.f) + LN_EPS);
; }
;     __device__ __forceinline__ void operator()(const f32x4 (&acc)[2][2][4][2], const pg8::Unit& u, int wr, int wc, int fr, int fq) const {
;     ...
;                 const int row = u.pm * 256 + ai * 128 + wr * 64 + m * 16 + fr;
;                 float mu = 0.f, rs = 1.f; if (ln) stats_main(stm_p, row, fq, mu, rs);
;                 float s1 = 0.f, s2 = 0.f;
; #pragma unroll
;                 for (int bj = 0; bj < 2; ++bj)
; #pragma unroll
;                     for (int n = 0; n < 2; ++n) {
;                         const int col = u.pn * 256 + bj * 128 + wc * 32 + n * 16 + fq * 4;
;                         const u32x2 raw = *(const u32x2*)(src + (size_t)row * DM + col);
;                         f32x4 x = (f32x4){bflo(raw.x), bfhi(raw.x), bflo(raw.y), bfhi(raw.y)};
;                         if (ln) x = (x - mu) * rs * *(const f32x4*)(g + col) + *(const f32x4*)(b + col);
;                         const u32x2 pz = pk4(x * ALPHA + acc[ai][bj][m][n]);
;                         *(u32x2*)(dst + (size_t)row * DM + col) = pz;
;                         const float z0 = bflo(pz.x), z1 = bfhi(pz.x), z2 = bflo(pz.y), z3 = bfhi(pz.y);
;                         s1 += (z0 + z1) + (z2 + z3); s2 += (z0 * z0 + z1 * z1) + (z2 * z2 + z3 * z3);
;                     }
;                 s1 += __shfl_xor(s1, 16); s2 += __shfl_xor(s2, 16); s1 += __shfl_xor(s1, 32); s2 += __shfl_xor(s2, 32);
;                 if (fq == 0) { float* p = stm_n + (size_t)row * 32 + (u.pn * 4 + wc) * 2; p[0] = s1; p[1] = s2; }
.LBB0_2383:
	s_or_b64 exec, exec, s[0:1]
	v_or_b32_e32 v94, 48, v146
	v_ashrrev_i32_e32 v95, 31, v94
	v_lshlrev_b64 v[84:85], 7, v[94:95]
	v_lshl_add_u64 v[90:91], v[134:135], 0, v[84:85]
	s_waitcnt lgkmcnt(0)
	s_waitcnt vmcnt(7)
	v_mov_b64_e32 v[86:87], v[206:207]
	v_mov_b64_e32 v[88:89], v[208:209]
	global_load_dwordx4 v[206:209], v[248:249], off offset:-2032
	s_nop 0
	s_waitcnt vmcnt(7)
	v_mov_b64_e32 v[90:91], v[214:215]
	v_mov_b64_e32 v[92:93], v[216:217]
	global_load_dwordx4 v[214:217], v[248:249], off offset:-2048
	s_waitcnt lgkmcnt(0)
	v_pk_add_f32 v[86:87], v[86:87], v[88:89]
	s_waitcnt lgkmcnt(0)
	v_pk_add_f32 v[90:91], v[90:91], v[92:93]
	s_nop 0
	v_pk_add_f32 v[86:87], v[90:91], v[86:87]
	ds_bpermute_b32 v88, v181, v86
	ds_bpermute_b32 v89, v181, v87
	s_waitcnt lgkmcnt(0)
	v_pk_add_f32 v[86:87], v[86:87], v[88:89]
	ds_bpermute_b32 v88, v180, v86
	ds_bpermute_b32 v89, v180, v87
	s_waitcnt lgkmcnt(0)
	v_pk_add_f32 v[86:87], v[86:87], v[88:89]
	s_nop 0
	v_pk_mul_f32 v[96:97], v[86:87], s[82:83] op_sel_hi:[1,0]
	v_lshlrev_b64 v[86:87], 11, v[94:95]
	v_lshl_add_u64 v[86:87], s[70:71], 0, v[86:87]
	v_lshl_add_u64 v[92:93], v[144:145], 1, v[86:87]
	v_add_u32_e32 v243, 0x48000, v242
	s_waitcnt vmcnt(7)
	v_permlane16_swap_b32_e32 v234, v236
	v_permlane16_swap_b32_e32 v235, v237
	s_nop 0
	v_permlane32_swap_b32_e32 v234, v236
	v_permlane32_swap_b32_e32 v235, v237
	v_mov_b64_e32 v[86:87], v[234:235]
	v_fma_f32 v3, -v96, v96, v97
	v_max_f32_e32 v3, 0, v3
	v_add_f32_e32 v3, 0x3727c5ac, v3
	v_rsq_f32_e32 v98, v3
	s_waitcnt lgkmcnt(0)
	v_lshlrev_b32_e32 v3, 16, v86
	v_and_b32_e32 v86, 0xffff0000, v86
	v_lshlrev_b32_e32 v88, 16, v87
	v_and_b32_e32 v89, 0xffff0000, v87
	v_sub_f32_e32 v87, v86, v96
	v_sub_f32_e32 v86, v3, v96
	v_sub_f32_e32 v89, v89, v96
	v_sub_f32_e32 v88, v88, v96
	v_pk_mul_f32 v[90:91], v[88:89], v[98:99] op_sel_hi:[1,0]
	v_pk_mul_f32 v[94:95], v[86:87], v[98:99] op_sel_hi:[1,0]
	ds_read_b128 v[86:89], v244
	ds_read_b128 v[100:103], v244 offset:256
	s_waitcnt lgkmcnt(0)
	v_pk_fma_f32 v[88:89], v[88:89], v[90:91], v[102:103]
	s_nop 0
	v_pk_fma_f32 v[82:83], v[88:89], s[72:73], v[82:83] op_sel_hi:[1,0,1]
	v_mov_b64_e32 v[88:89], v[236:237]
	v_lshrrev_b32_e32 v245, 4, v219
	v_lshl_add_u32 v245, v245, 3, v243
	global_load_dwordx4 v[234:237], v245, s[70:71]
	v_pk_fma_f32 v[86:87], v[86:87], v[94:95], v[100:101]
	s_waitcnt lgkmcnt(0)
	v_lshlrev_b32_e32 v3, 16, v88
	v_pk_fma_f32 v[80:81], v[86:87], s[72:73], v[80:81] op_sel_hi:[1,0,1]
	v_cvt_pk_bf16_f32 v87, v82, v83
	v_cvt_pk_bf16_f32 v86, v80, v81
	v_and_b32_e32 v81, 0xffff0000, v88
	v_lshlrev_b32_e32 v83, 16, v89
	v_and_b32_e32 v90, 0xffff0000, v89
	v_mov_b64_e32 v[148:149], v[86:87]
	v_sub_f32_e32 v89, v81, v96
	v_sub_f32_e32 v88, v3, v96
	v_sub_f32_e32 v91, v90, v96
	v_sub_f32_e32 v90, v83, v96
	v_pk_mul_f32 v[94:95], v[98:99], v[90:91] op_sel_hi:[0,1]
	v_pk_mul_f32 v[104:105], v[98:99], v[88:89] op_sel_hi:[0,1]
	ds_read_b128 v[88:91], v244 offset:64
	ds_read_b128 v[100:103], v244 offset:320
	v_and_b32_e32 v82, 0xffff0000, v86
	v_lshlrev_b32_e32 v80, 16, v87
	s_waitcnt lgkmcnt(0)
	v_pk_fma_f32 v[88:89], v[88:89], v[104:105], v[100:101]
	s_nop 0
	v_pk_fma_f32 v[76:77], v[88:89], s[72:73], v[76:77] op_sel_hi:[1,0,1]
	s_waitcnt vmcnt(7)
	v_permlane16_swap_b32_e32 v238, v240
	v_permlane16_swap_b32_e32 v239, v241
	s_nop 0
	v_permlane32_swap_b32_e32 v238, v240
	v_permlane32_swap_b32_e32 v239, v241
	v_mov_b64_e32 v[88:89], v[238:239]
	v_pk_fma_f32 v[90:91], v[90:91], v[94:95], v[102:103]
	v_cvt_pk_bf16_f32 v94, v76, v77
	v_pk_fma_f32 v[78:79], v[90:91], s[72:73], v[78:79] op_sel_hi:[1,0,1]
	s_waitcnt lgkmcnt(0)
	v_lshlrev_b32_e32 v3, 16, v88
	v_cvt_pk_bf16_f32 v95, v78, v79
	v_lshlrev_b32_e32 v78, 16, v95
	v_and_b32_e32 v79, 0xffff0000, v95
	v_mul_f32_e32 v76, v78, v78
	v_pk_fma_f32 v[76:77], v[78:79], v[78:79], v[76:77] op_sel_hi:[1,1,0]
	v_lshlrev_b32_e32 v81, 16, v89
	v_and_b32_e32 v76, 0xffff0000, v88
	v_and_b32_e32 v83, 0xffff0000, v89
	v_mov_b64_e32 v[150:151], v[94:95]
	v_lshrrev_b32_e32 v106, 4, v219
	v_lshlrev_b32_e32 v106, 3, v106
	v_mov_b32_e32 v107, v2
	v_permlane32_swap_b32_e32 v148, v150
	v_permlane32_swap_b32_e32 v149, v151
	v_lshl_add_u64 v[106:107], v[106:107], 0, v[92:93]
	s_nop 0
	v_permlane16_swap_b32_e32 v148, v150
	v_permlane16_swap_b32_e32 v149, v151
	global_store_dwordx4 v[106:107], v[148:151], off sc0
	v_sub_f32_e32 v89, v76, v96
	v_sub_f32_e32 v88, v3, v96
	v_sub_f32_e32 v91, v83, v96
	v_sub_f32_e32 v90, v81, v96
	v_pk_mul_f32 v[104:105], v[98:99], v[90:91] op_sel_hi:[0,1]
	v_pk_mul_f32 v[106:107], v[98:99], v[88:89] op_sel_hi:[0,1]
	ds_read_b128 v[88:91], v244 offset:128
	ds_read_b128 v[100:103], v244 offset:384
	v_and_b32_e32 v95, 0xffff0000, v94
	s_waitcnt lgkmcnt(0)
	v_pk_fma_f32 v[88:89], v[88:89], v[106:107], v[100:101]
	v_mov_b64_e32 v[100:101], v[240:241]
	v_lshrrev_b32_e32 v245, 4, v219
	v_lshl_add_u32 v245, v245, 3, v243
	global_load_dwordx4 v[238:241], v245, s[70:71] offset:256
	v_pk_fma_f32 v[90:91], v[90:91], v[104:105], v[102:103]
	v_pk_fma_f32 v[72:73], v[88:89], s[72:73], v[72:73] op_sel_hi:[1,0,1]
	v_pk_fma_f32 v[74:75], v[90:91], s[72:73], v[74:75] op_sel_hi:[1,0,1]
	v_cvt_pk_bf16_f32 v72, v72, v73
	v_cvt_pk_bf16_f32 v73, v74, v75
	v_mov_b64_e32 v[148:149], v[72:73]
	v_lshlrev_b32_e32 v88, 16, v72
	v_and_b32_e32 v90, 0xffff0000, v72
	v_lshlrev_b32_e32 v72, 16, v73
	v_and_b32_e32 v74, 0xffff0000, v73
	v_mul_f32_e32 v89, v88, v88
	v_mul_f32_e32 v91, v90, v90
	v_mul_f32_e32 v73, v72, v72
	v_mul_f32_e32 v75, v74, v74
	v_pk_add_f32 v[72:73], v[72:73], v[74:75]
	s_waitcnt lgkmcnt(0)
; __device__ __forceinline__ u32x2 pk4(f32x4 v) { u32x2 r; r.x = pk2(v.x, v.y); r.y = pk2(v.z, v.w); return r; }
; __device__ __forceinline__ void stats_main(const float* stm, int row, int fq, float& mu, float& rs) {
;     const f32x4* p = (const f32x4*)(stm + (size_t)row * 32 + fq * 8);
;     const f32x4 a = p[0], b = p[1];
;     float s1 = (a.x + a.z) + (b.x + b.z), s2 = (a.y + a.w) + (b.y + b.w);
;     s1 += __shfl_xor(s1, 16); s2 += __shfl_xor(s2, 16); s1 += __shfl_xor(s1, 32); s2 += __shfl_xor(s2, 32);
;     mu = s1 * (1.f / DM); rs = __builtin_amdgcn_rsqf(fmaxf(s2 * (1.f / DM) - mu * mu, 0.f) + LN_EPS);
; }
;     __device__ __forceinline__ void operator()(const f32x4 (&acc)[2][2][4][2], const pg8::Unit& u, int wr, int wc, int fr, int fq) const {
;     ...
;                 const int row = u.pm * 256 + ai * 128 + wr * 64 + m * 16 + fr;
;                 float mu = 0.f, rs = 1.f; if (ln) stats_main(stm_p, row, fq, mu, rs);
;                 float s1 = 0.f, s2 = 0.f;
; #pragma unroll
;                 for (int bj = 0; bj < 2; ++bj)
; #pragma unroll
;                     for (int n = 0; n < 2; ++n) {
;                         const int col = u.pn * 256 + bj * 128 + wc * 32 + n * 16 + fq * 4;
;                         const u32x2 raw = *(const u32x2*)(src + (size_t)row * DM + col);
;                         f32x4 x = (f32x4){bflo(raw.x), bfhi(raw.x), bflo(raw.y), bfhi(raw.y)};
;                         if (ln) x = (x - mu) * rs * *(const f32x4*)(g + col) + *(const f32x4*)(b + col);
;                         const u32x2 pz = pk4(x * ALPHA + acc[ai][bj][m][n]);
;                         *(u32x2*)(dst + (size_t)row * DM + col) = pz;
;                         const float z0 = bflo(pz.x), z1 = bfhi(pz.x), z2 = bflo(pz.y), z3 = bfhi(pz.y);
;                         s1 += (z0 + z1) + (z2 + z3); s2 += (z0 * z0 + z1 * z1) + (z2 * z2 + z3 * z3);
;                     }
;                 s1 += __shfl_xor(s1, 16); s2 += __shfl_xor(s2, 16); s1 += __shfl_xor(s1, 32); s2 += __shfl_xor(s2, 32);
;                 if (fq == 0) { float* p = stm_n + (size_t)row * 32 + (u.pn * 4 + wc) * 2; p[0] = s1; p[1] = s2; }
	v_lshlrev_b32_e32 v3, 16, v100
	v_and_b32_e32 v76, 0xffff0000, v100
	v_lshlrev_b32_e32 v81, 16, v101
	v_and_b32_e32 v83, 0xffff0000, v101
	v_sub_f32_e32 v101, v76, v96
	v_sub_f32_e32 v100, v3, v96
	v_sub_f32_e32 v97, v83, v96
	v_sub_f32_e32 v96, v81, v96
	v_pk_mul_f32 v[96:97], v[98:99], v[96:97] op_sel_hi:[0,1]
	v_pk_mul_f32 v[98:99], v[98:99], v[100:101] op_sel_hi:[0,1]
	ds_read_b128 v[100:103], v244 offset:192
	ds_read_b128 v[104:107], v244 offset:448
	v_mov_b32_e32 v81, v95
	v_mov_b32_e32 v3, v77
	s_waitcnt lgkmcnt(0)
	v_pk_fma_f32 v[98:99], v[100:101], v[98:99], v[104:105]
	s_nop 0
	v_pk_fma_f32 v[68:69], v[98:99], s[72:73], v[68:69] op_sel_hi:[1,0,1]
	v_lshlrev_b32_e32 v99, 16, v94
	v_lshlrev_b32_e32 v98, 16, v86
	v_mov_b32_e32 v83, v99
	v_pk_fma_f32 v[96:97], v[102:103], v[96:97], v[106:107]
	v_pk_mul_f32 v[100:101], v[98:99], v[98:99]
	v_pk_mul_f32 v[102:103], v[82:83], v[82:83]
	v_and_b32_e32 v94, 0xffff0000, v87
	v_pk_mul_f32 v[86:87], v[80:81], v[80:81]
	v_pk_mul_f32 v[104:105], v[94:95], v[94:95]
	v_pk_mov_b32 v[106:107], v[98:99], v[100:101] op_sel:[1,0]
	v_pk_mov_b32 v[102:103], v[94:95], v[102:103] op_sel:[1,0]
	v_pk_add_f32 v[82:83], v[98:99], v[82:83]
	v_pk_add_f32 v[80:81], v[94:95], v[80:81]
	v_pk_fma_f32 v[70:71], v[96:97], s[72:73], v[70:71] op_sel_hi:[1,0,1]
	v_pk_add_f32 v[102:103], v[106:107], v[102:103]
	v_mov_b32_e32 v106, v78
	v_mov_b32_e32 v107, v86
	v_pk_mov_b32 v[78:79], v[78:79], v[104:105] op_sel:[1,0]
	v_mov_b32_e32 v83, v101
	v_mov_b32_e32 v81, v105
	v_cvt_pk_bf16_f32 v68, v68, v69
	v_cvt_pk_bf16_f32 v69, v70, v71
	v_pk_add_f32 v[78:79], v[106:107], v[78:79]
	v_pk_add_f32 v[80:81], v[82:83], v[80:81]
	v_mov_b64_e32 v[150:151], v[68:69]
	v_lshrrev_b32_e32 v152, 4, v219
	v_lshlrev_b32_e32 v152, 3, v152
	v_mov_b32_e32 v153, v2
	v_permlane32_swap_b32_e32 v148, v150
	v_permlane32_swap_b32_e32 v149, v151
	v_lshl_add_u64 v[152:153], v[152:153], 0, v[92:93]
	s_nop 0
	v_permlane16_swap_b32_e32 v148, v150
	v_permlane16_swap_b32_e32 v149, v151
	global_store_dwordx4 v[152:153], v[148:151], off offset:256 sc0
	v_lshlrev_b32_e32 v92, 16, v68
	v_and_b32_e32 v96, 0xffff0000, v68
	v_lshlrev_b32_e32 v68, 16, v69
	v_and_b32_e32 v70, 0xffff0000, v69
	v_pk_add_f32 v[78:79], v[102:103], v[78:79]
	v_pk_add_f32 v[76:77], v[80:81], v[2:3]
	v_mul_f32_e32 v93, v92, v92
	v_mul_f32_e32 v97, v96, v96
	v_mul_f32_e32 v69, v68, v68
	v_mul_f32_e32 v71, v70, v70
	v_pk_add_f32 v[76:77], v[78:79], v[76:77]
	v_pk_add_f32 v[78:79], v[88:89], v[90:91]
	v_pk_add_f32 v[74:75], v[92:93], v[96:97]
	v_pk_add_f32 v[72:73], v[78:79], v[72:73]
	v_pk_add_f32 v[68:69], v[68:69], v[70:71]
	v_pk_add_f32 v[72:73], v[76:77], v[72:73]
	v_pk_add_f32 v[68:69], v[74:75], v[68:69]
	s_nop 0
	v_pk_add_f32 v[68:69], v[72:73], v[68:69]
	ds_bpermute_b32 v70, v181, v68
	ds_bpermute_b32 v71, v181, v69
	s_waitcnt lgkmcnt(0)
	v_pk_add_f32 v[68:69], v[68:69], v[70:71]
	ds_bpermute_b32 v70, v180, v68
	ds_bpermute_b32 v71, v180, v69
	s_and_saveexec_b64 s[0:1], s[40:41]
	s_cbranch_execz .LBB0_2385
	v_lshl_add_u64 v[72:73], s[52:53], 0, v[84:85]
	v_lshl_add_u64 v[72:73], s[68:69], 2, v[72:73]
	s_waitcnt lgkmcnt(0)
	v_pk_add_f32 v[68:69], v[68:69], v[70:71]
	global_store_dwordx2 v[72:73], v[68:69], off
.LBB0_2385:
	s_or_b64 exec, exec, s[0:1]
	v_add_u32_e32 v78, 0x80, v146
	v_ashrrev_i32_e32 v79, 31, v78
	v_lshlrev_b64 v[68:69], 7, v[78:79]
	v_lshl_add_u64 v[74:75], v[134:135], 0, v[68:69]
	s_waitcnt lgkmcnt(0)
	s_waitcnt vmcnt(7)
	v_mov_b64_e32 v[70:71], v[190:191]
	v_mov_b64_e32 v[72:73], v[192:193]
	global_load_dwordx4 v[190:193], v[248:249], off offset:16
	s_nop 0
	s_waitcnt vmcnt(7)
	v_mov_b64_e32 v[74:75], v[194:195]
	v_mov_b64_e32 v[76:77], v[196:197]
	global_load_dwordx4 v[194:197], v[248:249], off
	s_waitcnt lgkmcnt(0)
	v_pk_add_f32 v[70:71], v[70:71], v[72:73]
	s_waitcnt lgkmcnt(0)
	v_pk_add_f32 v[74:75], v[74:75], v[76:77]
	s_nop 0
	v_pk_add_f32 v[70:71], v[74:75], v[70:71]
	ds_bpermute_b32 v72, v181, v70
	ds_bpermute_b32 v73, v181, v71
	s_waitcnt lgkmcnt(0)
	v_pk_add_f32 v[70:71], v[70:71], v[72:73]
	ds_bpermute_b32 v72, v180, v70
	ds_bpermute_b32 v73, v180, v71
	s_waitcnt lgkmcnt(0)
	v_pk_add_f32 v[70:71], v[70:71], v[72:73]
	s_nop 0
	v_pk_mul_f32 v[80:81], v[70:71], s[82:83] op_sel_hi:[1,0]
	v_lshlrev_b64 v[70:71], 11, v[78:79]
	v_lshl_add_u64 v[70:71], s[70:71], 0, v[70:71]
	v_lshl_add_u64 v[76:77], v[144:145], 1, v[70:71]
	v_add_u32_e32 v243, 0x50000, v242
	s_waitcnt vmcnt(7)
	v_permlane16_swap_b32_e32 v198, v200
	v_permlane16_swap_b32_e32 v199, v201
	s_nop 0
	v_permlane32_swap_b32_e32 v198, v200
	v_permlane32_swap_b32_e32 v199, v201
	v_mov_b64_e32 v[70:71], v[198:199]
	v_fma_f32 v3, -v80, v80, v81
	v_max_f32_e32 v3, 0, v3
	v_add_f32_e32 v3, 0x3727c5ac, v3
	v_rsq_f32_e32 v82, v3
	s_waitcnt lgkmcnt(0)
	v_lshlrev_b32_e32 v3, 16, v70
	v_and_b32_e32 v70, 0xffff0000, v70
	v_lshlrev_b32_e32 v72, 16, v71
	v_and_b32_e32 v73, 0xffff0000, v71
	v_sub_f32_e32 v71, v70, v80
	v_sub_f32_e32 v70, v3, v80
	v_sub_f32_e32 v73, v73, v80
	v_sub_f32_e32 v72, v72, v80
	v_pk_mul_f32 v[74:75], v[72:73], v[82:83] op_sel_hi:[1,0]
	v_pk_mul_f32 v[78:79], v[70:71], v[82:83] op_sel_hi:[1,0]
	ds_read_b128 v[70:73], v244
	ds_read_b128 v[84:87], v244 offset:256
	s_waitcnt lgkmcnt(0)
	v_pk_fma_f32 v[72:73], v[72:73], v[74:75], v[86:87]
	s_nop 0
	v_pk_fma_f32 v[66:67], v[72:73], s[72:73], v[66:67] op_sel_hi:[1,0,1]
	v_mov_b64_e32 v[72:73], v[200:201]
	v_lshrrev_b32_e32 v245, 4, v219
	v_lshl_add_u32 v245, v245, 3, v243
	global_load_dwordx4 v[198:201], v245, s[70:71]
	v_pk_fma_f32 v[70:71], v[70:71], v[78:79], v[84:85]
	s_waitcnt lgkmcnt(0)
; __device__ __forceinline__ u32x2 pk4(f32x4 v) { u32x2 r; r.x = pk2(v.x, v.y); r.y = pk2(v.z, v.w); return r; }
; __device__ __forceinline__ void stats_main(const float* stm, int row, int fq, float& mu, float& rs) {
;     const f32x4* p = (const f32x4*)(stm + (size_t)row * 32 + fq * 8);
;     const f32x4 a = p[0], b = p[1];
;     float s1 = (a.x + a.z) + (b.x + b.z), s2 = (a.y + a.w) + (b.y + b.w);
;     s1 += __shfl_xor(s1, 16); s2 += __shfl_xor(s2, 16); s1 += __shfl_xor(s1, 32); s2 += __shfl_xor(s2, 32);
;     mu = s1 * (1.f / DM); rs = __builtin_amdgcn_rsqf(fmaxf(s2 * (1.f / DM) - mu * mu, 0.f) + LN_EPS);
; }
;     __device__ __forceinline__ void operator()(const f32x4 (&acc)[2][2][4][2], const pg8::Unit& u, int wr, int wc, int fr, int fq) const {
;     ...
;                 const int row = u.pm * 256 + ai * 128 + wr * 64 + m * 16 + fr;
;                 float mu = 0.f, rs = 1.f; if (ln) stats_main(stm_p, row, fq, mu, rs);
;                 float s1 = 0.f, s2 = 0.f;
; #pragma unroll
;                 for (int bj = 0; bj < 2; ++bj)
; #pragma unroll
;                     for (int n = 0; n < 2; ++n) {
;                         const int col = u.pn * 256 + bj * 128 + wc * 32 + n * 16 + fq * 4;
;                         const u32x2 raw = *(const u32x2*)(src + (size_t)row * DM + col);
;                         f32x4 x = (f32x4){bflo(raw.x), bfhi(raw.x), bflo(raw.y), bfhi(raw.y)};
;                         if (ln) x = (x - mu) * rs * *(const f32x4*)(g + col) + *(const f32x4*)(b + col);
;                         const u32x2 pz = pk4(x * ALPHA + acc[ai][bj][m][n]);
;                         *(u32x2*)(dst + (size_t)row * DM + col) = pz;
;                         const float z0 = bflo(pz.x), z1 = bfhi(pz.x), z2 = bflo(pz.y), z3 = bfhi(pz.y);
;                         s1 += (z0 + z1) + (z2 + z3); s2 += (z0 * z0 + z1 * z1) + (z2 * z2 + z3 * z3);
;                     }
;                 s1 += __shfl_xor(s1, 16); s2 += __shfl_xor(s2, 16); s1 += __shfl_xor(s1, 32); s2 += __shfl_xor(s2, 32);
;                 if (fq == 0) { float* p = stm_n + (size_t)row * 32 + (u.pn * 4 + wc) * 2; p[0] = s1; p[1] = s2; }
	v_lshlrev_b32_e32 v3, 16, v72
	v_pk_fma_f32 v[64:65], v[70:71], s[72:73], v[64:65] op_sel_hi:[1,0,1]
	v_cvt_pk_bf16_f32 v71, v66, v67
	v_cvt_pk_bf16_f32 v70, v64, v65
	v_and_b32_e32 v65, 0xffff0000, v72
	v_lshlrev_b32_e32 v67, 16, v73
	v_and_b32_e32 v74, 0xffff0000, v73
	v_mov_b64_e32 v[148:149], v[70:71]
	v_sub_f32_e32 v73, v65, v80
	v_sub_f32_e32 v72, v3, v80
	v_sub_f32_e32 v75, v74, v80
	v_sub_f32_e32 v74, v67, v80
	v_pk_mul_f32 v[78:79], v[82:83], v[74:75] op_sel_hi:[0,1]
	v_pk_mul_f32 v[88:89], v[82:83], v[72:73] op_sel_hi:[0,1]
	ds_read_b128 v[72:75], v244 offset:64
	ds_read_b128 v[84:87], v244 offset:320
	v_and_b32_e32 v66, 0xffff0000, v70
	v_lshlrev_b32_e32 v64, 16, v71
	s_waitcnt lgkmcnt(0)
	v_pk_fma_f32 v[72:73], v[72:73], v[88:89], v[84:85]
	s_nop 0
	v_pk_fma_f32 v[60:61], v[72:73], s[72:73], v[60:61] op_sel_hi:[1,0,1]
	s_waitcnt vmcnt(7)
	v_permlane16_swap_b32_e32 v202, v204
	v_permlane16_swap_b32_e32 v203, v205
	s_nop 0
	v_permlane32_swap_b32_e32 v202, v204
	v_permlane32_swap_b32_e32 v203, v205
	v_mov_b64_e32 v[72:73], v[202:203]
	v_pk_fma_f32 v[74:75], v[74:75], v[78:79], v[86:87]
	v_cvt_pk_bf16_f32 v78, v60, v61
	v_pk_fma_f32 v[62:63], v[74:75], s[72:73], v[62:63] op_sel_hi:[1,0,1]
	s_waitcnt lgkmcnt(0)
	v_lshlrev_b32_e32 v3, 16, v72
	v_cvt_pk_bf16_f32 v79, v62, v63
	v_lshlrev_b32_e32 v62, 16, v79
	v_and_b32_e32 v63, 0xffff0000, v79
	v_mul_f32_e32 v60, v62, v62
	v_pk_fma_f32 v[60:61], v[62:63], v[62:63], v[60:61] op_sel_hi:[1,1,0]
	v_lshlrev_b32_e32 v65, 16, v73
	v_and_b32_e32 v60, 0xffff0000, v72
	v_and_b32_e32 v67, 0xffff0000, v73
	v_mov_b64_e32 v[150:151], v[78:79]
	v_lshrrev_b32_e32 v90, 4, v219
	v_lshlrev_b32_e32 v90, 3, v90
	v_mov_b32_e32 v91, v2
	v_permlane32_swap_b32_e32 v148, v150
	v_permlane32_swap_b32_e32 v149, v151
	v_lshl_add_u64 v[90:91], v[90:91], 0, v[76:77]
	s_nop 0
	v_permlane16_swap_b32_e32 v148, v150
	v_permlane16_swap_b32_e32 v149, v151
	global_store_dwordx4 v[90:91], v[148:151], off sc0
	v_sub_f32_e32 v73, v60, v80
	v_sub_f32_e32 v72, v3, v80
	v_sub_f32_e32 v75, v67, v80
	v_sub_f32_e32 v74, v65, v80
	v_pk_mul_f32 v[88:89], v[82:83], v[74:75] op_sel_hi:[0,1]
	v_pk_mul_f32 v[90:91], v[82:83], v[72:73] op_sel_hi:[0,1]
	ds_read_b128 v[72:75], v244 offset:128
	ds_read_b128 v[84:87], v244 offset:384
	v_and_b32_e32 v79, 0xffff0000, v78
	s_waitcnt lgkmcnt(0)
	v_pk_fma_f32 v[72:73], v[72:73], v[90:91], v[84:85]
	v_mov_b64_e32 v[84:85], v[204:205]
	v_lshrrev_b32_e32 v245, 4, v219
	v_lshl_add_u32 v245, v245, 3, v243
	global_load_dwordx4 v[202:205], v245, s[70:71] offset:256
	v_pk_fma_f32 v[74:75], v[74:75], v[88:89], v[86:87]
	v_pk_fma_f32 v[56:57], v[72:73], s[72:73], v[56:57] op_sel_hi:[1,0,1]
	v_pk_fma_f32 v[58:59], v[74:75], s[72:73], v[58:59] op_sel_hi:[1,0,1]
	v_cvt_pk_bf16_f32 v56, v56, v57
	v_cvt_pk_bf16_f32 v57, v58, v59
	v_mov_b64_e32 v[148:149], v[56:57]
	v_lshlrev_b32_e32 v72, 16, v56
	v_and_b32_e32 v74, 0xffff0000, v56
	v_lshlrev_b32_e32 v56, 16, v57
	v_and_b32_e32 v58, 0xffff0000, v57
	v_mul_f32_e32 v73, v72, v72
	v_mul_f32_e32 v75, v74, v74
	v_mul_f32_e32 v57, v56, v56
	v_mul_f32_e32 v59, v58, v58
	v_pk_add_f32 v[56:57], v[56:57], v[58:59]
	s_waitcnt lgkmcnt(0)
	v_lshlrev_b32_e32 v3, 16, v84
	v_and_b32_e32 v60, 0xffff0000, v84
	v_lshlrev_b32_e32 v65, 16, v85
	v_and_b32_e32 v67, 0xffff0000, v85
	v_sub_f32_e32 v85, v60, v80
	v_sub_f32_e32 v84, v3, v80
	v_sub_f32_e32 v81, v67, v80
	v_sub_f32_e32 v80, v65, v80
	v_pk_mul_f32 v[80:81], v[82:83], v[80:81] op_sel_hi:[0,1]
	v_pk_mul_f32 v[82:83], v[82:83], v[84:85] op_sel_hi:[0,1]
	ds_read_b128 v[84:87], v244 offset:192
	ds_read_b128 v[88:91], v244 offset:448
	v_mov_b32_e32 v65, v79
	v_mov_b32_e32 v3, v61
	s_waitcnt lgkmcnt(0)
	v_pk_fma_f32 v[82:83], v[84:85], v[82:83], v[88:89]
	s_nop 0
	v_pk_fma_f32 v[52:53], v[82:83], s[72:73], v[52:53] op_sel_hi:[1,0,1]
	v_lshlrev_b32_e32 v83, 16, v78
	v_lshlrev_b32_e32 v82, 16, v70
	v_mov_b32_e32 v67, v83
	v_pk_fma_f32 v[80:81], v[86:87], v[80:81], v[90:91]
	v_pk_mul_f32 v[84:85], v[82:83], v[82:83]
	v_pk_mul_f32 v[86:87], v[66:67], v[66:67]
	v_and_b32_e32 v78, 0xffff0000, v71
	v_pk_mul_f32 v[70:71], v[64:65], v[64:65]
	v_pk_mul_f32 v[88:89], v[78:79], v[78:79]
	v_pk_mov_b32 v[90:91], v[82:83], v[84:85] op_sel:[1,0]
	v_pk_mov_b32 v[86:87], v[78:79], v[86:87] op_sel:[1,0]
	v_pk_add_f32 v[66:67], v[82:83], v[66:67]
	v_pk_add_f32 v[64:65], v[78:79], v[64:65]
	v_pk_fma_f32 v[54:55], v[80:81], s[72:73], v[54:55] op_sel_hi:[1,0,1]
	v_pk_add_f32 v[86:87], v[90:91], v[86:87]
	v_mov_b32_e32 v90, v62
	v_mov_b32_e32 v91, v70
	v_pk_mov_b32 v[62:63], v[62:63], v[88:89] op_sel:[1,0]
	v_mov_b32_e32 v67, v85
	v_mov_b32_e32 v65, v89
	v_cvt_pk_bf16_f32 v52, v52, v53
	v_cvt_pk_bf16_f32 v53, v54, v55
	v_pk_add_f32 v[62:63], v[90:91], v[62:63]
	v_pk_add_f32 v[64:65], v[66:67], v[64:65]
	v_mov_b64_e32 v[150:151], v[52:53]
	v_lshrrev_b32_e32 v152, 4, v219
	v_lshlrev_b32_e32 v152, 3, v152
	v_mov_b32_e32 v153, v2
	v_permlane32_swap_b32_e32 v148, v150
	v_permlane32_swap_b32_e32 v149, v151
	v_lshl_add_u64 v[152:153], v[152:153], 0, v[76:77]
	s_nop 0
	v_permlane16_swap_b32_e32 v148, v150
	v_permlane16_swap_b32_e32 v149, v151
	global_store_dwordx4 v[152:153], v[148:151], off offset:256 sc0
	v_lshlrev_b32_e32 v76, 16, v52
	v_and_b32_e32 v80, 0xffff0000, v52
	v_lshlrev_b32_e32 v52, 16, v53
	v_and_b32_e32 v54, 0xffff0000, v53
	v_pk_add_f32 v[62:63], v[86:87], v[62:63]
	v_pk_add_f32 v[60:61], v[64:65], v[2:3]
	v_mul_f32_e32 v77, v76, v76
	v_mul_f32_e32 v81, v80, v80
	v_mul_f32_e32 v53, v52, v52
	v_mul_f32_e32 v55, v54, v54
	v_pk_add_f32 v[60:61], v[62:63], v[60:61]
	v_pk_add_f32 v[62:63], v[72:73], v[74:75]
	v_pk_add_f32 v[58:59], v[76:77], v[80:81]
	v_pk_add_f32 v[56:57], v[62:63], v[56:57]
	v_pk_add_f32 v[52:53], v[52:53], v[54:55]
	v_pk_add_f32 v[56:57], v[60:61], v[56:57]
	v_pk_add_f32 v[52:53], v[58:59], v[52:53]
	s_nop 0
	v_pk_add_f32 v[52:53], v[56:57], v[52:53]
	ds_bpermute_b32 v54, v181, v52
	ds_bpermute_b32 v55, v181, v53
	s_waitcnt lgkmcnt(0)
	v_pk_add_f32 v[52:53], v[52:53], v[54:55]
	ds_bpermute_b32 v54, v180, v52
	ds_bpermute_b32 v55, v180, v53
	s_and_saveexec_b64 s[0:1], s[40:41]
	s_cbranch_execz .LBB0_2387
	v_lshl_add_u64 v[56:57], s[52:53], 0, v[68:69]
	v_lshl_add_u64 v[56:57], s[68:69], 2, v[56:57]
	s_waitcnt lgkmcnt(0)
	v_pk_add_f32 v[52:53], v[52:53], v[54:55]
	global_store_dwordx2 v[56:57], v[52:53], off
; __device__ __forceinline__ u32x2 pk4(f32x4 v) { u32x2 r; r.x = pk2(v.x, v.y); r.y = pk2(v.z, v.w); return r; }
; __device__ __forceinline__ void stats_main(const float* stm, int row, int fq, float& mu, float& rs) {
;     const f32x4* p = (const f32x4*)(stm + (size_t)row * 32 + fq * 8);
;     const f32x4 a = p[0], b = p[1];
;     float s1 = (a.x + a.z) + (b.x + b.z), s2 = (a.y + a.w) + (b.y + b.w);
;     s1 += __shfl_xor(s1, 16); s2 += __shfl_xor(s2, 16); s1 += __shfl_xor(s1, 32); s2 += __shfl_xor(s2, 32);
;     mu = s1 * (1.f / DM); rs = __builtin_amdgcn_rsqf(fmaxf(s2 * (1.f / DM) - mu * mu, 0.f) + LN_EPS);
; }
;     __device__ __forceinline__ void operator()(const f32x4 (&acc)[2][2][4][2], const pg8::Unit& u, int wr, int wc, int fr, int fq) const {
;     ...
;                 const int row = u.pm * 256 + ai * 128 + wr * 64 + m * 16 + fr;
;                 float mu = 0.f, rs = 1.f; if (ln) stats_main(stm_p, row, fq, mu, rs);
;                 float s1 = 0.f, s2 = 0.f;
; #pragma unroll
;                 for (int bj = 0; bj < 2; ++bj)
; #pragma unroll
;                     for (int n = 0; n < 2; ++n) {
;                         const int col = u.pn * 256 + bj * 128 + wc * 32 + n * 16 + fq * 4;
;                         const u32x2 raw = *(const u32x2*)(src + (size_t)row * DM + col);
;                         f32x4 x = (f32x4){bflo(raw.x), bfhi(raw.x), bflo(raw.y), bfhi(raw.y)};
;                         if (ln) x = (x - mu) * rs * *(const f32x4*)(g + col) + *(const f32x4*)(b + col);
;                         const u32x2 pz = pk4(x * ALPHA + acc[ai][bj][m][n]);
;                         *(u32x2*)(dst + (size_t)row * DM + col) = pz;
;                         const float z0 = bflo(pz.x), z1 = bfhi(pz.x), z2 = bflo(pz.y), z3 = bfhi(pz.y);
;                         s1 += (z0 + z1) + (z2 + z3); s2 += (z0 * z0 + z1 * z1) + (z2 * z2 + z3 * z3);
;                     }
;                 s1 += __shfl_xor(s1, 16); s2 += __shfl_xor(s2, 16); s1 += __shfl_xor(s1, 32); s2 += __shfl_xor(s2, 32);
;                 if (fq == 0) { float* p = stm_n + (size_t)row * 32 + (u.pn * 4 + wc) * 2; p[0] = s1; p[1] = s2; }
.LBB0_2387:
	s_or_b64 exec, exec, s[0:1]
	v_add_u32_e32 v62, 0x90, v146
	v_ashrrev_i32_e32 v63, 31, v62
	v_lshlrev_b64 v[52:53], 7, v[62:63]
	v_lshl_add_u64 v[58:59], v[134:135], 0, v[52:53]
	s_waitcnt lgkmcnt(0)
	s_waitcnt vmcnt(7)
	v_mov_b64_e32 v[54:55], v[206:207]
	v_mov_b64_e32 v[56:57], v[208:209]
	global_load_dwordx4 v[206:209], v[248:249], off offset:2064
	s_nop 0
	s_waitcnt vmcnt(7)
	v_mov_b64_e32 v[58:59], v[214:215]
	v_mov_b64_e32 v[60:61], v[216:217]
	global_load_dwordx4 v[214:217], v[248:249], off offset:2048
	s_waitcnt lgkmcnt(0)
	v_pk_add_f32 v[54:55], v[54:55], v[56:57]
	s_waitcnt lgkmcnt(0)
	v_pk_add_f32 v[58:59], v[58:59], v[60:61]
	s_nop 0
	v_pk_add_f32 v[54:55], v[58:59], v[54:55]
	ds_bpermute_b32 v56, v181, v54
	ds_bpermute_b32 v57, v181, v55
	s_waitcnt lgkmcnt(0)
	v_pk_add_f32 v[54:55], v[54:55], v[56:57]
	ds_bpermute_b32 v56, v180, v54
	ds_bpermute_b32 v57, v180, v55
	s_waitcnt lgkmcnt(0)
	v_pk_add_f32 v[54:55], v[54:55], v[56:57]
	s_nop 0
	v_pk_mul_f32 v[64:65], v[54:55], s[82:83] op_sel_hi:[1,0]
	v_lshlrev_b64 v[54:55], 11, v[62:63]
	v_lshl_add_u64 v[54:55], s[70:71], 0, v[54:55]
	v_lshl_add_u64 v[60:61], v[144:145], 1, v[54:55]
	v_add_u32_e32 v243, 0x58000, v242
	s_waitcnt vmcnt(7)
	v_permlane16_swap_b32_e32 v234, v236
	v_permlane16_swap_b32_e32 v235, v237
	s_nop 0
	v_permlane32_swap_b32_e32 v234, v236
	v_permlane32_swap_b32_e32 v235, v237
	v_mov_b64_e32 v[54:55], v[234:235]
	v_fma_f32 v3, -v64, v64, v65
	v_max_f32_e32 v3, 0, v3
	v_add_f32_e32 v3, 0x3727c5ac, v3
	v_rsq_f32_e32 v66, v3
	s_waitcnt lgkmcnt(0)
	v_lshlrev_b32_e32 v3, 16, v54
	v_and_b32_e32 v54, 0xffff0000, v54
	v_lshlrev_b32_e32 v56, 16, v55
	v_and_b32_e32 v57, 0xffff0000, v55
	v_sub_f32_e32 v55, v54, v64
	v_sub_f32_e32 v54, v3, v64
	v_sub_f32_e32 v57, v57, v64
	v_sub_f32_e32 v56, v56, v64
	v_pk_mul_f32 v[58:59], v[56:57], v[66:67] op_sel_hi:[1,0]
	v_pk_mul_f32 v[62:63], v[54:55], v[66:67] op_sel_hi:[1,0]
	ds_read_b128 v[54:57], v244
	ds_read_b128 v[68:71], v244 offset:256
	s_waitcnt lgkmcnt(0)
	v_pk_fma_f32 v[56:57], v[56:57], v[58:59], v[70:71]
	s_nop 0
	v_pk_fma_f32 v[50:51], v[56:57], s[72:73], v[50:51] op_sel_hi:[1,0,1]
	v_mov_b64_e32 v[56:57], v[236:237]
	v_lshrrev_b32_e32 v245, 4, v219
	v_lshl_add_u32 v245, v245, 3, v243
	global_load_dwordx4 v[234:237], v245, s[70:71]
	v_pk_fma_f32 v[54:55], v[54:55], v[62:63], v[68:69]
	s_waitcnt lgkmcnt(0)
	v_lshlrev_b32_e32 v3, 16, v56
	v_pk_fma_f32 v[48:49], v[54:55], s[72:73], v[48:49] op_sel_hi:[1,0,1]
	v_cvt_pk_bf16_f32 v55, v50, v51
	v_cvt_pk_bf16_f32 v54, v48, v49
	v_and_b32_e32 v49, 0xffff0000, v56
	v_lshlrev_b32_e32 v51, 16, v57
	v_and_b32_e32 v58, 0xffff0000, v57
	v_mov_b64_e32 v[148:149], v[54:55]
	v_sub_f32_e32 v57, v49, v64
	v_sub_f32_e32 v56, v3, v64
	v_sub_f32_e32 v59, v58, v64
	v_sub_f32_e32 v58, v51, v64
	v_pk_mul_f32 v[62:63], v[66:67], v[58:59] op_sel_hi:[0,1]
	v_pk_mul_f32 v[72:73], v[66:67], v[56:57] op_sel_hi:[0,1]
	ds_read_b128 v[56:59], v244 offset:64
	ds_read_b128 v[68:71], v244 offset:320
	v_and_b32_e32 v50, 0xffff0000, v54
	v_lshlrev_b32_e32 v48, 16, v55
	s_waitcnt lgkmcnt(0)
	v_pk_fma_f32 v[56:57], v[56:57], v[72:73], v[68:69]
	s_nop 0
	v_pk_fma_f32 v[44:45], v[56:57], s[72:73], v[44:45] op_sel_hi:[1,0,1]
	s_waitcnt vmcnt(7)
	v_permlane16_swap_b32_e32 v238, v240
	v_permlane16_swap_b32_e32 v239, v241
	s_nop 0
	v_permlane32_swap_b32_e32 v238, v240
	v_permlane32_swap_b32_e32 v239, v241
	v_mov_b64_e32 v[56:57], v[238:239]
	v_pk_fma_f32 v[58:59], v[58:59], v[62:63], v[70:71]
	v_cvt_pk_bf16_f32 v62, v44, v45
	v_pk_fma_f32 v[46:47], v[58:59], s[72:73], v[46:47] op_sel_hi:[1,0,1]
	s_waitcnt lgkmcnt(0)
	v_lshlrev_b32_e32 v3, 16, v56
	v_cvt_pk_bf16_f32 v63, v46, v47
	v_lshlrev_b32_e32 v46, 16, v63
	v_and_b32_e32 v47, 0xffff0000, v63
	v_mul_f32_e32 v44, v46, v46
	v_pk_fma_f32 v[44:45], v[46:47], v[46:47], v[44:45] op_sel_hi:[1,1,0]
	v_lshlrev_b32_e32 v49, 16, v57
	v_and_b32_e32 v44, 0xffff0000, v56
	v_and_b32_e32 v51, 0xffff0000, v57
	v_mov_b64_e32 v[150:151], v[62:63]
	v_lshrrev_b32_e32 v74, 4, v219
	v_lshlrev_b32_e32 v74, 3, v74
	v_mov_b32_e32 v75, v2
	v_permlane32_swap_b32_e32 v148, v150
	v_permlane32_swap_b32_e32 v149, v151
	v_lshl_add_u64 v[74:75], v[74:75], 0, v[60:61]
	s_nop 0
	v_permlane16_swap_b32_e32 v148, v150
	v_permlane16_swap_b32_e32 v149, v151
	global_store_dwordx4 v[74:75], v[148:151], off sc0
	v_sub_f32_e32 v57, v44, v64
	v_sub_f32_e32 v56, v3, v64
	v_sub_f32_e32 v59, v51, v64
	v_sub_f32_e32 v58, v49, v64
	v_pk_mul_f32 v[72:73], v[66:67], v[58:59] op_sel_hi:[0,1]
	v_pk_mul_f32 v[74:75], v[66:67], v[56:57] op_sel_hi:[0,1]
	ds_read_b128 v[56:59], v244 offset:128
	ds_read_b128 v[68:71], v244 offset:384
	v_and_b32_e32 v63, 0xffff0000, v62
	s_waitcnt lgkmcnt(0)
	v_pk_fma_f32 v[56:57], v[56:57], v[74:75], v[68:69]
	v_mov_b64_e32 v[68:69], v[240:241]
	v_lshrrev_b32_e32 v245, 4, v219
	v_lshl_add_u32 v245, v245, 3, v243
	global_load_dwordx4 v[238:241], v245, s[70:71] offset:256
	v_pk_fma_f32 v[58:59], v[58:59], v[72:73], v[70:71]
	v_pk_fma_f32 v[40:41], v[56:57], s[72:73], v[40:41] op_sel_hi:[1,0,1]
	v_pk_fma_f32 v[42:43], v[58:59], s[72:73], v[42:43] op_sel_hi:[1,0,1]
	v_cvt_pk_bf16_f32 v40, v40, v41
	v_cvt_pk_bf16_f32 v41, v42, v43
	v_mov_b64_e32 v[148:149], v[40:41]
	v_lshlrev_b32_e32 v56, 16, v40
	v_and_b32_e32 v58, 0xffff0000, v40
	v_lshlrev_b32_e32 v40, 16, v41
	v_and_b32_e32 v42, 0xffff0000, v41
	v_mul_f32_e32 v57, v56, v56
	v_mul_f32_e32 v59, v58, v58
	v_mul_f32_e32 v41, v40, v40
	v_mul_f32_e32 v43, v42, v42
	v_pk_add_f32 v[40:41], v[40:41], v[42:43]
	s_waitcnt lgkmcnt(0)
; __device__ __forceinline__ u32x2 pk4(f32x4 v) { u32x2 r; r.x = pk2(v.x, v.y); r.y = pk2(v.z, v.w); return r; }
; __device__ __forceinline__ void stats_main(const float* stm, int row, int fq, float& mu, float& rs) {
;     const f32x4* p = (const f32x4*)(stm + (size_t)row * 32 + fq * 8);
;     const f32x4 a = p[0], b = p[1];
;     float s1 = (a.x + a.z) + (b.x + b.z), s2 = (a.y + a.w) + (b.y + b.w);
;     s1 += __shfl_xor(s1, 16); s2 += __shfl_xor(s2, 16); s1 += __shfl_xor(s1, 32); s2 += __shfl_xor(s2, 32);
;     mu = s1 * (1.f / DM); rs = __builtin_amdgcn_rsqf(fmaxf(s2 * (1.f / DM) - mu * mu, 0.f) + LN_EPS);
; }
;     __device__ __forceinline__ void operator()(const f32x4 (&acc)[2][2][4][2], const pg8::Unit& u, int wr, int wc, int fr, int fq) const {
;     ...
;                 const int row = u.pm * 256 + ai * 128 + wr * 64 + m * 16 + fr;
;                 float mu = 0.f, rs = 1.f; if (ln) stats_main(stm_p, row, fq, mu, rs);
;                 float s1 = 0.f, s2 = 0.f;
; #pragma unroll
;                 for (int bj = 0; bj < 2; ++bj)
; #pragma unroll
;                     for (int n = 0; n < 2; ++n) {
;                         const int col = u.pn * 256 + bj * 128 + wc * 32 + n * 16 + fq * 4;
;                         const u32x2 raw = *(const u32x2*)(src + (size_t)row * DM + col);
;                         f32x4 x = (f32x4){bflo(raw.x), bfhi(raw.x), bflo(raw.y), bfhi(raw.y)};
;                         if (ln) x = (x - mu) * rs * *(const f32x4*)(g + col) + *(const f32x4*)(b + col);
;                         const u32x2 pz = pk4(x * ALPHA + acc[ai][bj][m][n]);
;                         *(u32x2*)(dst + (size_t)row * DM + col) = pz;
;                         const float z0 = bflo(pz.x), z1 = bfhi(pz.x), z2 = bflo(pz.y), z3 = bfhi(pz.y);
;                         s1 += (z0 + z1) + (z2 + z3); s2 += (z0 * z0 + z1 * z1) + (z2 * z2 + z3 * z3);
;                     }
;                 s1 += __shfl_xor(s1, 16); s2 += __shfl_xor(s2, 16); s1 += __shfl_xor(s1, 32); s2 += __shfl_xor(s2, 32);
;                 if (fq == 0) { float* p = stm_n + (size_t)row * 32 + (u.pn * 4 + wc) * 2; p[0] = s1; p[1] = s2; }
	v_lshlrev_b32_e32 v3, 16, v68
	v_and_b32_e32 v44, 0xffff0000, v68
	v_lshlrev_b32_e32 v49, 16, v69
	v_and_b32_e32 v51, 0xffff0000, v69
	v_sub_f32_e32 v69, v44, v64
	v_sub_f32_e32 v68, v3, v64
	v_sub_f32_e32 v65, v51, v64
	v_sub_f32_e32 v64, v49, v64
	v_pk_mul_f32 v[64:65], v[66:67], v[64:65] op_sel_hi:[0,1]
	v_pk_mul_f32 v[66:67], v[66:67], v[68:69] op_sel_hi:[0,1]
	ds_read_b128 v[68:71], v244 offset:192
	ds_read_b128 v[72:75], v244 offset:448
	v_mov_b32_e32 v49, v63
	v_mov_b32_e32 v3, v45
	s_waitcnt lgkmcnt(0)
	v_pk_fma_f32 v[66:67], v[68:69], v[66:67], v[72:73]
	s_nop 0
	v_pk_fma_f32 v[36:37], v[66:67], s[72:73], v[36:37] op_sel_hi:[1,0,1]
	v_lshlrev_b32_e32 v67, 16, v62
	v_lshlrev_b32_e32 v66, 16, v54
	v_mov_b32_e32 v51, v67
	v_pk_fma_f32 v[64:65], v[70:71], v[64:65], v[74:75]
	v_pk_mul_f32 v[68:69], v[66:67], v[66:67]
	v_pk_mul_f32 v[70:71], v[50:51], v[50:51]
	v_and_b32_e32 v62, 0xffff0000, v55
	v_pk_mul_f32 v[54:55], v[48:49], v[48:49]
	v_pk_mul_f32 v[72:73], v[62:63], v[62:63]
	v_pk_mov_b32 v[74:75], v[66:67], v[68:69] op_sel:[1,0]
	v_pk_mov_b32 v[70:71], v[62:63], v[70:71] op_sel:[1,0]
	v_pk_add_f32 v[50:51], v[66:67], v[50:51]
	v_pk_add_f32 v[48:49], v[62:63], v[48:49]
	v_pk_fma_f32 v[38:39], v[64:65], s[72:73], v[38:39] op_sel_hi:[1,0,1]
	v_pk_add_f32 v[70:71], v[74:75], v[70:71]
	v_mov_b32_e32 v74, v46
	v_mov_b32_e32 v75, v54
	v_pk_mov_b32 v[46:47], v[46:47], v[72:73] op_sel:[1,0]
	v_mov_b32_e32 v51, v69
	v_mov_b32_e32 v49, v73
	v_cvt_pk_bf16_f32 v36, v36, v37
	v_cvt_pk_bf16_f32 v37, v38, v39
	v_pk_add_f32 v[46:47], v[74:75], v[46:47]
	v_pk_add_f32 v[48:49], v[50:51], v[48:49]
	v_mov_b64_e32 v[150:151], v[36:37]
	v_lshrrev_b32_e32 v152, 4, v219
	v_lshlrev_b32_e32 v152, 3, v152
	v_mov_b32_e32 v153, v2
	v_permlane32_swap_b32_e32 v148, v150
	v_permlane32_swap_b32_e32 v149, v151
	v_lshl_add_u64 v[152:153], v[152:153], 0, v[60:61]
	s_nop 0
	v_permlane16_swap_b32_e32 v148, v150
	v_permlane16_swap_b32_e32 v149, v151
	global_store_dwordx4 v[152:153], v[148:151], off offset:256 sc0
	v_lshlrev_b32_e32 v60, 16, v36
	v_and_b32_e32 v64, 0xffff0000, v36
	v_lshlrev_b32_e32 v36, 16, v37
	v_and_b32_e32 v38, 0xffff0000, v37
	v_pk_add_f32 v[46:47], v[70:71], v[46:47]
	v_pk_add_f32 v[44:45], v[48:49], v[2:3]
	v_mul_f32_e32 v61, v60, v60
	v_mul_f32_e32 v65, v64, v64
	v_mul_f32_e32 v37, v36, v36
	v_mul_f32_e32 v39, v38, v38
	v_pk_add_f32 v[44:45], v[46:47], v[44:45]
	v_pk_add_f32 v[46:47], v[56:57], v[58:59]
	v_pk_add_f32 v[42:43], v[60:61], v[64:65]
	v_pk_add_f32 v[40:41], v[46:47], v[40:41]
	v_pk_add_f32 v[36:37], v[36:37], v[38:39]
	v_pk_add_f32 v[40:41], v[44:45], v[40:41]
	v_pk_add_f32 v[36:37], v[42:43], v[36:37]
	s_nop 0
	v_pk_add_f32 v[36:37], v[40:41], v[36:37]
	ds_bpermute_b32 v38, v181, v36
	ds_bpermute_b32 v39, v181, v37
	s_waitcnt lgkmcnt(0)
	v_pk_add_f32 v[36:37], v[36:37], v[38:39]
	ds_bpermute_b32 v38, v180, v36
	ds_bpermute_b32 v39, v180, v37
	s_and_saveexec_b64 s[0:1], s[40:41]
	s_cbranch_execz .LBB0_2389
	v_lshl_add_u64 v[40:41], s[52:53], 0, v[52:53]
	v_lshl_add_u64 v[40:41], s[68:69], 2, v[40:41]
	s_waitcnt lgkmcnt(0)
	v_pk_add_f32 v[36:37], v[36:37], v[38:39]
	global_store_dwordx2 v[40:41], v[36:37], off
.LBB0_2389:
	s_or_b64 exec, exec, s[0:1]
	v_add_u32_e32 v46, 0xa0, v146
	v_ashrrev_i32_e32 v47, 31, v46
	v_lshlrev_b64 v[36:37], 7, v[46:47]
	v_lshl_add_u64 v[42:43], v[134:135], 0, v[36:37]
	s_waitcnt lgkmcnt(0)
	s_waitcnt vmcnt(7)
	v_mov_b64_e32 v[38:39], v[190:191]
	v_mov_b64_e32 v[40:41], v[192:193]
	s_nop 0
	s_waitcnt vmcnt(6)
	v_mov_b64_e32 v[42:43], v[194:195]
	v_mov_b64_e32 v[44:45], v[196:197]
	s_waitcnt lgkmcnt(0)
	v_pk_add_f32 v[38:39], v[38:39], v[40:41]
	s_waitcnt lgkmcnt(0)
	v_pk_add_f32 v[42:43], v[42:43], v[44:45]
	s_nop 0
	v_pk_add_f32 v[38:39], v[42:43], v[38:39]
	ds_bpermute_b32 v40, v181, v38
	ds_bpermute_b32 v41, v181, v39
	s_waitcnt lgkmcnt(0)
	v_pk_add_f32 v[38:39], v[38:39], v[40:41]
	ds_bpermute_b32 v40, v180, v38
	ds_bpermute_b32 v41, v180, v39
	s_waitcnt lgkmcnt(0)
	v_pk_add_f32 v[38:39], v[38:39], v[40:41]
	s_nop 0
	v_pk_mul_f32 v[48:49], v[38:39], s[82:83] op_sel_hi:[1,0]
	v_lshlrev_b64 v[38:39], 11, v[46:47]
	v_lshl_add_u64 v[38:39], s[70:71], 0, v[38:39]
	v_lshl_add_u64 v[44:45], v[144:145], 1, v[38:39]
	s_waitcnt vmcnt(5)
	v_permlane16_swap_b32_e32 v198, v200
	v_permlane16_swap_b32_e32 v199, v201
	s_nop 0
	v_permlane32_swap_b32_e32 v198, v200
	v_permlane32_swap_b32_e32 v199, v201
	v_mov_b64_e32 v[38:39], v[198:199]
	v_fma_f32 v3, -v48, v48, v49
	v_max_f32_e32 v3, 0, v3
	v_add_f32_e32 v3, 0x3727c5ac, v3
	v_rsq_f32_e32 v50, v3
	s_waitcnt lgkmcnt(0)
	v_lshlrev_b32_e32 v3, 16, v38
	v_and_b32_e32 v38, 0xffff0000, v38
	v_lshlrev_b32_e32 v40, 16, v39
	v_and_b32_e32 v41, 0xffff0000, v39
	v_sub_f32_e32 v39, v38, v48
	v_sub_f32_e32 v38, v3, v48
	v_sub_f32_e32 v41, v41, v48
	v_sub_f32_e32 v40, v40, v48
	v_pk_mul_f32 v[42:43], v[40:41], v[50:51] op_sel_hi:[1,0]
	v_pk_mul_f32 v[46:47], v[38:39], v[50:51] op_sel_hi:[1,0]
	ds_read_b128 v[38:41], v244
	ds_read_b128 v[52:55], v244 offset:256
	s_waitcnt lgkmcnt(0)
	v_pk_fma_f32 v[40:41], v[40:41], v[42:43], v[54:55]
	s_nop 0
	v_pk_fma_f32 v[34:35], v[40:41], s[72:73], v[34:35] op_sel_hi:[1,0,1]
	v_mov_b64_e32 v[40:41], v[200:201]
	v_pk_fma_f32 v[38:39], v[38:39], v[46:47], v[52:53]
	s_waitcnt lgkmcnt(0)
	v_lshlrev_b32_e32 v3, 16, v40
	v_pk_fma_f32 v[32:33], v[38:39], s[72:73], v[32:33] op_sel_hi:[1,0,1]
	v_cvt_pk_bf16_f32 v39, v34, v35
	v_cvt_pk_bf16_f32 v38, v32, v33
	v_and_b32_e32 v33, 0xffff0000, v40
	v_lshlrev_b32_e32 v35, 16, v41
	v_and_b32_e32 v42, 0xffff0000, v41
	v_mov_b64_e32 v[148:149], v[38:39]
	v_sub_f32_e32 v41, v33, v48
	v_sub_f32_e32 v40, v3, v48
	v_sub_f32_e32 v43, v42, v48
	v_sub_f32_e32 v42, v35, v48
	v_pk_mul_f32 v[46:47], v[50:51], v[42:43] op_sel_hi:[0,1]
	v_pk_mul_f32 v[56:57], v[50:51], v[40:41] op_sel_hi:[0,1]
	ds_read_b128 v[40:43], v244 offset:64
	ds_read_b128 v[52:55], v244 offset:320
	v_and_b32_e32 v34, 0xffff0000, v38
	v_lshlrev_b32_e32 v32, 16, v39
	s_waitcnt lgkmcnt(0)
; __device__ __forceinline__ u32x2 pk4(f32x4 v) { u32x2 r; r.x = pk2(v.x, v.y); r.y = pk2(v.z, v.w); return r; }
; __device__ __forceinline__ void stats_main(const float* stm, int row, int fq, float& mu, float& rs) {
;     const f32x4* p = (const f32x4*)(stm + (size_t)row * 32 + fq * 8);
;     const f32x4 a = p[0], b = p[1];
;     float s1 = (a.x + a.z) + (b.x + b.z), s2 = (a.y + a.w) + (b.y + b.w);
;     s1 += __shfl_xor(s1, 16); s2 += __shfl_xor(s2, 16); s1 += __shfl_xor(s1, 32); s2 += __shfl_xor(s2, 32);
;     mu = s1 * (1.f / DM); rs = __builtin_amdgcn_rsqf(fmaxf(s2 * (1.f / DM) - mu * mu, 0.f) + LN_EPS);
; }
;     __device__ __forceinline__ void operator()(const f32x4 (&acc)[2][2][4][2], const pg8::Unit& u, int wr, int wc, int fr, int fq) const {
;     ...
;                 const int row = u.pm * 256 + ai * 128 + wr * 64 + m * 16 + fr;
;                 float mu = 0.f, rs = 1.f; if (ln) stats_main(stm_p, row, fq, mu, rs);
;                 float s1 = 0.f, s2 = 0.f;
; #pragma unroll
;                 for (int bj = 0; bj < 2; ++bj)
; #pragma unroll
;                     for (int n = 0; n < 2; ++n) {
;                         const int col = u.pn * 256 + bj * 128 + wc * 32 + n * 16 + fq * 4;
;                         const u32x2 raw = *(const u32x2*)(src + (size_t)row * DM + col);
;                         f32x4 x = (f32x4){bflo(raw.x), bfhi(raw.x), bflo(raw.y), bfhi(raw.y)};
;                         if (ln) x = (x - mu) * rs * *(const f32x4*)(g + col) + *(const f32x4*)(b + col);
;                         const u32x2 pz = pk4(x * ALPHA + acc[ai][bj][m][n]);
;                         *(u32x2*)(dst + (size_t)row * DM + col) = pz;
;                         const float z0 = bflo(pz.x), z1 = bfhi(pz.x), z2 = bflo(pz.y), z3 = bfhi(pz.y);
;                         s1 += (z0 + z1) + (z2 + z3); s2 += (z0 * z0 + z1 * z1) + (z2 * z2 + z3 * z3);
;                     }
;                 s1 += __shfl_xor(s1, 16); s2 += __shfl_xor(s2, 16); s1 += __shfl_xor(s1, 32); s2 += __shfl_xor(s2, 32);
;                 if (fq == 0) { float* p = stm_n + (size_t)row * 32 + (u.pn * 4 + wc) * 2; p[0] = s1; p[1] = s2; }
	v_pk_fma_f32 v[40:41], v[40:41], v[56:57], v[52:53]
	s_nop 0
	v_pk_fma_f32 v[28:29], v[40:41], s[72:73], v[28:29] op_sel_hi:[1,0,1]
	s_waitcnt vmcnt(4)
	v_permlane16_swap_b32_e32 v202, v204
	v_permlane16_swap_b32_e32 v203, v205
	s_nop 0
	v_permlane32_swap_b32_e32 v202, v204
	v_permlane32_swap_b32_e32 v203, v205
	v_mov_b64_e32 v[40:41], v[202:203]
	v_pk_fma_f32 v[42:43], v[42:43], v[46:47], v[54:55]
	v_cvt_pk_bf16_f32 v46, v28, v29
	v_pk_fma_f32 v[30:31], v[42:43], s[72:73], v[30:31] op_sel_hi:[1,0,1]
	s_waitcnt lgkmcnt(0)
	v_lshlrev_b32_e32 v3, 16, v40
	v_cvt_pk_bf16_f32 v47, v30, v31
	v_lshlrev_b32_e32 v30, 16, v47
	v_and_b32_e32 v31, 0xffff0000, v47
	v_mul_f32_e32 v28, v30, v30
	v_pk_fma_f32 v[28:29], v[30:31], v[30:31], v[28:29] op_sel_hi:[1,1,0]
	v_lshlrev_b32_e32 v33, 16, v41
	v_and_b32_e32 v28, 0xffff0000, v40
	v_and_b32_e32 v35, 0xffff0000, v41
	v_mov_b64_e32 v[150:151], v[46:47]
	v_lshrrev_b32_e32 v58, 4, v219
	v_lshlrev_b32_e32 v58, 3, v58
	v_mov_b32_e32 v59, v2
	v_permlane32_swap_b32_e32 v148, v150
	v_permlane32_swap_b32_e32 v149, v151
	v_lshl_add_u64 v[58:59], v[58:59], 0, v[44:45]
	s_nop 0
	v_permlane16_swap_b32_e32 v148, v150
	v_permlane16_swap_b32_e32 v149, v151
	global_store_dwordx4 v[58:59], v[148:151], off sc0
	v_sub_f32_e32 v41, v28, v48
	v_sub_f32_e32 v40, v3, v48
	v_sub_f32_e32 v43, v35, v48
	v_sub_f32_e32 v42, v33, v48
	v_pk_mul_f32 v[56:57], v[50:51], v[42:43] op_sel_hi:[0,1]
	v_pk_mul_f32 v[58:59], v[50:51], v[40:41] op_sel_hi:[0,1]
	ds_read_b128 v[40:43], v244 offset:128
	ds_read_b128 v[52:55], v244 offset:384
	v_and_b32_e32 v47, 0xffff0000, v46
	s_waitcnt lgkmcnt(0)
	v_pk_fma_f32 v[40:41], v[40:41], v[58:59], v[52:53]
	v_mov_b64_e32 v[52:53], v[204:205]
	v_pk_fma_f32 v[42:43], v[42:43], v[56:57], v[54:55]
	v_pk_fma_f32 v[24:25], v[40:41], s[72:73], v[24:25] op_sel_hi:[1,0,1]
	v_pk_fma_f32 v[26:27], v[42:43], s[72:73], v[26:27] op_sel_hi:[1,0,1]
	v_cvt_pk_bf16_f32 v24, v24, v25
	v_cvt_pk_bf16_f32 v25, v26, v27
	v_mov_b64_e32 v[148:149], v[24:25]
	v_lshlrev_b32_e32 v40, 16, v24
	v_and_b32_e32 v42, 0xffff0000, v24
	v_lshlrev_b32_e32 v24, 16, v25
	v_and_b32_e32 v26, 0xffff0000, v25
	v_mul_f32_e32 v41, v40, v40
	v_mul_f32_e32 v43, v42, v42
	v_mul_f32_e32 v25, v24, v24
	v_mul_f32_e32 v27, v26, v26
	v_pk_add_f32 v[24:25], v[24:25], v[26:27]
	s_waitcnt lgkmcnt(0)
	v_lshlrev_b32_e32 v3, 16, v52
	v_and_b32_e32 v28, 0xffff0000, v52
	v_lshlrev_b32_e32 v33, 16, v53
	v_and_b32_e32 v35, 0xffff0000, v53
	v_sub_f32_e32 v53, v28, v48
	v_sub_f32_e32 v52, v3, v48
	v_sub_f32_e32 v49, v35, v48
	v_sub_f32_e32 v48, v33, v48
	v_pk_mul_f32 v[48:49], v[50:51], v[48:49] op_sel_hi:[0,1]
	v_pk_mul_f32 v[50:51], v[50:51], v[52:53] op_sel_hi:[0,1]
	ds_read_b128 v[52:55], v244 offset:192
	ds_read_b128 v[56:59], v244 offset:448
	v_mov_b32_e32 v33, v47
	v_mov_b32_e32 v3, v29
	s_waitcnt lgkmcnt(0)
	v_pk_fma_f32 v[50:51], v[52:53], v[50:51], v[56:57]
	s_nop 0
	v_pk_fma_f32 v[20:21], v[50:51], s[72:73], v[20:21] op_sel_hi:[1,0,1]
	v_lshlrev_b32_e32 v51, 16, v46
	v_lshlrev_b32_e32 v50, 16, v38
	v_mov_b32_e32 v35, v51
	v_pk_fma_f32 v[48:49], v[54:55], v[48:49], v[58:59]
	v_pk_mul_f32 v[52:53], v[50:51], v[50:51]
	v_pk_mul_f32 v[54:55], v[34:35], v[34:35]
	v_and_b32_e32 v46, 0xffff0000, v39
	v_pk_mul_f32 v[38:39], v[32:33], v[32:33]
	v_pk_mul_f32 v[56:57], v[46:47], v[46:47]
	v_pk_mov_b32 v[58:59], v[50:51], v[52:53] op_sel:[1,0]
	v_pk_mov_b32 v[54:55], v[46:47], v[54:55] op_sel:[1,0]
	v_pk_add_f32 v[34:35], v[50:51], v[34:35]
	v_pk_add_f32 v[32:33], v[46:47], v[32:33]
	v_pk_fma_f32 v[22:23], v[48:49], s[72:73], v[22:23] op_sel_hi:[1,0,1]
	v_pk_add_f32 v[54:55], v[58:59], v[54:55]
	v_mov_b32_e32 v58, v30
	v_mov_b32_e32 v59, v38
	v_pk_mov_b32 v[30:31], v[30:31], v[56:57] op_sel:[1,0]
	v_mov_b32_e32 v35, v53
	v_mov_b32_e32 v33, v57
	v_cvt_pk_bf16_f32 v20, v20, v21
	v_cvt_pk_bf16_f32 v21, v22, v23
	v_pk_add_f32 v[30:31], v[58:59], v[30:31]
	v_pk_add_f32 v[32:33], v[34:35], v[32:33]
	v_mov_b64_e32 v[150:151], v[20:21]
	v_lshrrev_b32_e32 v152, 4, v219
	v_lshlrev_b32_e32 v152, 3, v152
	v_mov_b32_e32 v153, v2
	v_permlane32_swap_b32_e32 v148, v150
	v_permlane32_swap_b32_e32 v149, v151
	v_lshl_add_u64 v[152:153], v[152:153], 0, v[44:45]
	s_nop 0
	v_permlane16_swap_b32_e32 v148, v150
	v_permlane16_swap_b32_e32 v149, v151
	global_store_dwordx4 v[152:153], v[148:151], off offset:256 sc0
	v_lshlrev_b32_e32 v44, 16, v20
	v_and_b32_e32 v48, 0xffff0000, v20
	v_lshlrev_b32_e32 v20, 16, v21
	v_and_b32_e32 v22, 0xffff0000, v21
	v_pk_add_f32 v[30:31], v[54:55], v[30:31]
	v_pk_add_f32 v[28:29], v[32:33], v[2:3]
	v_mul_f32_e32 v45, v44, v44
	v_mul_f32_e32 v49, v48, v48
	v_mul_f32_e32 v21, v20, v20
	v_mul_f32_e32 v23, v22, v22
	v_pk_add_f32 v[28:29], v[30:31], v[28:29]
	v_pk_add_f32 v[30:31], v[40:41], v[42:43]
	v_pk_add_f32 v[26:27], v[44:45], v[48:49]
	v_pk_add_f32 v[24:25], v[30:31], v[24:25]
	v_pk_add_f32 v[20:21], v[20:21], v[22:23]
	v_pk_add_f32 v[24:25], v[28:29], v[24:25]
	v_pk_add_f32 v[20:21], v[26:27], v[20:21]
	s_nop 0
	v_pk_add_f32 v[20:21], v[24:25], v[20:21]
	ds_bpermute_b32 v22, v181, v20
	ds_bpermute_b32 v23, v181, v21
	s_waitcnt lgkmcnt(0)
	v_pk_add_f32 v[20:21], v[20:21], v[22:23]
	ds_bpermute_b32 v22, v180, v20
	ds_bpermute_b32 v23, v180, v21
	s_and_saveexec_b64 s[0:1], s[40:41]
	s_cbranch_execz .LBB0_2391
	v_lshl_add_u64 v[24:25], s[52:53], 0, v[36:37]
	v_lshl_add_u64 v[24:25], s[68:69], 2, v[24:25]
	s_waitcnt lgkmcnt(0)
	v_pk_add_f32 v[20:21], v[20:21], v[22:23]
	global_store_dwordx2 v[24:25], v[20:21], off
; __device__ __forceinline__ u32x2 pk4(f32x4 v) { u32x2 r; r.x = pk2(v.x, v.y); r.y = pk2(v.z, v.w); return r; }
; __device__ __forceinline__ void stats_main(const float* stm, int row, int fq, float& mu, float& rs) {
;     const f32x4* p = (const f32x4*)(stm + (size_t)row * 32 + fq * 8);
;     const f32x4 a = p[0], b = p[1];
;     float s1 = (a.x + a.z) + (b.x + b.z), s2 = (a.y + a.w) + (b.y + b.w);
;     s1 += __shfl_xor(s1, 16); s2 += __shfl_xor(s2, 16); s1 += __shfl_xor(s1, 32); s2 += __shfl_xor(s2, 32);
;     mu = s1 * (1.f / DM); rs = __builtin_amdgcn_rsqf(fmaxf(s2 * (1.f / DM) - mu * mu, 0.f) + LN_EPS);
; }
;     __device__ __forceinline__ void operator()(const f32x4 (&acc)[2][2][4][2], const pg8::Unit& u, int wr, int wc, int fr, int fq) const {
;     ...
;                 const int row = u.pm * 256 + ai * 128 + wr * 64 + m * 16 + fr;
;                 float mu = 0.f, rs = 1.f; if (ln) stats_main(stm_p, row, fq, mu, rs);
;                 float s1 = 0.f, s2 = 0.f;
; #pragma unroll
;                 for (int bj = 0; bj < 2; ++bj)
; #pragma unroll
;                     for (int n = 0; n < 2; ++n) {
;                         const int col = u.pn * 256 + bj * 128 + wc * 32 + n * 16 + fq * 4;
;                         const u32x2 raw = *(const u32x2*)(src + (size_t)row * DM + col);
;                         f32x4 x = (f32x4){bflo(raw.x), bfhi(raw.x), bflo(raw.y), bfhi(raw.y)};
;                         if (ln) x = (x - mu) * rs * *(const f32x4*)(g + col) + *(const f32x4*)(b + col);
;                         const u32x2 pz = pk4(x * ALPHA + acc[ai][bj][m][n]);
;                         *(u32x2*)(dst + (size_t)row * DM + col) = pz;
;                         const float z0 = bflo(pz.x), z1 = bfhi(pz.x), z2 = bflo(pz.y), z3 = bfhi(pz.y);
;                         s1 += (z0 + z1) + (z2 + z3); s2 += (z0 * z0 + z1 * z1) + (z2 * z2 + z3 * z3);
;                     }
;                 s1 += __shfl_xor(s1, 16); s2 += __shfl_xor(s2, 16); s1 += __shfl_xor(s1, 32); s2 += __shfl_xor(s2, 32);
;                 if (fq == 0) { float* p = stm_n + (size_t)row * 32 + (u.pn * 4 + wc) * 2; p[0] = s1; p[1] = s2; }
.LBB0_2391:
	s_or_b64 exec, exec, s[0:1]
	v_add_u32_e32 v30, 0xb0, v146
	v_ashrrev_i32_e32 v31, 31, v30
	v_lshlrev_b64 v[20:21], 7, v[30:31]
	v_lshl_add_u64 v[26:27], v[134:135], 0, v[20:21]
	s_waitcnt lgkmcnt(0)
	s_waitcnt vmcnt(3)
	v_mov_b64_e32 v[22:23], v[206:207]
	v_mov_b64_e32 v[24:25], v[208:209]
	s_nop 0
	s_waitcnt vmcnt(2)
	v_mov_b64_e32 v[26:27], v[214:215]
	v_mov_b64_e32 v[28:29], v[216:217]
	s_waitcnt lgkmcnt(0)
	v_pk_add_f32 v[22:23], v[22:23], v[24:25]
	s_waitcnt lgkmcnt(0)
	v_pk_add_f32 v[26:27], v[26:27], v[28:29]
	s_nop 0
	v_pk_add_f32 v[22:23], v[26:27], v[22:23]
	ds_bpermute_b32 v24, v181, v22
	ds_bpermute_b32 v25, v181, v23
	s_waitcnt lgkmcnt(0)
	v_pk_add_f32 v[22:23], v[22:23], v[24:25]
	ds_bpermute_b32 v24, v180, v22
	ds_bpermute_b32 v25, v180, v23
	s_waitcnt lgkmcnt(0)
	v_pk_add_f32 v[22:23], v[22:23], v[24:25]
	s_nop 0
	v_pk_mul_f32 v[32:33], v[22:23], s[82:83] op_sel_hi:[1,0]
	v_lshlrev_b64 v[22:23], 11, v[30:31]
	v_lshl_add_u64 v[22:23], s[70:71], 0, v[22:23]
	v_lshl_add_u64 v[28:29], v[144:145], 1, v[22:23]
	s_waitcnt vmcnt(1)
	v_permlane16_swap_b32_e32 v234, v236
	v_permlane16_swap_b32_e32 v235, v237
	s_nop 0
	v_permlane32_swap_b32_e32 v234, v236
	v_permlane32_swap_b32_e32 v235, v237
	v_mov_b64_e32 v[22:23], v[234:235]
	v_fma_f32 v3, -v32, v32, v33
	v_max_f32_e32 v3, 0, v3
	v_add_f32_e32 v3, 0x3727c5ac, v3
	v_rsq_f32_e32 v34, v3
	s_waitcnt lgkmcnt(0)
	v_lshlrev_b32_e32 v3, 16, v22
	v_and_b32_e32 v22, 0xffff0000, v22
	v_lshlrev_b32_e32 v24, 16, v23
	v_and_b32_e32 v25, 0xffff0000, v23
	v_sub_f32_e32 v23, v22, v32
	v_sub_f32_e32 v22, v3, v32
	v_sub_f32_e32 v25, v25, v32
	v_sub_f32_e32 v24, v24, v32
	v_pk_mul_f32 v[26:27], v[24:25], v[34:35] op_sel_hi:[1,0]
	v_pk_mul_f32 v[30:31], v[22:23], v[34:35] op_sel_hi:[1,0]
	ds_read_b128 v[22:25], v244
	ds_read_b128 v[36:39], v244 offset:256
	s_waitcnt lgkmcnt(0)
	v_pk_fma_f32 v[24:25], v[24:25], v[26:27], v[38:39]
	s_nop 0
	v_pk_fma_f32 v[18:19], v[24:25], s[72:73], v[18:19] op_sel_hi:[1,0,1]
	v_mov_b64_e32 v[24:25], v[236:237]
	v_pk_fma_f32 v[22:23], v[22:23], v[30:31], v[36:37]
	s_waitcnt lgkmcnt(0)
	v_lshlrev_b32_e32 v3, 16, v24
	v_pk_fma_f32 v[16:17], v[22:23], s[72:73], v[16:17] op_sel_hi:[1,0,1]
	v_cvt_pk_bf16_f32 v23, v18, v19
	v_cvt_pk_bf16_f32 v22, v16, v17
	v_and_b32_e32 v17, 0xffff0000, v24
	v_lshlrev_b32_e32 v19, 16, v25
	v_and_b32_e32 v26, 0xffff0000, v25
	v_mov_b64_e32 v[148:149], v[22:23]
	v_sub_f32_e32 v25, v17, v32
	v_sub_f32_e32 v24, v3, v32
	v_sub_f32_e32 v27, v26, v32
	v_sub_f32_e32 v26, v19, v32
	v_pk_mul_f32 v[30:31], v[34:35], v[26:27] op_sel_hi:[0,1]
	v_pk_mul_f32 v[40:41], v[34:35], v[24:25] op_sel_hi:[0,1]
	ds_read_b128 v[24:27], v244 offset:64
	ds_read_b128 v[36:39], v244 offset:320
	v_and_b32_e32 v18, 0xffff0000, v22
	v_lshlrev_b32_e32 v16, 16, v23
	s_waitcnt lgkmcnt(0)
	v_pk_fma_f32 v[24:25], v[24:25], v[40:41], v[36:37]
	s_nop 0
	v_pk_fma_f32 v[12:13], v[24:25], s[72:73], v[12:13] op_sel_hi:[1,0,1]
	s_waitcnt vmcnt(0)
	v_permlane16_swap_b32_e32 v238, v240
	v_permlane16_swap_b32_e32 v239, v241
	s_nop 0
	v_permlane32_swap_b32_e32 v238, v240
	v_permlane32_swap_b32_e32 v239, v241
	v_mov_b64_e32 v[24:25], v[238:239]
	v_pk_fma_f32 v[26:27], v[26:27], v[30:31], v[38:39]
	v_cvt_pk_bf16_f32 v30, v12, v13
	v_pk_fma_f32 v[14:15], v[26:27], s[72:73], v[14:15] op_sel_hi:[1,0,1]
	s_waitcnt lgkmcnt(0)
	v_lshlrev_b32_e32 v3, 16, v24
	v_cvt_pk_bf16_f32 v31, v14, v15
	v_lshlrev_b32_e32 v14, 16, v31
	v_and_b32_e32 v15, 0xffff0000, v31
	v_mul_f32_e32 v12, v14, v14
	v_pk_fma_f32 v[12:13], v[14:15], v[14:15], v[12:13] op_sel_hi:[1,1,0]
	v_lshlrev_b32_e32 v17, 16, v25
	v_and_b32_e32 v12, 0xffff0000, v24
	v_and_b32_e32 v19, 0xffff0000, v25
	v_mov_b64_e32 v[150:151], v[30:31]
	v_lshrrev_b32_e32 v42, 4, v219
	v_lshlrev_b32_e32 v42, 3, v42
	v_mov_b32_e32 v43, v2
	v_permlane32_swap_b32_e32 v148, v150
	v_permlane32_swap_b32_e32 v149, v151
	v_lshl_add_u64 v[42:43], v[42:43], 0, v[28:29]
	s_nop 0
	v_permlane16_swap_b32_e32 v148, v150
	v_permlane16_swap_b32_e32 v149, v151
	global_store_dwordx4 v[42:43], v[148:151], off sc0
	v_sub_f32_e32 v25, v12, v32
	v_sub_f32_e32 v24, v3, v32
	v_sub_f32_e32 v27, v19, v32
	v_sub_f32_e32 v26, v17, v32
	v_pk_mul_f32 v[40:41], v[34:35], v[26:27] op_sel_hi:[0,1]
	v_pk_mul_f32 v[42:43], v[34:35], v[24:25] op_sel_hi:[0,1]
	ds_read_b128 v[24:27], v244 offset:128
	ds_read_b128 v[36:39], v244 offset:384
	v_and_b32_e32 v31, 0xffff0000, v30
	s_waitcnt lgkmcnt(0)
; __device__ __forceinline__ u32x2 pk4(f32x4 v) { u32x2 r; r.x = pk2(v.x, v.y); r.y = pk2(v.z, v.w); return r; }
; __device__ __forceinline__ void stats_main(const float* stm, int row, int fq, float& mu, float& rs) {
;     const f32x4* p = (const f32x4*)(stm + (size_t)row * 32 + fq * 8);
;     const f32x4 a = p[0], b = p[1];
;     float s1 = (a.x + a.z) + (b.x + b.z), s2 = (a.y + a.w) + (b.y + b.w);
;     s1 += __shfl_xor(s1, 16); s2 += __shfl_xor(s2, 16); s1 += __shfl_xor(s1, 32); s2 += __shfl_xor(s2, 32);
;     mu = s1 * (1.f / DM); rs = __builtin_amdgcn_rsqf(fmaxf(s2 * (1.f / DM) - mu * mu, 0.f) + LN_EPS);
; }
;     __device__ __forceinline__ void operator()(const f32x4 (&acc)[2][2][4][2], const pg8::Unit& u, int wr, int wc, int fr, int fq) const {
;     ...
;                 const int row = u.pm * 256 + ai * 128 + wr * 64 + m * 16 + fr;
;                 float mu = 0.f, rs = 1.f; if (ln) stats_main(stm_p, row, fq, mu, rs);
;                 float s1 = 0.f, s2 = 0.f;
; #pragma unroll
;                 for (int bj = 0; bj < 2; ++bj)
; #pragma unroll
;                     for (int n = 0; n < 2; ++n) {
;                         const int col = u.pn * 256 + bj * 128 + wc * 32 + n * 16 + fq * 4;
;                         const u32x2 raw = *(const u32x2*)(src + (size_t)row * DM + col);
;                         f32x4 x = (f32x4){bflo(raw.x), bfhi(raw.x), bflo(raw.y), bfhi(raw.y)};
;                         if (ln) x = (x - mu) * rs * *(const f32x4*)(g + col) + *(const f32x4*)(b + col);
;                         const u32x2 pz = pk4(x * ALPHA + acc[ai][bj][m][n]);
;                         *(u32x2*)(dst + (size_t)row * DM + col) = pz;
;                         const float z0 = bflo(pz.x), z1 = bfhi(pz.x), z2 = bflo(pz.y), z3 = bfhi(pz.y);
;                         s1 += (z0 + z1) + (z2 + z3); s2 += (z0 * z0 + z1 * z1) + (z2 * z2 + z3 * z3);
;                     }
;                 s1 += __shfl_xor(s1, 16); s2 += __shfl_xor(s2, 16); s1 += __shfl_xor(s1, 32); s2 += __shfl_xor(s2, 32);
;                 if (fq == 0) { float* p = stm_n + (size_t)row * 32 + (u.pn * 4 + wc) * 2; p[0] = s1; p[1] = s2; }
	v_pk_fma_f32 v[24:25], v[24:25], v[42:43], v[36:37]
	v_mov_b64_e32 v[36:37], v[240:241]
	v_pk_fma_f32 v[26:27], v[26:27], v[40:41], v[38:39]
	v_pk_fma_f32 v[8:9], v[24:25], s[72:73], v[8:9] op_sel_hi:[1,0,1]
	v_pk_fma_f32 v[10:11], v[26:27], s[72:73], v[10:11] op_sel_hi:[1,0,1]
	v_cvt_pk_bf16_f32 v8, v8, v9
	v_cvt_pk_bf16_f32 v9, v10, v11
	v_mov_b64_e32 v[148:149], v[8:9]
	v_lshlrev_b32_e32 v24, 16, v8
	v_and_b32_e32 v26, 0xffff0000, v8
	v_lshlrev_b32_e32 v8, 16, v9
	v_and_b32_e32 v10, 0xffff0000, v9
	v_mul_f32_e32 v25, v24, v24
	v_mul_f32_e32 v27, v26, v26
	v_mul_f32_e32 v9, v8, v8
	v_mul_f32_e32 v11, v10, v10
	v_pk_add_f32 v[8:9], v[8:9], v[10:11]
	s_waitcnt lgkmcnt(0)
	v_lshlrev_b32_e32 v3, 16, v36
	v_and_b32_e32 v12, 0xffff0000, v36
	v_lshlrev_b32_e32 v17, 16, v37
	v_and_b32_e32 v19, 0xffff0000, v37
	v_sub_f32_e32 v37, v12, v32
	v_sub_f32_e32 v36, v3, v32
	v_sub_f32_e32 v33, v19, v32
	v_sub_f32_e32 v32, v17, v32
	v_pk_mul_f32 v[32:33], v[34:35], v[32:33] op_sel_hi:[0,1]
	v_pk_mul_f32 v[34:35], v[34:35], v[36:37] op_sel_hi:[0,1]
	ds_read_b128 v[36:39], v244 offset:192
	ds_read_b128 v[40:43], v244 offset:448
	v_mov_b32_e32 v17, v31
	v_mov_b32_e32 v3, v13
	s_waitcnt lgkmcnt(0)
	v_pk_fma_f32 v[34:35], v[36:37], v[34:35], v[40:41]
	s_nop 0
	v_pk_fma_f32 v[4:5], v[34:35], s[72:73], v[4:5] op_sel_hi:[1,0,1]
	v_lshlrev_b32_e32 v35, 16, v30
	v_lshlrev_b32_e32 v34, 16, v22
	v_mov_b32_e32 v19, v35
	v_pk_fma_f32 v[32:33], v[38:39], v[32:33], v[42:43]
	v_pk_mul_f32 v[36:37], v[34:35], v[34:35]
	v_pk_mul_f32 v[38:39], v[18:19], v[18:19]
	v_and_b32_e32 v30, 0xffff0000, v23
	v_pk_mul_f32 v[22:23], v[16:17], v[16:17]
	v_pk_mul_f32 v[40:41], v[30:31], v[30:31]
	v_pk_mov_b32 v[42:43], v[34:35], v[36:37] op_sel:[1,0]
	v_pk_mov_b32 v[38:39], v[30:31], v[38:39] op_sel:[1,0]
	v_pk_add_f32 v[18:19], v[34:35], v[18:19]
	v_pk_add_f32 v[16:17], v[30:31], v[16:17]
	v_pk_fma_f32 v[6:7], v[32:33], s[72:73], v[6:7] op_sel_hi:[1,0,1]
	v_pk_add_f32 v[38:39], v[42:43], v[38:39]
	v_mov_b32_e32 v42, v14
	v_mov_b32_e32 v43, v22
	v_pk_mov_b32 v[14:15], v[14:15], v[40:41] op_sel:[1,0]
	v_mov_b32_e32 v19, v37
	v_mov_b32_e32 v17, v41
	v_cvt_pk_bf16_f32 v4, v4, v5
	v_cvt_pk_bf16_f32 v5, v6, v7
	v_pk_add_f32 v[14:15], v[42:43], v[14:15]
	v_pk_add_f32 v[16:17], v[18:19], v[16:17]
	v_mov_b64_e32 v[150:151], v[4:5]
	v_lshrrev_b32_e32 v146, 4, v219
	v_lshlrev_b32_e32 v146, 3, v146
	v_mov_b32_e32 v147, v2
	v_permlane32_swap_b32_e32 v148, v150
	v_permlane32_swap_b32_e32 v149, v151
	v_lshl_add_u64 v[146:147], v[146:147], 0, v[28:29]
	s_nop 0
	v_permlane16_swap_b32_e32 v148, v150
	v_permlane16_swap_b32_e32 v149, v151
	global_store_dwordx4 v[146:147], v[148:151], off offset:256 sc0
	v_lshlrev_b32_e32 v28, 16, v4
	v_and_b32_e32 v32, 0xffff0000, v4
	v_lshlrev_b32_e32 v4, 16, v5
	v_and_b32_e32 v6, 0xffff0000, v5
	v_pk_add_f32 v[14:15], v[38:39], v[14:15]
	v_pk_add_f32 v[12:13], v[16:17], v[2:3]
	v_mul_f32_e32 v29, v28, v28
	v_mul_f32_e32 v33, v32, v32
	v_mul_f32_e32 v5, v4, v4
	v_mul_f32_e32 v7, v6, v6
	v_pk_add_f32 v[12:13], v[14:15], v[12:13]
	v_pk_add_f32 v[14:15], v[24:25], v[26:27]
	v_pk_add_f32 v[10:11], v[28:29], v[32:33]
	v_pk_add_f32 v[8:9], v[14:15], v[8:9]
	v_pk_add_f32 v[4:5], v[4:5], v[6:7]
	v_pk_add_f32 v[8:9], v[12:13], v[8:9]
	v_pk_add_f32 v[4:5], v[10:11], v[4:5]
	s_nop 0
	v_pk_add_f32 v[4:5], v[8:9], v[4:5]
	ds_bpermute_b32 v6, v181, v4
	ds_bpermute_b32 v7, v181, v5
	s_waitcnt lgkmcnt(0)
	v_pk_add_f32 v[4:5], v[4:5], v[6:7]
	ds_bpermute_b32 v6, v180, v4
	ds_bpermute_b32 v7, v180, v5
	s_and_saveexec_b64 s[0:1], s[40:41]
	s_cbranch_execz .LBB0_2393
	v_lshl_add_u64 v[8:9], s[52:53], 0, v[20:21]
	v_lshl_add_u64 v[8:9], s[68:69], 2, v[8:9]
	s_waitcnt lgkmcnt(0)
	v_pk_add_f32 v[4:5], v[4:5], v[6:7]
	global_store_dwordx2 v[8:9], v[4:5], off
